# GEMM main loops: LDS-DMA stage instructions use an SGPR base + 32-bit lane offset; the per-stage 64-bit vector address adds are gone (no VALU left in the loops)
# speedup vs baseline: 1.0071x; 1.0071x over previous
.LBB0_316:
	ds_read_b128 v[150:153], v167
	ds_read_b128 v[154:157], v167 offset:1024
	ds_read_b128 v[158:161], v167 offset:2048
	ds_read_b128 v[172:175], v167 offset:3072
	s_add_u32 s4, s8, 0xfff80080
	s_addc_u32 s5, s9, -1
	s_cmp_eq_u32 s25, 28
	s_cselect_b32 s5, s69, s5
	s_cselect_b32 s4, s68, s4
	s_cselect_b32 s75, s0, s24
	s_cselect_b32 s74, s1, s12
	s_add_i32 m0, s11, 0xc000
	ds_read_b128 v[176:179], v168
	ds_read_b128 v[180:183], v168 offset:1024
	ds_read_b128 v[184:187], v168 offset:2048
	ds_read_b128 v[188:191], v168 offset:3072
	ds_read_b128 v[192:195], v168 offset:4096
	ds_read_b128 v[196:199], v168 offset:5120
	ds_read_b128 v[200:203], v168 offset:6144
	ds_read_b128 v[204:207], v168 offset:7168
	global_load_lds_dwordx4 v142, s[8:9]
	s_add_i32 m0, s11, 0xe000
	s_nop 0
	global_load_lds_dwordx4 v144, s[8:9]
	s_waitcnt lgkmcnt(8)
	s_barrier
	s_waitcnt lgkmcnt(0)
	s_waitcnt lgkmcnt(0)
	v_mfma_f32_16x16x32_bf16 v[124:127], v[150:153], v[176:179], v[124:127]
	v_mfma_f32_16x16x32_bf16 v[120:123], v[158:161], v[176:179], v[120:123]
	v_mfma_f32_16x16x32_bf16 v[116:119], v[150:153], v[184:187], v[116:119]
	v_mfma_f32_16x16x32_bf16 v[112:115], v[158:161], v[184:187], v[112:115]
	v_mfma_f32_16x16x32_bf16 v[100:103], v[150:153], v[192:195], v[100:103]
	v_mfma_f32_16x16x32_bf16 v[96:99], v[158:161], v[192:195], v[96:99]
	v_mfma_f32_16x16x32_bf16 v[84:87], v[150:153], v[200:203], v[84:87]
	v_mfma_f32_16x16x32_bf16 v[80:83], v[158:161], v[200:203], v[80:83]
	v_mfma_f32_16x16x32_bf16 v[124:127], v[154:157], v[180:183], v[124:127]
	v_mfma_f32_16x16x32_bf16 v[120:123], v[172:175], v[180:183], v[120:123]
	v_mfma_f32_16x16x32_bf16 v[116:119], v[154:157], v[188:191], v[116:119]
	v_mfma_f32_16x16x32_bf16 v[112:115], v[172:175], v[188:191], v[112:115]
	v_mfma_f32_16x16x32_bf16 v[100:103], v[154:157], v[196:199], v[100:103]
	v_mfma_f32_16x16x32_bf16 v[96:99], v[172:175], v[196:199], v[96:99]
	v_mfma_f32_16x16x32_bf16 v[84:87], v[154:157], v[204:207], v[84:87]
	v_mfma_f32_16x16x32_bf16 v[80:83], v[172:175], v[204:207], v[80:83]
	s_barrier
	s_add_i32 s33, s80, s28
	s_add_u32 s98, s74, s14
	s_addc_u32 s99, s75, s15
	s_mov_b32 m0, s33
	ds_read_b128 v[208:211], v169
	ds_read_b128 v[212:215], v169 offset:1024
	ds_read_b128 v[218:221], v169 offset:2048
	ds_read_b128 v[222:225], v169 offset:3072
	global_load_lds_dwordx4 v132, s[74:75]
	s_add_i32 m0, s33, 0x2000
	s_nop 0
	global_load_lds_dwordx4 v136, s[74:75]
	s_barrier
	s_waitcnt lgkmcnt(0)
	s_waitcnt lgkmcnt(0)
	v_mfma_f32_16x16x32_bf16 v[108:111], v[208:211], v[176:179], v[108:111]
	v_mfma_f32_16x16x32_bf16 v[104:107], v[218:221], v[176:179], v[104:107]
	v_mfma_f32_16x16x32_bf16 v[92:95], v[208:211], v[184:187], v[92:95]
	v_mfma_f32_16x16x32_bf16 v[88:91], v[218:221], v[184:187], v[88:91]
	v_mfma_f32_16x16x32_bf16 v[76:79], v[208:211], v[192:195], v[76:79]
	v_mfma_f32_16x16x32_bf16 v[72:75], v[218:221], v[192:195], v[72:75]
	v_mfma_f32_16x16x32_bf16 v[68:71], v[208:211], v[200:203], v[68:71]
	v_mfma_f32_16x16x32_bf16 v[64:67], v[218:221], v[200:203], v[64:67]
	v_mfma_f32_16x16x32_bf16 v[108:111], v[212:215], v[180:183], v[108:111]
	v_mfma_f32_16x16x32_bf16 v[104:107], v[222:225], v[180:183], v[104:107]
	v_mfma_f32_16x16x32_bf16 v[92:95], v[212:215], v[188:191], v[92:95]
	v_mfma_f32_16x16x32_bf16 v[88:91], v[222:225], v[188:191], v[88:91]
	v_mfma_f32_16x16x32_bf16 v[76:79], v[212:215], v[196:199], v[76:79]
	v_mfma_f32_16x16x32_bf16 v[72:75], v[222:225], v[196:199], v[72:75]
	v_mfma_f32_16x16x32_bf16 v[68:71], v[212:215], v[204:207], v[68:71]
	v_mfma_f32_16x16x32_bf16 v[64:67], v[222:225], v[204:207], v[64:67]
	s_mov_b32 m0, s11
	s_add_u32 s100, s4, s14
	s_addc_u32 s101, s5, s15
	s_barrier
	ds_read_b128 v[176:179], v168 offset:16384
	ds_read_b128 v[180:183], v168 offset:17408
	ds_read_b128 v[184:187], v168 offset:18432
	ds_read_b128 v[188:191], v168 offset:19456
	ds_read_b128 v[192:195], v168 offset:20480
	ds_read_b128 v[196:199], v168 offset:21504
	ds_read_b128 v[200:203], v168 offset:22528
	ds_read_b128 v[204:207], v168 offset:23552
	global_load_lds_dwordx4 v130, s[4:5]
	s_mov_b32 m0, s29
	s_nop 0
	global_load_lds_dwordx4 v134, s[4:5]
	s_barrier
	s_waitcnt lgkmcnt(0)
	s_waitcnt lgkmcnt(0)
	v_mfma_f32_16x16x32_bf16 v[60:63], v[150:153], v[176:179], v[60:63]
	v_mfma_f32_16x16x32_bf16 v[56:59], v[158:161], v[176:179], v[56:59]
	v_mfma_f32_16x16x32_bf16 v[52:55], v[150:153], v[184:187], v[52:55]
	v_mfma_f32_16x16x32_bf16 v[48:51], v[158:161], v[184:187], v[48:51]
	v_mfma_f32_16x16x32_bf16 v[40:43], v[150:153], v[192:195], v[40:43]
	v_mfma_f32_16x16x32_bf16 v[32:35], v[158:161], v[192:195], v[32:35]
	v_mfma_f32_16x16x32_bf16 v[24:27], v[150:153], v[200:203], v[24:27]
	v_mfma_f32_16x16x32_bf16 v[16:19], v[158:161], v[200:203], v[16:19]
	v_mfma_f32_16x16x32_bf16 v[60:63], v[154:157], v[180:183], v[60:63]
	v_mfma_f32_16x16x32_bf16 v[56:59], v[172:175], v[180:183], v[56:59]
	v_mfma_f32_16x16x32_bf16 v[52:55], v[154:157], v[188:191], v[52:55]
	v_mfma_f32_16x16x32_bf16 v[48:51], v[172:175], v[188:191], v[48:51]
	v_mfma_f32_16x16x32_bf16 v[40:43], v[154:157], v[196:199], v[40:43]
	v_mfma_f32_16x16x32_bf16 v[32:35], v[172:175], v[196:199], v[32:35]
	v_mfma_f32_16x16x32_bf16 v[24:27], v[154:157], v[204:207], v[24:27]
	v_mfma_f32_16x16x32_bf16 v[16:19], v[172:175], v[204:207], v[16:19]
	s_barrier
	s_add_u32 s76, s74, 0x80000
	s_addc_u32 s77, s75, 0
	s_add_i32 s33, s81, s28
	s_mov_b32 m0, s33
	s_nop 0
	global_load_lds_dwordx4 v132, s[76:77]
	s_add_i32 m0, s33, 0x2000
	s_nop 0
	global_load_lds_dwordx4 v136, s[76:77]
	s_waitcnt vmcnt(6)
	s_barrier
	v_mfma_f32_16x16x32_bf16 v[44:47], v[208:211], v[176:179], v[44:47]
	v_mfma_f32_16x16x32_bf16 v[36:39], v[218:221], v[176:179], v[36:39]
	v_mfma_f32_16x16x32_bf16 v[28:31], v[208:211], v[184:187], v[28:31]
	v_mfma_f32_16x16x32_bf16 v[20:23], v[218:221], v[184:187], v[20:23]
	v_mfma_f32_16x16x32_bf16 v[12:15], v[208:211], v[192:195], v[12:15]
	v_mfma_f32_16x16x32_bf16 v[8:11], v[218:221], v[192:195], v[8:11]
	v_mfma_f32_16x16x32_bf16 v[4:7], v[208:211], v[200:203], v[4:7]
	v_mfma_f32_16x16x32_bf16 v[0:3], v[218:221], v[200:203], v[0:3]
	v_mfma_f32_16x16x32_bf16 v[44:47], v[212:215], v[180:183], v[44:47]
	v_mfma_f32_16x16x32_bf16 v[36:39], v[222:225], v[180:183], v[36:39]
	v_mfma_f32_16x16x32_bf16 v[28:31], v[212:215], v[188:191], v[28:31]
	v_mfma_f32_16x16x32_bf16 v[20:23], v[222:225], v[188:191], v[20:23]
	v_mfma_f32_16x16x32_bf16 v[12:15], v[212:215], v[196:199], v[12:15]
	v_mfma_f32_16x16x32_bf16 v[8:11], v[222:225], v[196:199], v[8:11]
	v_mfma_f32_16x16x32_bf16 v[4:7], v[212:215], v[204:207], v[4:7]
	v_mfma_f32_16x16x32_bf16 v[0:3], v[222:225], v[204:207], v[0:3]
	s_add_i32 s33, 0, 0x18000
	v_add_u32_e32 v138, s33, v164
	s_barrier
	ds_read_b128 v[150:153], v138
	ds_read_b128 v[154:157], v138 offset:1024
	ds_read_b128 v[158:161], v138 offset:2048
	ds_read_b128 v[172:175], v138 offset:3072
	s_add_u32 s4, s4, 0x80000
	s_addc_u32 s5, s5, 0
	s_mov_b32 m0, s36
	ds_read_b128 v[176:179], v168 offset:32768
	ds_read_b128 v[180:183], v168 offset:33792
	ds_read_b128 v[184:187], v168 offset:34816
	ds_read_b128 v[188:191], v168 offset:35840
	ds_read_b128 v[192:195], v168 offset:36864
	ds_read_b128 v[196:199], v168 offset:37888
	ds_read_b128 v[200:203], v168 offset:38912
	ds_read_b128 v[204:207], v168 offset:39936
	global_load_lds_dwordx4 v130, s[4:5]
	s_mov_b32 m0, s37
	s_nop 0
	global_load_lds_dwordx4 v134, s[4:5]
	s_waitcnt lgkmcnt(8)
	s_barrier
	s_waitcnt lgkmcnt(0)
	s_waitcnt lgkmcnt(0)
	v_mfma_f32_16x16x32_bf16 v[124:127], v[150:153], v[176:179], v[124:127]
	v_mfma_f32_16x16x32_bf16 v[120:123], v[158:161], v[176:179], v[120:123]
	v_mfma_f32_16x16x32_bf16 v[116:119], v[150:153], v[184:187], v[116:119]
	v_mfma_f32_16x16x32_bf16 v[112:115], v[158:161], v[184:187], v[112:115]
	v_mfma_f32_16x16x32_bf16 v[100:103], v[150:153], v[192:195], v[100:103]
	v_mfma_f32_16x16x32_bf16 v[96:99], v[158:161], v[192:195], v[96:99]
	v_mfma_f32_16x16x32_bf16 v[84:87], v[150:153], v[200:203], v[84:87]
	v_mfma_f32_16x16x32_bf16 v[80:83], v[158:161], v[200:203], v[80:83]
	v_mfma_f32_16x16x32_bf16 v[124:127], v[154:157], v[180:183], v[124:127]
	v_mfma_f32_16x16x32_bf16 v[120:123], v[172:175], v[180:183], v[120:123]
	v_mfma_f32_16x16x32_bf16 v[116:119], v[154:157], v[188:191], v[116:119]
	v_mfma_f32_16x16x32_bf16 v[112:115], v[172:175], v[188:191], v[112:115]
	v_mfma_f32_16x16x32_bf16 v[100:103], v[154:157], v[196:199], v[100:103]
	v_mfma_f32_16x16x32_bf16 v[96:99], v[172:175], v[196:199], v[96:99]
	v_mfma_f32_16x16x32_bf16 v[84:87], v[154:157], v[204:207], v[84:87]
	v_mfma_f32_16x16x32_bf16 v[80:83], v[172:175], v[204:207], v[80:83]
	s_barrier
	s_add_i32 s65, 0, 0x1c000
	s_add_i32 s4, s33, s28
	v_add_u32_e32 v138, s65, v164
	s_mov_b32 m0, s4
	ds_read_b128 v[208:211], v138
	ds_read_b128 v[212:215], v138 offset:1024
	ds_read_b128 v[218:221], v138 offset:2048
	ds_read_b128 v[222:225], v138 offset:3072
	global_load_lds_dwordx4 v132, s[98:99]
	s_add_i32 m0, s4, 0x2000
	s_nop 0
	global_load_lds_dwordx4 v136, s[98:99]
	s_barrier
	s_waitcnt lgkmcnt(0)
	s_waitcnt lgkmcnt(0)
	v_mfma_f32_16x16x32_bf16 v[108:111], v[208:211], v[176:179], v[108:111]
	v_mfma_f32_16x16x32_bf16 v[104:107], v[218:221], v[176:179], v[104:107]
	v_mfma_f32_16x16x32_bf16 v[92:95], v[208:211], v[184:187], v[92:95]
	v_mfma_f32_16x16x32_bf16 v[88:91], v[218:221], v[184:187], v[88:91]
	v_mfma_f32_16x16x32_bf16 v[76:79], v[208:211], v[192:195], v[76:79]
	v_mfma_f32_16x16x32_bf16 v[72:75], v[218:221], v[192:195], v[72:75]
	v_mfma_f32_16x16x32_bf16 v[68:71], v[208:211], v[200:203], v[68:71]
	v_mfma_f32_16x16x32_bf16 v[64:67], v[218:221], v[200:203], v[64:67]
	v_mfma_f32_16x16x32_bf16 v[108:111], v[212:215], v[180:183], v[108:111]
	v_mfma_f32_16x16x32_bf16 v[104:107], v[222:225], v[180:183], v[104:107]
	v_mfma_f32_16x16x32_bf16 v[92:95], v[212:215], v[188:191], v[92:95]
	v_mfma_f32_16x16x32_bf16 v[88:91], v[222:225], v[188:191], v[88:91]
	v_mfma_f32_16x16x32_bf16 v[76:79], v[212:215], v[196:199], v[76:79]
	v_mfma_f32_16x16x32_bf16 v[72:75], v[222:225], v[196:199], v[72:75]
	v_mfma_f32_16x16x32_bf16 v[68:71], v[212:215], v[204:207], v[68:71]
	v_mfma_f32_16x16x32_bf16 v[64:67], v[222:225], v[204:207], v[64:67]
	s_mov_b32 m0, s73
	s_barrier
	ds_read_b128 v[176:179], v168 offset:49152
	ds_read_b128 v[180:183], v168 offset:50176
	ds_read_b128 v[184:187], v168 offset:51200
	ds_read_b128 v[188:191], v168 offset:52224
	ds_read_b128 v[192:195], v168 offset:53248
	ds_read_b128 v[196:199], v168 offset:54272
	ds_read_b128 v[200:203], v168 offset:55296
	ds_read_b128 v[204:207], v168 offset:56320
	global_load_lds_dwordx4 v130, s[100:101]
	s_mov_b32 m0, s78
	s_nop 0
	global_load_lds_dwordx4 v134, s[100:101]
	s_barrier
	s_waitcnt lgkmcnt(0)
	s_waitcnt lgkmcnt(0)
	v_mfma_f32_16x16x32_bf16 v[60:63], v[150:153], v[176:179], v[60:63]
	v_mfma_f32_16x16x32_bf16 v[56:59], v[158:161], v[176:179], v[56:59]
	v_mfma_f32_16x16x32_bf16 v[52:55], v[150:153], v[184:187], v[52:55]
	v_mfma_f32_16x16x32_bf16 v[48:51], v[158:161], v[184:187], v[48:51]
	v_mfma_f32_16x16x32_bf16 v[40:43], v[150:153], v[192:195], v[40:43]
	v_mfma_f32_16x16x32_bf16 v[32:35], v[158:161], v[192:195], v[32:35]
	v_mfma_f32_16x16x32_bf16 v[24:27], v[150:153], v[200:203], v[24:27]
	v_mfma_f32_16x16x32_bf16 v[16:19], v[158:161], v[200:203], v[16:19]
	v_mfma_f32_16x16x32_bf16 v[60:63], v[154:157], v[180:183], v[60:63]
	v_mfma_f32_16x16x32_bf16 v[56:59], v[172:175], v[180:183], v[56:59]
	v_mfma_f32_16x16x32_bf16 v[52:55], v[154:157], v[188:191], v[52:55]
	v_mfma_f32_16x16x32_bf16 v[48:51], v[172:175], v[188:191], v[48:51]
	v_mfma_f32_16x16x32_bf16 v[40:43], v[154:157], v[196:199], v[40:43]
	v_mfma_f32_16x16x32_bf16 v[32:35], v[172:175], v[196:199], v[32:35]
	v_mfma_f32_16x16x32_bf16 v[24:27], v[154:157], v[204:207], v[24:27]
	v_mfma_f32_16x16x32_bf16 v[16:19], v[172:175], v[204:207], v[16:19]
	s_barrier
	s_add_u32 s4, s74, 0x80080
	s_addc_u32 s5, s75, 0
	s_add_i32 s33, s65, s28
	s_mov_b32 m0, s33
	s_nop 0
	global_load_lds_dwordx4 v132, s[4:5]
	s_add_i32 m0, s33, 0x2000
	s_nop 0
	global_load_lds_dwordx4 v136, s[4:5]
	s_waitcnt vmcnt(6)
	s_barrier
	v_mfma_f32_16x16x32_bf16 v[44:47], v[208:211], v[176:179], v[44:47]
	v_mfma_f32_16x16x32_bf16 v[36:39], v[218:221], v[176:179], v[36:39]
	v_mfma_f32_16x16x32_bf16 v[28:31], v[208:211], v[184:187], v[28:31]
	v_mfma_f32_16x16x32_bf16 v[20:23], v[218:221], v[184:187], v[20:23]
	v_mfma_f32_16x16x32_bf16 v[12:15], v[208:211], v[192:195], v[12:15]
	v_mfma_f32_16x16x32_bf16 v[8:11], v[218:221], v[192:195], v[8:11]
	v_mfma_f32_16x16x32_bf16 v[4:7], v[208:211], v[200:203], v[4:7]
	v_mfma_f32_16x16x32_bf16 v[0:3], v[218:221], v[200:203], v[0:3]
	v_mfma_f32_16x16x32_bf16 v[44:47], v[212:215], v[180:183], v[44:47]
	v_mfma_f32_16x16x32_bf16 v[36:39], v[222:225], v[180:183], v[36:39]
	v_mfma_f32_16x16x32_bf16 v[28:31], v[212:215], v[188:191], v[28:31]
	v_mfma_f32_16x16x32_bf16 v[20:23], v[222:225], v[188:191], v[20:23]
	v_mfma_f32_16x16x32_bf16 v[12:15], v[212:215], v[196:199], v[12:15]
	v_mfma_f32_16x16x32_bf16 v[8:11], v[222:225], v[196:199], v[8:11]
	v_mfma_f32_16x16x32_bf16 v[4:7], v[212:215], v[204:207], v[4:7]
	v_mfma_f32_16x16x32_bf16 v[0:3], v[222:225], v[204:207], v[0:3]
	s_add_i32 s25, s25, 2
	s_add_u32 s8, s8, 0x100
	s_addc_u32 s9, s9, 0
	s_add_u32 s12, s12, 0x100
	s_addc_u32 s24, s24, 0
	s_cmp_gt_u32 s25, 29
	s_barrier
	s_cbranch_scc0 .LBB0_316
	s_and_b32 s0, s10, -8
	v_lshl_add_u32 v150, s72, 8, v129
	s_cmp_lg_u32 s0, 8
	s_mov_b64 s[0:1], -1
	s_cbranch_scc0 .LBB0_435
	s_cmp_gt_i32 s10, 23
	s_cbranch_scc0 .LBB0_432
	s_cmp_lt_i32 s10, 26
	s_cbranch_scc1 .LBB0_323
	s_cmp_eq_u32 s10, 26
	v_mov_b32_e32 v161, v123
	v_mov_b32_e32 v160, v122
	v_mov_b32_e32 v157, v121
	v_mov_b32_e32 v156, v120
	v_mov_b32_e32 v163, v127
	v_mov_b32_e32 v162, v126
	v_mov_b32_e32 v159, v125
	v_mov_b32_e32 v158, v124
	s_cbranch_scc0 .LBB0_322
	v_mul_f32_e32 v138, 0xbfb8aa3b, v124
	v_exp_f32_e32 v138, v138
	v_mul_f32_e32 v151, 0xbfb8aa3b, v120
	v_exp_f32_e32 v151, v151
	v_mul_f32_e32 v152, 0xbfb8aa3b, v121
	v_add_f32_e32 v138, 1.0, v138
	v_rcp_f32_e32 v158, v138
	v_mul_f32_e32 v138, 0xbfb8aa3b, v125
	v_exp_f32_e32 v138, v138
	v_exp_f32_e32 v152, v152
	v_add_f32_e32 v151, 1.0, v151
	v_rcp_f32_e32 v156, v151
	v_add_f32_e32 v138, 1.0, v138
	v_mul_f32_e32 v151, 0xbfb8aa3b, v126
	v_rcp_f32_e32 v159, v138
	v_add_f32_e32 v138, 1.0, v152
	v_exp_f32_e32 v151, v151
	v_mul_f32_e32 v152, 0xbfb8aa3b, v122
	v_exp_f32_e32 v152, v152
	v_rcp_f32_e32 v157, v138
	v_add_f32_e32 v138, 1.0, v151
	v_mul_f32_e32 v151, 0xbfb8aa3b, v127
	v_rcp_f32_e32 v162, v138
	v_add_f32_e32 v138, 1.0, v152
	v_exp_f32_e32 v151, v151
	v_mul_f32_e32 v152, 0xbfb8aa3b, v123
	v_exp_f32_e32 v152, v152
	v_rcp_f32_e32 v160, v138
	v_add_f32_e32 v138, 1.0, v151
	v_rcp_f32_e32 v163, v138
	v_add_f32_e32 v138, 1.0, v152
	v_rcp_f32_e32 v161, v138

.LBB0_850:
	ds_read_b128 v[140:143], v147
	ds_read_b128 v[150:153], v147 offset:1024
	ds_read_b128 v[154:157], v147 offset:2048
	ds_read_b128 v[158:161], v147 offset:3072
	s_add_u32 s76, s74, 0x100
	s_addc_u32 s77, s75, 0
	s_cmp_eq_u32 s73, 28
	s_cselect_b32 s5, s0, s77
	s_cselect_b32 s4, s1, s76
	s_cselect_b32 s51, s46, s67
	s_cselect_b32 s50, s47, s61
	s_add_i32 m0, s23, 0xc000
	ds_read_b128 v[162:165], v148
	ds_read_b128 v[166:169], v148 offset:1024
	ds_read_b128 v[170:173], v148 offset:2048
	ds_read_b128 v[174:177], v148 offset:3072
	ds_read_b128 v[178:181], v148 offset:4096
	ds_read_b128 v[182:185], v148 offset:5120
	ds_read_b128 v[186:189], v148 offset:6144
	ds_read_b128 v[190:193], v148 offset:7168
	global_load_lds_dwordx4 v132, s[74:75]
	s_add_i32 m0, s23, 0xe000
	s_nop 0
	global_load_lds_dwordx4 v134, s[74:75]
	s_waitcnt lgkmcnt(8)
	s_barrier
	s_waitcnt lgkmcnt(0)
	s_waitcnt lgkmcnt(0)
	v_mfma_f32_16x16x32_bf16 v[124:127], v[140:143], v[162:165], v[124:127]
	v_mfma_f32_16x16x32_bf16 v[100:103], v[154:157], v[162:165], v[100:103]
	v_mfma_f32_16x16x32_bf16 v[120:123], v[140:143], v[170:173], v[120:123]
	v_mfma_f32_16x16x32_bf16 v[96:99], v[154:157], v[170:173], v[96:99]
	v_mfma_f32_16x16x32_bf16 v[116:119], v[140:143], v[178:181], v[116:119]
	v_mfma_f32_16x16x32_bf16 v[88:91], v[154:157], v[178:181], v[88:91]
	v_mfma_f32_16x16x32_bf16 v[112:115], v[140:143], v[186:189], v[112:115]
	v_mfma_f32_16x16x32_bf16 v[80:83], v[154:157], v[186:189], v[80:83]
	v_mfma_f32_16x16x32_bf16 v[124:127], v[150:153], v[166:169], v[124:127]
	v_mfma_f32_16x16x32_bf16 v[100:103], v[158:161], v[166:169], v[100:103]
	v_mfma_f32_16x16x32_bf16 v[120:123], v[150:153], v[174:177], v[120:123]
	v_mfma_f32_16x16x32_bf16 v[96:99], v[158:161], v[174:177], v[96:99]
	v_mfma_f32_16x16x32_bf16 v[116:119], v[150:153], v[182:185], v[116:119]
	v_mfma_f32_16x16x32_bf16 v[88:91], v[158:161], v[182:185], v[88:91]
	v_mfma_f32_16x16x32_bf16 v[112:115], v[150:153], v[190:193], v[112:115]
	v_mfma_f32_16x16x32_bf16 v[80:83], v[158:161], v[190:193], v[80:83]
	s_barrier
	s_add_i32 s42, s37, s21
	s_add_u32 s98, s50, s16
	s_addc_u32 s99, s51, s17
	s_mov_b32 m0, s42
	ds_read_b128 v[194:197], v149
	ds_read_b128 v[198:201], v149 offset:1024
	ds_read_b128 v[202:205], v149 offset:2048
	ds_read_b128 v[206:209], v149 offset:3072
	global_load_lds_dwordx4 v130, s[50:51]
	s_add_i32 m0, s42, 0x2000
	s_nop 0
	global_load_lds_dwordx4 v128, s[50:51]
	s_barrier
	s_waitcnt lgkmcnt(0)
	s_waitcnt lgkmcnt(0)
	v_mfma_f32_16x16x32_bf16 v[68:71], v[194:197], v[162:165], v[68:71]
	v_mfma_f32_16x16x32_bf16 v[40:43], v[202:205], v[162:165], v[40:43]
	v_mfma_f32_16x16x32_bf16 v[60:63], v[194:197], v[170:173], v[60:63]
	v_mfma_f32_16x16x32_bf16 v[32:35], v[202:205], v[170:173], v[32:35]
	v_mfma_f32_16x16x32_bf16 v[52:55], v[194:197], v[178:181], v[52:55]
	v_mfma_f32_16x16x32_bf16 v[24:27], v[202:205], v[178:181], v[24:27]
	v_mfma_f32_16x16x32_bf16 v[48:51], v[194:197], v[186:189], v[48:51]
	v_mfma_f32_16x16x32_bf16 v[16:19], v[202:205], v[186:189], v[16:19]
	v_mfma_f32_16x16x32_bf16 v[68:71], v[198:201], v[166:169], v[68:71]
	v_mfma_f32_16x16x32_bf16 v[40:43], v[206:209], v[166:169], v[40:43]
	v_mfma_f32_16x16x32_bf16 v[60:63], v[198:201], v[174:177], v[60:63]
	v_mfma_f32_16x16x32_bf16 v[32:35], v[206:209], v[174:177], v[32:35]
	v_mfma_f32_16x16x32_bf16 v[52:55], v[198:201], v[182:185], v[52:55]
	v_mfma_f32_16x16x32_bf16 v[24:27], v[206:209], v[182:185], v[24:27]
	v_mfma_f32_16x16x32_bf16 v[48:51], v[198:201], v[190:193], v[48:51]
	v_mfma_f32_16x16x32_bf16 v[16:19], v[206:209], v[190:193], v[16:19]
	s_mov_b32 m0, s23
	s_add_u32 s100, s4, s16
	s_addc_u32 s101, s5, s17
	s_barrier
	ds_read_b128 v[162:165], v148 offset:16384
	ds_read_b128 v[166:169], v148 offset:17408
	ds_read_b128 v[170:173], v148 offset:18432
	ds_read_b128 v[174:177], v148 offset:19456
	ds_read_b128 v[178:181], v148 offset:20480
	ds_read_b128 v[182:185], v148 offset:21504
	ds_read_b128 v[186:189], v148 offset:22528
	ds_read_b128 v[190:193], v148 offset:23552
	global_load_lds_dwordx4 v130, s[4:5]
	s_mov_b32 m0, s24
	s_nop 0
	global_load_lds_dwordx4 v128, s[4:5]
	s_barrier
	s_waitcnt lgkmcnt(0)
	s_waitcnt lgkmcnt(0)
	v_mfma_f32_16x16x32_bf16 v[108:111], v[140:143], v[162:165], v[108:111]
	v_mfma_f32_16x16x32_bf16 v[76:79], v[154:157], v[162:165], v[76:79]
	v_mfma_f32_16x16x32_bf16 v[104:107], v[140:143], v[170:173], v[104:107]
	v_mfma_f32_16x16x32_bf16 v[72:75], v[154:157], v[170:173], v[72:75]
	v_mfma_f32_16x16x32_bf16 v[92:95], v[140:143], v[178:181], v[92:95]
	v_mfma_f32_16x16x32_bf16 v[64:67], v[154:157], v[178:181], v[64:67]
	v_mfma_f32_16x16x32_bf16 v[84:87], v[140:143], v[186:189], v[84:87]
	v_mfma_f32_16x16x32_bf16 v[56:59], v[154:157], v[186:189], v[56:59]
	v_mfma_f32_16x16x32_bf16 v[108:111], v[150:153], v[166:169], v[108:111]
	v_mfma_f32_16x16x32_bf16 v[76:79], v[158:161], v[166:169], v[76:79]
	v_mfma_f32_16x16x32_bf16 v[104:107], v[150:153], v[174:177], v[104:107]
	v_mfma_f32_16x16x32_bf16 v[72:75], v[158:161], v[174:177], v[72:75]
	v_mfma_f32_16x16x32_bf16 v[92:95], v[150:153], v[182:185], v[92:95]
	v_mfma_f32_16x16x32_bf16 v[64:67], v[158:161], v[182:185], v[64:67]
	v_mfma_f32_16x16x32_bf16 v[84:87], v[150:153], v[190:193], v[84:87]
	v_mfma_f32_16x16x32_bf16 v[56:59], v[158:161], v[190:193], v[56:59]
	s_barrier
	s_add_u32 s42, s50, 0x80000
	s_addc_u32 s43, s51, 0
	s_add_i32 s44, s40, s21
	s_mov_b32 m0, s44
	s_nop 0
	global_load_lds_dwordx4 v130, s[42:43]
	s_add_i32 m0, s44, 0x2000
	s_nop 0
	global_load_lds_dwordx4 v128, s[42:43]
	s_waitcnt vmcnt(6)
	s_barrier
	v_mfma_f32_16x16x32_bf16 v[44:47], v[194:197], v[162:165], v[44:47]
	v_mfma_f32_16x16x32_bf16 v[12:15], v[202:205], v[162:165], v[12:15]
	v_mfma_f32_16x16x32_bf16 v[36:39], v[194:197], v[170:173], v[36:39]
	v_mfma_f32_16x16x32_bf16 v[8:11], v[202:205], v[170:173], v[8:11]
	v_mfma_f32_16x16x32_bf16 v[28:31], v[194:197], v[178:181], v[28:31]
	v_mfma_f32_16x16x32_bf16 v[4:7], v[202:205], v[178:181], v[4:7]
	v_mfma_f32_16x16x32_bf16 v[20:23], v[194:197], v[186:189], v[20:23]
	v_mfma_f32_16x16x32_bf16 v[0:3], v[202:205], v[186:189], v[0:3]
	v_mfma_f32_16x16x32_bf16 v[44:47], v[198:201], v[166:169], v[44:47]
	v_mfma_f32_16x16x32_bf16 v[12:15], v[206:209], v[166:169], v[12:15]
	v_mfma_f32_16x16x32_bf16 v[36:39], v[198:201], v[174:177], v[36:39]
	v_mfma_f32_16x16x32_bf16 v[8:11], v[206:209], v[174:177], v[8:11]
	v_mfma_f32_16x16x32_bf16 v[28:31], v[198:201], v[182:185], v[28:31]
	v_mfma_f32_16x16x32_bf16 v[4:7], v[206:209], v[182:185], v[4:7]
	v_mfma_f32_16x16x32_bf16 v[20:23], v[198:201], v[190:193], v[20:23]
	v_mfma_f32_16x16x32_bf16 v[0:3], v[206:209], v[190:193], v[0:3]
	s_add_i32 s42, 0, 0x18000
	v_add_u32_e32 v158, s42, v145
	s_barrier
	ds_read_b128 v[140:143], v158
	ds_read_b128 v[150:153], v158 offset:1024
	ds_read_b128 v[154:157], v158 offset:2048
	ds_read_b128 v[158:161], v158 offset:3072
	s_add_u32 s4, s4, 0x80000
	s_addc_u32 s5, s5, 0
	s_mov_b32 m0, s25
	ds_read_b128 v[162:165], v148 offset:32768
	ds_read_b128 v[166:169], v148 offset:33792
	ds_read_b128 v[170:173], v148 offset:34816
	ds_read_b128 v[174:177], v148 offset:35840
	ds_read_b128 v[178:181], v148 offset:36864
	ds_read_b128 v[182:185], v148 offset:37888
	ds_read_b128 v[186:189], v148 offset:38912
	ds_read_b128 v[190:193], v148 offset:39936
	global_load_lds_dwordx4 v130, s[4:5]
	s_mov_b32 m0, s28
	s_nop 0
	global_load_lds_dwordx4 v128, s[4:5]
	s_waitcnt lgkmcnt(8)
	s_barrier
	s_waitcnt lgkmcnt(0)
	s_waitcnt lgkmcnt(0)
	v_mfma_f32_16x16x32_bf16 v[124:127], v[140:143], v[162:165], v[124:127]
	v_mfma_f32_16x16x32_bf16 v[100:103], v[154:157], v[162:165], v[100:103]
	v_mfma_f32_16x16x32_bf16 v[120:123], v[140:143], v[170:173], v[120:123]
	v_mfma_f32_16x16x32_bf16 v[96:99], v[154:157], v[170:173], v[96:99]
	v_mfma_f32_16x16x32_bf16 v[116:119], v[140:143], v[178:181], v[116:119]
	v_mfma_f32_16x16x32_bf16 v[88:91], v[154:157], v[178:181], v[88:91]
	v_mfma_f32_16x16x32_bf16 v[112:115], v[140:143], v[186:189], v[112:115]
	v_mfma_f32_16x16x32_bf16 v[80:83], v[154:157], v[186:189], v[80:83]
	v_mfma_f32_16x16x32_bf16 v[124:127], v[150:153], v[166:169], v[124:127]
	v_mfma_f32_16x16x32_bf16 v[100:103], v[158:161], v[166:169], v[100:103]
	v_mfma_f32_16x16x32_bf16 v[120:123], v[150:153], v[174:177], v[120:123]
	v_mfma_f32_16x16x32_bf16 v[96:99], v[158:161], v[174:177], v[96:99]
	v_mfma_f32_16x16x32_bf16 v[116:119], v[150:153], v[182:185], v[116:119]
	v_mfma_f32_16x16x32_bf16 v[88:91], v[158:161], v[182:185], v[88:91]
	v_mfma_f32_16x16x32_bf16 v[112:115], v[150:153], v[190:193], v[112:115]
	v_mfma_f32_16x16x32_bf16 v[80:83], v[158:161], v[190:193], v[80:83]
	s_barrier
	s_add_i32 s43, 0, 0x1c000
	s_add_i32 s4, s42, s21
	v_add_u32_e32 v206, s43, v145
	s_mov_b32 m0, s4
	ds_read_b128 v[194:197], v206
	ds_read_b128 v[198:201], v206 offset:1024
	ds_read_b128 v[202:205], v206 offset:2048
	ds_read_b128 v[206:209], v206 offset:3072
	global_load_lds_dwordx4 v130, s[98:99]
	s_add_i32 m0, s4, 0x2000
	s_nop 0
	global_load_lds_dwordx4 v128, s[98:99]
	s_barrier
	s_waitcnt lgkmcnt(0)
	s_waitcnt lgkmcnt(0)
	v_mfma_f32_16x16x32_bf16 v[68:71], v[194:197], v[162:165], v[68:71]
	v_mfma_f32_16x16x32_bf16 v[40:43], v[202:205], v[162:165], v[40:43]
	v_mfma_f32_16x16x32_bf16 v[60:63], v[194:197], v[170:173], v[60:63]
	v_mfma_f32_16x16x32_bf16 v[32:35], v[202:205], v[170:173], v[32:35]
	v_mfma_f32_16x16x32_bf16 v[52:55], v[194:197], v[178:181], v[52:55]
	v_mfma_f32_16x16x32_bf16 v[24:27], v[202:205], v[178:181], v[24:27]
	v_mfma_f32_16x16x32_bf16 v[48:51], v[194:197], v[186:189], v[48:51]
	v_mfma_f32_16x16x32_bf16 v[16:19], v[202:205], v[186:189], v[16:19]
	v_mfma_f32_16x16x32_bf16 v[68:71], v[198:201], v[166:169], v[68:71]
	v_mfma_f32_16x16x32_bf16 v[40:43], v[206:209], v[166:169], v[40:43]
	v_mfma_f32_16x16x32_bf16 v[60:63], v[198:201], v[174:177], v[60:63]
	v_mfma_f32_16x16x32_bf16 v[32:35], v[206:209], v[174:177], v[32:35]
	v_mfma_f32_16x16x32_bf16 v[52:55], v[198:201], v[182:185], v[52:55]
	v_mfma_f32_16x16x32_bf16 v[24:27], v[206:209], v[182:185], v[24:27]
	v_mfma_f32_16x16x32_bf16 v[48:51], v[198:201], v[190:193], v[48:51]
	v_mfma_f32_16x16x32_bf16 v[16:19], v[206:209], v[190:193], v[16:19]
	s_mov_b32 m0, s33
	s_barrier
	ds_read_b128 v[162:165], v148 offset:49152
	ds_read_b128 v[166:169], v148 offset:50176
	ds_read_b128 v[170:173], v148 offset:51200
	ds_read_b128 v[174:177], v148 offset:52224
	ds_read_b128 v[178:181], v148 offset:53248
	ds_read_b128 v[182:185], v148 offset:54272
	ds_read_b128 v[186:189], v148 offset:55296
	ds_read_b128 v[190:193], v148 offset:56320
	global_load_lds_dwordx4 v130, s[100:101]
	s_mov_b32 m0, s36
	s_nop 0
	global_load_lds_dwordx4 v128, s[100:101]
	s_barrier
	s_waitcnt lgkmcnt(0)
	s_waitcnt lgkmcnt(0)
	v_mfma_f32_16x16x32_bf16 v[108:111], v[140:143], v[162:165], v[108:111]
	v_mfma_f32_16x16x32_bf16 v[76:79], v[154:157], v[162:165], v[76:79]
	v_mfma_f32_16x16x32_bf16 v[104:107], v[140:143], v[170:173], v[104:107]
	v_mfma_f32_16x16x32_bf16 v[72:75], v[154:157], v[170:173], v[72:75]
	v_mfma_f32_16x16x32_bf16 v[92:95], v[140:143], v[178:181], v[92:95]
	v_mfma_f32_16x16x32_bf16 v[64:67], v[154:157], v[178:181], v[64:67]
	v_mfma_f32_16x16x32_bf16 v[84:87], v[140:143], v[186:189], v[84:87]
	v_mfma_f32_16x16x32_bf16 v[56:59], v[154:157], v[186:189], v[56:59]
	v_mfma_f32_16x16x32_bf16 v[108:111], v[150:153], v[166:169], v[108:111]
	v_mfma_f32_16x16x32_bf16 v[76:79], v[158:161], v[166:169], v[76:79]
	v_mfma_f32_16x16x32_bf16 v[104:107], v[150:153], v[174:177], v[104:107]
	v_mfma_f32_16x16x32_bf16 v[72:75], v[158:161], v[174:177], v[72:75]
	v_mfma_f32_16x16x32_bf16 v[92:95], v[150:153], v[182:185], v[92:95]
	v_mfma_f32_16x16x32_bf16 v[64:67], v[158:161], v[182:185], v[64:67]
	v_mfma_f32_16x16x32_bf16 v[84:87], v[150:153], v[190:193], v[84:87]
	v_mfma_f32_16x16x32_bf16 v[56:59], v[158:161], v[190:193], v[56:59]
	s_barrier
	s_add_u32 s4, s50, 0x80080
	s_addc_u32 s5, s51, 0
	s_add_i32 s42, s43, s21
	s_mov_b32 m0, s42
	s_nop 0
	global_load_lds_dwordx4 v130, s[4:5]
	s_add_i32 m0, s42, 0x2000
	s_nop 0
	global_load_lds_dwordx4 v128, s[4:5]
	s_waitcnt vmcnt(6)
	s_barrier
	v_mfma_f32_16x16x32_bf16 v[44:47], v[194:197], v[162:165], v[44:47]
	v_mfma_f32_16x16x32_bf16 v[12:15], v[202:205], v[162:165], v[12:15]
	v_mfma_f32_16x16x32_bf16 v[36:39], v[194:197], v[170:173], v[36:39]
	v_mfma_f32_16x16x32_bf16 v[8:11], v[202:205], v[170:173], v[8:11]
	v_mfma_f32_16x16x32_bf16 v[28:31], v[194:197], v[178:181], v[28:31]
	v_mfma_f32_16x16x32_bf16 v[4:7], v[202:205], v[178:181], v[4:7]
	v_mfma_f32_16x16x32_bf16 v[20:23], v[194:197], v[186:189], v[20:23]
	v_mfma_f32_16x16x32_bf16 v[0:3], v[202:205], v[186:189], v[0:3]
	v_mfma_f32_16x16x32_bf16 v[44:47], v[198:201], v[166:169], v[44:47]
	v_mfma_f32_16x16x32_bf16 v[12:15], v[206:209], v[166:169], v[12:15]
	v_mfma_f32_16x16x32_bf16 v[36:39], v[198:201], v[174:177], v[36:39]
	v_mfma_f32_16x16x32_bf16 v[8:11], v[206:209], v[174:177], v[8:11]
	v_mfma_f32_16x16x32_bf16 v[28:31], v[198:201], v[182:185], v[28:31]
	v_mfma_f32_16x16x32_bf16 v[4:7], v[206:209], v[182:185], v[4:7]
	v_mfma_f32_16x16x32_bf16 v[20:23], v[198:201], v[190:193], v[20:23]
	v_mfma_f32_16x16x32_bf16 v[0:3], v[206:209], v[190:193], v[0:3]
	s_add_i32 s73, s73, 2
	s_add_u32 s61, s61, 0x100
	s_addc_u32 s67, s67, 0
	s_cmp_gt_u32 s73, 29
	s_mov_b64 s[74:75], s[76:77]
	s_barrier
	s_cbranch_scc0 .LBB0_850
	v_lshl_or_b32 v140, s41, 8, v146
	v_lshl_add_u32 v143, s72, 8, v144
	v_lshlrev_b32_e32 v140, 2, v140
	v_lshl_add_u32 v143, v143, 13, v140
	s_mov_b32 s41, s60
	s_mov_b32 s72, s66
	s_mov_b64 s[50:51], s[70:71]
	s_mov_b64 s[74:75], s[68:69]
	v_mov_b32_e32 v141, v143
	v_mov_b32_e32 v142, v143
	global_load_dwordx4 v[166:169], v140, s[14:15] offset:0
	global_load_dwordx4 v[150:153], v141, s[10:11] offset:0
	v_add_u32_e32 v141, 0x20000, v141
	global_load_dwordx4 v[154:157], v141, s[10:11] offset:0
	v_add_u32_e32 v141, 0x20000, v141
	global_load_dwordx4 v[158:161], v141, s[10:11] offset:0
	v_add_u32_e32 v141, 0x20000, v141
	global_load_dwordx4 v[162:165], v141, s[10:11] offset:0
	v_add_u32_e32 v141, 0xa0000, v141
	s_waitcnt vmcnt(3)
	v_pk_fma_f32 v[150:151], v[124:125], v[166:167], v[150:151]
	v_pk_fma_f32 v[152:153], v[126:127], v[168:169], v[152:153]
	global_store_dwordx4 v142, v[150:153], s[12:13] offset:0
	v_add_u32_e32 v142, 0x20000, v142
	global_load_dwordx4 v[150:153], v141, s[10:11] offset:0
	v_add_u32_e32 v141, 0x20000, v141
	s_waitcnt vmcnt(4)
	v_pk_fma_f32 v[154:155], v[120:121], v[166:167], v[154:155]
	v_pk_fma_f32 v[156:157], v[122:123], v[168:169], v[156:157]
	global_store_dwordx4 v142, v[154:157], s[12:13] offset:0
	v_add_u32_e32 v142, 0x20000, v142
	global_load_dwordx4 v[154:157], v141, s[10:11] offset:0
	v_add_u32_e32 v141, 0x20000, v141
	s_waitcnt vmcnt(5)
	v_pk_fma_f32 v[158:159], v[116:117], v[166:167], v[158:159]
	v_pk_fma_f32 v[160:161], v[118:119], v[168:169], v[160:161]
	global_store_dwordx4 v142, v[158:161], s[12:13] offset:0
	v_add_u32_e32 v142, 0x20000, v142
	global_load_dwordx4 v[158:161], v141, s[10:11] offset:0
	v_add_u32_e32 v141, 0x20000, v141
	s_waitcnt vmcnt(6)
	v_pk_fma_f32 v[162:163], v[112:113], v[166:167], v[162:163]
	v_pk_fma_f32 v[164:165], v[114:115], v[168:169], v[164:165]
	global_store_dwordx4 v142, v[162:165], s[12:13] offset:0
	v_add_u32_e32 v142, 0xa0000, v142
	global_load_dwordx4 v[162:165], v141, s[10:11] offset:0
	v_add_u32_e32 v141, 0x20000, v141
	s_waitcnt vmcnt(6)
	v_pk_fma_f32 v[150:151], v[108:109], v[166:167], v[150:151]
	v_pk_fma_f32 v[152:153], v[110:111], v[168:169], v[152:153]
	global_store_dwordx4 v142, v[150:153], s[12:13] offset:0
	v_add_u32_e32 v142, 0x20000, v142
	s_waitcnt vmcnt(5)
	v_pk_fma_f32 v[154:155], v[104:105], v[166:167], v[154:155]
	v_pk_fma_f32 v[156:157], v[106:107], v[168:169], v[156:157]
	global_store_dwordx4 v142, v[154:157], s[12:13] offset:0
	v_add_u32_e32 v142, 0x20000, v142
	s_waitcnt vmcnt(4)
	v_pk_fma_f32 v[158:159], v[92:93], v[166:167], v[158:159]
	v_pk_fma_f32 v[160:161], v[94:95], v[168:169], v[160:161]
	global_store_dwordx4 v142, v[158:161], s[12:13] offset:0
	v_add_u32_e32 v142, 0x20000, v142
	s_waitcnt vmcnt(3)
	v_pk_fma_f32 v[162:163], v[84:85], v[166:167], v[162:163]
	v_pk_fma_f32 v[164:165], v[86:87], v[168:169], v[164:165]
	global_store_dwordx4 v142, v[162:165], s[12:13] offset:0
	v_add_u32_e32 v142, 0x20000, v142
	v_mov_b32_e32 v141, v143
	v_mov_b32_e32 v142, v143
	global_load_dwordx4 v[166:169], v140, s[14:15] offset:64
	global_load_dwordx4 v[150:153], v141, s[10:11] offset:64
	v_add_u32_e32 v141, 0x20000, v141
	global_load_dwordx4 v[154:157], v141, s[10:11] offset:64
	v_add_u32_e32 v141, 0x20000, v141
	global_load_dwordx4 v[158:161], v141, s[10:11] offset:64
	v_add_u32_e32 v141, 0x20000, v141
	global_load_dwordx4 v[162:165], v141, s[10:11] offset:64
	v_add_u32_e32 v141, 0xa0000, v141
	s_waitcnt vmcnt(3)
	v_pk_fma_f32 v[150:151], v[100:101], v[166:167], v[150:151]
	v_pk_fma_f32 v[152:153], v[102:103], v[168:169], v[152:153]
	global_store_dwordx4 v142, v[150:153], s[12:13] offset:64
	v_add_u32_e32 v142, 0x20000, v142
	global_load_dwordx4 v[150:153], v141, s[10:11] offset:64
	v_add_u32_e32 v141, 0x20000, v141
	s_waitcnt vmcnt(4)
	v_pk_fma_f32 v[154:155], v[96:97], v[166:167], v[154:155]
	v_pk_fma_f32 v[156:157], v[98:99], v[168:169], v[156:157]
	global_store_dwordx4 v142, v[154:157], s[12:13] offset:64
	v_add_u32_e32 v142, 0x20000, v142
	global_load_dwordx4 v[154:157], v141, s[10:11] offset:64
	v_add_u32_e32 v141, 0x20000, v141
	s_waitcnt vmcnt(5)
	v_pk_fma_f32 v[158:159], v[88:89], v[166:167], v[158:159]
	v_pk_fma_f32 v[160:161], v[90:91], v[168:169], v[160:161]
	global_store_dwordx4 v142, v[158:161], s[12:13] offset:64
	v_add_u32_e32 v142, 0x20000, v142
	global_load_dwordx4 v[158:161], v141, s[10:11] offset:64
	v_add_u32_e32 v141, 0x20000, v141
	s_waitcnt vmcnt(6)
	v_pk_fma_f32 v[162:163], v[80:81], v[166:167], v[162:163]
	v_pk_fma_f32 v[164:165], v[82:83], v[168:169], v[164:165]
	global_store_dwordx4 v142, v[162:165], s[12:13] offset:64
	v_add_u32_e32 v142, 0xa0000, v142
	global_load_dwordx4 v[162:165], v141, s[10:11] offset:64
	v_add_u32_e32 v141, 0x20000, v141
	s_waitcnt vmcnt(6)
	v_pk_fma_f32 v[150:151], v[76:77], v[166:167], v[150:151]
	v_pk_fma_f32 v[152:153], v[78:79], v[168:169], v[152:153]
	global_store_dwordx4 v142, v[150:153], s[12:13] offset:64
	v_add_u32_e32 v142, 0x20000, v142
	s_waitcnt vmcnt(5)
	v_pk_fma_f32 v[154:155], v[72:73], v[166:167], v[154:155]
	v_pk_fma_f32 v[156:157], v[74:75], v[168:169], v[156:157]
	global_store_dwordx4 v142, v[154:157], s[12:13] offset:64
	v_add_u32_e32 v142, 0x20000, v142
	s_waitcnt vmcnt(4)
	v_pk_fma_f32 v[158:159], v[64:65], v[166:167], v[158:159]
	v_pk_fma_f32 v[160:161], v[66:67], v[168:169], v[160:161]
	global_store_dwordx4 v142, v[158:161], s[12:13] offset:64
	v_add_u32_e32 v142, 0x20000, v142
	s_waitcnt vmcnt(3)
	v_pk_fma_f32 v[162:163], v[56:57], v[166:167], v[162:163]
	v_pk_fma_f32 v[164:165], v[58:59], v[168:169], v[164:165]
	global_store_dwordx4 v142, v[162:165], s[12:13] offset:64
	v_add_u32_e32 v142, 0x20000, v142
	v_mov_b32_e32 v141, v143
	v_mov_b32_e32 v142, v143
	global_load_dwordx4 v[166:169], v140, s[14:15] offset:512
	global_load_dwordx4 v[150:153], v141, s[10:11] offset:512
	v_add_u32_e32 v141, 0x20000, v141
	global_load_dwordx4 v[154:157], v141, s[10:11] offset:512
	v_add_u32_e32 v141, 0x20000, v141
	global_load_dwordx4 v[158:161], v141, s[10:11] offset:512
	v_add_u32_e32 v141, 0x20000, v141
	global_load_dwordx4 v[162:165], v141, s[10:11] offset:512
	v_add_u32_e32 v141, 0xa0000, v141
	s_waitcnt vmcnt(3)
	v_pk_fma_f32 v[150:151], v[68:69], v[166:167], v[150:151]
	v_pk_fma_f32 v[152:153], v[70:71], v[168:169], v[152:153]
	global_store_dwordx4 v142, v[150:153], s[12:13] offset:512
	v_add_u32_e32 v142, 0x20000, v142
	global_load_dwordx4 v[150:153], v141, s[10:11] offset:512
	v_add_u32_e32 v141, 0x20000, v141
	s_waitcnt vmcnt(4)
	v_pk_fma_f32 v[154:155], v[60:61], v[166:167], v[154:155]
	v_pk_fma_f32 v[156:157], v[62:63], v[168:169], v[156:157]
	global_store_dwordx4 v142, v[154:157], s[12:13] offset:512
	v_add_u32_e32 v142, 0x20000, v142
	global_load_dwordx4 v[154:157], v141, s[10:11] offset:512
	v_add_u32_e32 v141, 0x20000, v141
	s_waitcnt vmcnt(5)
	v_pk_fma_f32 v[158:159], v[52:53], v[166:167], v[158:159]
	v_pk_fma_f32 v[160:161], v[54:55], v[168:169], v[160:161]
	global_store_dwordx4 v142, v[158:161], s[12:13] offset:512
	v_add_u32_e32 v142, 0x20000, v142
	global_load_dwordx4 v[158:161], v141, s[10:11] offset:512
	v_add_u32_e32 v141, 0x20000, v141
	s_waitcnt vmcnt(6)
	v_pk_fma_f32 v[162:163], v[48:49], v[166:167], v[162:163]
	v_pk_fma_f32 v[164:165], v[50:51], v[168:169], v[164:165]
	global_store_dwordx4 v142, v[162:165], s[12:13] offset:512
	v_add_u32_e32 v142, 0xa0000, v142
	global_load_dwordx4 v[162:165], v141, s[10:11] offset:512
	v_add_u32_e32 v141, 0x20000, v141
	s_waitcnt vmcnt(6)
	v_pk_fma_f32 v[150:151], v[44:45], v[166:167], v[150:151]
	v_pk_fma_f32 v[152:153], v[46:47], v[168:169], v[152:153]
	global_store_dwordx4 v142, v[150:153], s[12:13] offset:512
	v_add_u32_e32 v142, 0x20000, v142
	s_waitcnt vmcnt(5)
	v_pk_fma_f32 v[154:155], v[36:37], v[166:167], v[154:155]
	v_pk_fma_f32 v[156:157], v[38:39], v[168:169], v[156:157]
	global_store_dwordx4 v142, v[154:157], s[12:13] offset:512
	v_add_u32_e32 v142, 0x20000, v142
	s_waitcnt vmcnt(4)
	v_pk_fma_f32 v[158:159], v[28:29], v[166:167], v[158:159]
	v_pk_fma_f32 v[160:161], v[30:31], v[168:169], v[160:161]
	global_store_dwordx4 v142, v[158:161], s[12:13] offset:512
	v_add_u32_e32 v142, 0x20000, v142
	s_waitcnt vmcnt(3)
	v_pk_fma_f32 v[162:163], v[20:21], v[166:167], v[162:163]
	v_pk_fma_f32 v[164:165], v[22:23], v[168:169], v[164:165]
	global_store_dwordx4 v142, v[162:165], s[12:13] offset:512
	v_add_u32_e32 v142, 0x20000, v142
	v_mov_b32_e32 v141, v143
	v_mov_b32_e32 v142, v143
	global_load_dwordx4 v[166:169], v140, s[14:15] offset:576
	global_load_dwordx4 v[150:153], v141, s[10:11] offset:576
	v_add_u32_e32 v141, 0x20000, v141
	global_load_dwordx4 v[154:157], v141, s[10:11] offset:576
	v_add_u32_e32 v141, 0x20000, v141
	global_load_dwordx4 v[158:161], v141, s[10:11] offset:576
	v_add_u32_e32 v141, 0x20000, v141
	global_load_dwordx4 v[162:165], v141, s[10:11] offset:576
	v_add_u32_e32 v141, 0xa0000, v141
	s_waitcnt vmcnt(3)
	v_pk_fma_f32 v[150:151], v[40:41], v[166:167], v[150:151]
	v_pk_fma_f32 v[152:153], v[42:43], v[168:169], v[152:153]
	global_store_dwordx4 v142, v[150:153], s[12:13] offset:576
	v_add_u32_e32 v142, 0x20000, v142
	global_load_dwordx4 v[150:153], v141, s[10:11] offset:576
	v_add_u32_e32 v141, 0x20000, v141
	s_waitcnt vmcnt(4)
	v_pk_fma_f32 v[154:155], v[32:33], v[166:167], v[154:155]
	v_pk_fma_f32 v[156:157], v[34:35], v[168:169], v[156:157]
	global_store_dwordx4 v142, v[154:157], s[12:13] offset:576
	v_add_u32_e32 v142, 0x20000, v142
	global_load_dwordx4 v[154:157], v141, s[10:11] offset:576
	v_add_u32_e32 v141, 0x20000, v141
	s_waitcnt vmcnt(5)
	v_pk_fma_f32 v[158:159], v[24:25], v[166:167], v[158:159]
	v_pk_fma_f32 v[160:161], v[26:27], v[168:169], v[160:161]
	global_store_dwordx4 v142, v[158:161], s[12:13] offset:576
	v_add_u32_e32 v142, 0x20000, v142
	global_load_dwordx4 v[158:161], v141, s[10:11] offset:576
	v_add_u32_e32 v141, 0x20000, v141
	s_waitcnt vmcnt(6)
	v_pk_fma_f32 v[162:163], v[16:17], v[166:167], v[162:163]
	v_pk_fma_f32 v[164:165], v[18:19], v[168:169], v[164:165]
	global_store_dwordx4 v142, v[162:165], s[12:13] offset:576
	v_add_u32_e32 v142, 0xa0000, v142
	global_load_dwordx4 v[162:165], v141, s[10:11] offset:576
	v_add_u32_e32 v141, 0x20000, v141
	s_waitcnt vmcnt(6)
	v_pk_fma_f32 v[150:151], v[12:13], v[166:167], v[150:151]
	v_pk_fma_f32 v[152:153], v[14:15], v[168:169], v[152:153]
	global_store_dwordx4 v142, v[150:153], s[12:13] offset:576
	v_add_u32_e32 v142, 0x20000, v142
	s_waitcnt vmcnt(5)
	v_pk_fma_f32 v[154:155], v[8:9], v[166:167], v[154:155]
	v_pk_fma_f32 v[156:157], v[10:11], v[168:169], v[156:157]
	global_store_dwordx4 v142, v[154:157], s[12:13] offset:576
	v_add_u32_e32 v142, 0x20000, v142
	s_waitcnt vmcnt(4)
	v_pk_fma_f32 v[158:159], v[4:5], v[166:167], v[158:159]
	v_pk_fma_f32 v[160:161], v[6:7], v[168:169], v[160:161]
	global_store_dwordx4 v142, v[158:161], s[12:13] offset:576
	v_add_u32_e32 v142, 0x20000, v142
	s_waitcnt vmcnt(3)
	v_pk_fma_f32 v[162:163], v[0:1], v[166:167], v[162:163]
	v_pk_fma_f32 v[164:165], v[2:3], v[168:169], v[164:165]
	global_store_dwordx4 v142, v[162:165], s[12:13] offset:576
	v_add_u32_e32 v142, 0x20000, v142
	s_and_b64 vcc, exec, s[6:7]
	s_cbranch_vccz .LBB0_843
	s_waitcnt vmcnt(0)
	s_cmpk_gt_u32 s20, 0xff
	s_cbranch_scc1 .LBB0_854
	s_barrier

.LBB0_986:
	ds_read_b128 v[152:155], v148
	ds_read_b128 v[156:159], v148 offset:1024
	ds_read_b128 v[160:163], v148 offset:2048
	ds_read_b128 v[164:167], v148 offset:3072
	s_add_u32 s4, s60, 0xfff80080
	s_addc_u32 s5, s61, -1
	s_cmp_eq_u32 s64, 28
	s_cselect_b32 s5, s0, s5
	s_cselect_b32 s4, s1, s4
	s_cselect_b32 s51, s11, s37
	s_cselect_b32 s50, s13, s36
	s_add_i32 m0, s19, 0xc000
	ds_read_b128 v[168:171], v149
	ds_read_b128 v[172:175], v149 offset:1024
	ds_read_b128 v[176:179], v149 offset:2048
	ds_read_b128 v[180:183], v149 offset:3072
	ds_read_b128 v[184:187], v149 offset:4096
	ds_read_b128 v[188:191], v149 offset:5120
	ds_read_b128 v[192:195], v149 offset:6144
	ds_read_b128 v[196:199], v149 offset:7168
	global_load_lds_dwordx4 v138, s[60:61]
	s_add_i32 m0, s19, 0xe000
	s_nop 0
	global_load_lds_dwordx4 v140, s[60:61]
	s_waitcnt lgkmcnt(8)
	s_barrier
	s_waitcnt lgkmcnt(0)
	s_waitcnt lgkmcnt(0)
	v_mfma_f32_16x16x32_bf16 v[124:127], v[152:155], v[168:171], v[124:127]
	v_mfma_f32_16x16x32_bf16 v[120:123], v[160:163], v[168:171], v[120:123]
	v_mfma_f32_16x16x32_bf16 v[108:111], v[152:155], v[176:179], v[108:111]
	v_mfma_f32_16x16x32_bf16 v[104:107], v[160:163], v[176:179], v[104:107]
	v_mfma_f32_16x16x32_bf16 v[92:95], v[152:155], v[184:187], v[92:95]
	v_mfma_f32_16x16x32_bf16 v[88:91], v[160:163], v[184:187], v[88:91]
	v_mfma_f32_16x16x32_bf16 v[76:79], v[152:155], v[192:195], v[76:79]
	v_mfma_f32_16x16x32_bf16 v[72:75], v[160:163], v[192:195], v[72:75]
	v_mfma_f32_16x16x32_bf16 v[124:127], v[156:159], v[172:175], v[124:127]
	v_mfma_f32_16x16x32_bf16 v[120:123], v[164:167], v[172:175], v[120:123]
	v_mfma_f32_16x16x32_bf16 v[108:111], v[156:159], v[180:183], v[108:111]
	v_mfma_f32_16x16x32_bf16 v[104:107], v[164:167], v[180:183], v[104:107]
	v_mfma_f32_16x16x32_bf16 v[92:95], v[156:159], v[188:191], v[92:95]
	v_mfma_f32_16x16x32_bf16 v[88:91], v[164:167], v[188:191], v[88:91]
	v_mfma_f32_16x16x32_bf16 v[76:79], v[156:159], v[196:199], v[76:79]
	v_mfma_f32_16x16x32_bf16 v[72:75], v[164:167], v[196:199], v[72:75]
	s_barrier
	s_add_i32 s42, s41, s21
	s_add_u32 s98, s50, s8
	s_addc_u32 s99, s51, s9
	s_mov_b32 m0, s42
	ds_read_b128 v[200:203], v150
	ds_read_b128 v[204:207], v150 offset:1024
	ds_read_b128 v[208:211], v150 offset:2048
	ds_read_b128 v[212:215], v150 offset:3072
	global_load_lds_dwordx4 v134, s[50:51]
	s_add_i32 m0, s42, 0x2000
	s_nop 0
	global_load_lds_dwordx4 v130, s[50:51]
	s_barrier
	s_waitcnt lgkmcnt(0)
	s_waitcnt lgkmcnt(0)
	v_mfma_f32_16x16x32_bf16 v[116:119], v[200:203], v[168:171], v[116:119]
	v_mfma_f32_16x16x32_bf16 v[112:115], v[208:211], v[168:171], v[112:115]
	v_mfma_f32_16x16x32_bf16 v[100:103], v[200:203], v[176:179], v[100:103]
	v_mfma_f32_16x16x32_bf16 v[96:99], v[208:211], v[176:179], v[96:99]
	v_mfma_f32_16x16x32_bf16 v[84:87], v[200:203], v[184:187], v[84:87]
	v_mfma_f32_16x16x32_bf16 v[80:83], v[208:211], v[184:187], v[80:83]
	v_mfma_f32_16x16x32_bf16 v[68:71], v[200:203], v[192:195], v[68:71]
	v_mfma_f32_16x16x32_bf16 v[64:67], v[208:211], v[192:195], v[64:67]
	v_mfma_f32_16x16x32_bf16 v[116:119], v[204:207], v[172:175], v[116:119]
	v_mfma_f32_16x16x32_bf16 v[112:115], v[212:215], v[172:175], v[112:115]
	v_mfma_f32_16x16x32_bf16 v[100:103], v[204:207], v[180:183], v[100:103]
	v_mfma_f32_16x16x32_bf16 v[96:99], v[212:215], v[180:183], v[96:99]
	v_mfma_f32_16x16x32_bf16 v[84:87], v[204:207], v[188:191], v[84:87]
	v_mfma_f32_16x16x32_bf16 v[80:83], v[212:215], v[188:191], v[80:83]
	v_mfma_f32_16x16x32_bf16 v[68:71], v[204:207], v[196:199], v[68:71]
	v_mfma_f32_16x16x32_bf16 v[64:67], v[212:215], v[196:199], v[64:67]
	s_mov_b32 m0, s19
	s_add_u32 s100, s4, s8
	s_addc_u32 s101, s5, s9
	s_barrier
	ds_read_b128 v[168:171], v149 offset:16384
	ds_read_b128 v[172:175], v149 offset:17408
	ds_read_b128 v[176:179], v149 offset:18432
	ds_read_b128 v[180:183], v149 offset:19456
	ds_read_b128 v[184:187], v149 offset:20480
	ds_read_b128 v[188:191], v149 offset:21504
	ds_read_b128 v[192:195], v149 offset:22528
	ds_read_b128 v[196:199], v149 offset:23552
	global_load_lds_dwordx4 v136, s[4:5]
	s_mov_b32 m0, s24
	s_nop 0
	global_load_lds_dwordx4 v132, s[4:5]
	s_barrier
	s_waitcnt lgkmcnt(0)
	s_waitcnt lgkmcnt(0)
	v_mfma_f32_16x16x32_bf16 v[60:63], v[152:155], v[168:171], v[60:63]
	v_mfma_f32_16x16x32_bf16 v[56:59], v[160:163], v[168:171], v[56:59]
	v_mfma_f32_16x16x32_bf16 v[44:47], v[152:155], v[176:179], v[44:47]
	v_mfma_f32_16x16x32_bf16 v[40:43], v[160:163], v[176:179], v[40:43]
	v_mfma_f32_16x16x32_bf16 v[28:31], v[152:155], v[184:187], v[28:31]
	v_mfma_f32_16x16x32_bf16 v[24:27], v[160:163], v[184:187], v[24:27]
	v_mfma_f32_16x16x32_bf16 v[12:15], v[152:155], v[192:195], v[12:15]
	v_mfma_f32_16x16x32_bf16 v[8:11], v[160:163], v[192:195], v[8:11]
	v_mfma_f32_16x16x32_bf16 v[60:63], v[156:159], v[172:175], v[60:63]
	v_mfma_f32_16x16x32_bf16 v[56:59], v[164:167], v[172:175], v[56:59]
	v_mfma_f32_16x16x32_bf16 v[44:47], v[156:159], v[180:183], v[44:47]
	v_mfma_f32_16x16x32_bf16 v[40:43], v[164:167], v[180:183], v[40:43]
	v_mfma_f32_16x16x32_bf16 v[28:31], v[156:159], v[188:191], v[28:31]
	v_mfma_f32_16x16x32_bf16 v[24:27], v[164:167], v[188:191], v[24:27]
	v_mfma_f32_16x16x32_bf16 v[12:15], v[156:159], v[196:199], v[12:15]
	v_mfma_f32_16x16x32_bf16 v[8:11], v[164:167], v[196:199], v[8:11]
	s_barrier
	s_add_u32 s42, s50, 0x80000
	s_addc_u32 s43, s51, 0
	s_add_i32 s44, s46, s21
	s_mov_b32 m0, s44
	s_nop 0
	global_load_lds_dwordx4 v134, s[42:43]
	s_add_i32 m0, s44, 0x2000
	s_nop 0
	global_load_lds_dwordx4 v130, s[42:43]
	s_waitcnt vmcnt(6)
	s_barrier
	v_mfma_f32_16x16x32_bf16 v[52:55], v[200:203], v[168:171], v[52:55]
	v_mfma_f32_16x16x32_bf16 v[48:51], v[208:211], v[168:171], v[48:51]
	v_mfma_f32_16x16x32_bf16 v[36:39], v[200:203], v[176:179], v[36:39]
	v_mfma_f32_16x16x32_bf16 v[32:35], v[208:211], v[176:179], v[32:35]
	v_mfma_f32_16x16x32_bf16 v[20:23], v[200:203], v[184:187], v[20:23]
	v_mfma_f32_16x16x32_bf16 v[16:19], v[208:211], v[184:187], v[16:19]
	v_mfma_f32_16x16x32_bf16 v[4:7], v[200:203], v[192:195], v[4:7]
	v_mfma_f32_16x16x32_bf16 v[0:3], v[208:211], v[192:195], v[0:3]
	v_mfma_f32_16x16x32_bf16 v[52:55], v[204:207], v[172:175], v[52:55]
	v_mfma_f32_16x16x32_bf16 v[48:51], v[212:215], v[172:175], v[48:51]
	v_mfma_f32_16x16x32_bf16 v[36:39], v[204:207], v[180:183], v[36:39]
	v_mfma_f32_16x16x32_bf16 v[32:35], v[212:215], v[180:183], v[32:35]
	v_mfma_f32_16x16x32_bf16 v[20:23], v[204:207], v[188:191], v[20:23]
	v_mfma_f32_16x16x32_bf16 v[16:19], v[212:215], v[188:191], v[16:19]
	v_mfma_f32_16x16x32_bf16 v[4:7], v[204:207], v[196:199], v[4:7]
	v_mfma_f32_16x16x32_bf16 v[0:3], v[212:215], v[196:199], v[0:3]
	s_add_i32 s42, 0, 0x18000
	v_add_u32_e32 v151, s42, v146
	s_barrier
	ds_read_b128 v[152:155], v151
	ds_read_b128 v[156:159], v151 offset:1024
	ds_read_b128 v[160:163], v151 offset:2048
	ds_read_b128 v[164:167], v151 offset:3072
	s_add_u32 s4, s4, 0x80000
	s_addc_u32 s5, s5, 0
	s_mov_b32 m0, s25
	ds_read_b128 v[168:171], v149 offset:32768
	ds_read_b128 v[172:175], v149 offset:33792
	ds_read_b128 v[176:179], v149 offset:34816
	ds_read_b128 v[180:183], v149 offset:35840
	ds_read_b128 v[184:187], v149 offset:36864
	ds_read_b128 v[188:191], v149 offset:37888
	ds_read_b128 v[192:195], v149 offset:38912
	ds_read_b128 v[196:199], v149 offset:39936
	global_load_lds_dwordx4 v136, s[4:5]
	s_mov_b32 m0, s28
	s_nop 0
	global_load_lds_dwordx4 v132, s[4:5]
	s_waitcnt lgkmcnt(8)
	s_barrier
	s_waitcnt lgkmcnt(0)
	s_waitcnt lgkmcnt(0)
	v_mfma_f32_16x16x32_bf16 v[124:127], v[152:155], v[168:171], v[124:127]
	v_mfma_f32_16x16x32_bf16 v[120:123], v[160:163], v[168:171], v[120:123]
	v_mfma_f32_16x16x32_bf16 v[108:111], v[152:155], v[176:179], v[108:111]
	v_mfma_f32_16x16x32_bf16 v[104:107], v[160:163], v[176:179], v[104:107]
	v_mfma_f32_16x16x32_bf16 v[92:95], v[152:155], v[184:187], v[92:95]
	v_mfma_f32_16x16x32_bf16 v[88:91], v[160:163], v[184:187], v[88:91]
	v_mfma_f32_16x16x32_bf16 v[76:79], v[152:155], v[192:195], v[76:79]
	v_mfma_f32_16x16x32_bf16 v[72:75], v[160:163], v[192:195], v[72:75]
	v_mfma_f32_16x16x32_bf16 v[124:127], v[156:159], v[172:175], v[124:127]
	v_mfma_f32_16x16x32_bf16 v[120:123], v[164:167], v[172:175], v[120:123]
	v_mfma_f32_16x16x32_bf16 v[108:111], v[156:159], v[180:183], v[108:111]
	v_mfma_f32_16x16x32_bf16 v[104:107], v[164:167], v[180:183], v[104:107]
	v_mfma_f32_16x16x32_bf16 v[92:95], v[156:159], v[188:191], v[92:95]
	v_mfma_f32_16x16x32_bf16 v[88:91], v[164:167], v[188:191], v[88:91]
	v_mfma_f32_16x16x32_bf16 v[76:79], v[156:159], v[196:199], v[76:79]
	v_mfma_f32_16x16x32_bf16 v[72:75], v[164:167], v[196:199], v[72:75]
	s_barrier
	s_add_i32 s43, 0, 0x1c000
	s_add_i32 s4, s42, s21
	v_add_u32_e32 v151, s43, v146
	s_mov_b32 m0, s4
	ds_read_b128 v[200:203], v151
	ds_read_b128 v[204:207], v151 offset:1024
	ds_read_b128 v[208:211], v151 offset:2048
	ds_read_b128 v[212:215], v151 offset:3072
	global_load_lds_dwordx4 v134, s[98:99]
	s_add_i32 m0, s4, 0x2000
	s_nop 0
	global_load_lds_dwordx4 v130, s[98:99]
	s_barrier
	s_waitcnt lgkmcnt(0)
	s_waitcnt lgkmcnt(0)
	v_mfma_f32_16x16x32_bf16 v[116:119], v[200:203], v[168:171], v[116:119]
	v_mfma_f32_16x16x32_bf16 v[112:115], v[208:211], v[168:171], v[112:115]
	v_mfma_f32_16x16x32_bf16 v[100:103], v[200:203], v[176:179], v[100:103]
	v_mfma_f32_16x16x32_bf16 v[96:99], v[208:211], v[176:179], v[96:99]
	v_mfma_f32_16x16x32_bf16 v[84:87], v[200:203], v[184:187], v[84:87]
	v_mfma_f32_16x16x32_bf16 v[80:83], v[208:211], v[184:187], v[80:83]
	v_mfma_f32_16x16x32_bf16 v[68:71], v[200:203], v[192:195], v[68:71]
	v_mfma_f32_16x16x32_bf16 v[64:67], v[208:211], v[192:195], v[64:67]
	v_mfma_f32_16x16x32_bf16 v[116:119], v[204:207], v[172:175], v[116:119]
	v_mfma_f32_16x16x32_bf16 v[112:115], v[212:215], v[172:175], v[112:115]
	v_mfma_f32_16x16x32_bf16 v[100:103], v[204:207], v[180:183], v[100:103]
	v_mfma_f32_16x16x32_bf16 v[96:99], v[212:215], v[180:183], v[96:99]
	v_mfma_f32_16x16x32_bf16 v[84:87], v[204:207], v[188:191], v[84:87]
	v_mfma_f32_16x16x32_bf16 v[80:83], v[212:215], v[188:191], v[80:83]
	v_mfma_f32_16x16x32_bf16 v[68:71], v[204:207], v[196:199], v[68:71]
	v_mfma_f32_16x16x32_bf16 v[64:67], v[212:215], v[196:199], v[64:67]
	s_mov_b32 m0, s33
	s_barrier
	ds_read_b128 v[168:171], v149 offset:49152
	ds_read_b128 v[172:175], v149 offset:50176
	ds_read_b128 v[176:179], v149 offset:51200
	ds_read_b128 v[180:183], v149 offset:52224
	ds_read_b128 v[184:187], v149 offset:53248
	ds_read_b128 v[188:191], v149 offset:54272
	ds_read_b128 v[192:195], v149 offset:55296
	ds_read_b128 v[196:199], v149 offset:56320
	global_load_lds_dwordx4 v136, s[100:101]
	s_mov_b32 m0, s40
	s_nop 0
	global_load_lds_dwordx4 v132, s[100:101]
	s_barrier
	s_waitcnt lgkmcnt(0)
	s_waitcnt lgkmcnt(0)
	v_mfma_f32_16x16x32_bf16 v[60:63], v[152:155], v[168:171], v[60:63]
	v_mfma_f32_16x16x32_bf16 v[56:59], v[160:163], v[168:171], v[56:59]
	v_mfma_f32_16x16x32_bf16 v[44:47], v[152:155], v[176:179], v[44:47]
	v_mfma_f32_16x16x32_bf16 v[40:43], v[160:163], v[176:179], v[40:43]
	v_mfma_f32_16x16x32_bf16 v[28:31], v[152:155], v[184:187], v[28:31]
	v_mfma_f32_16x16x32_bf16 v[24:27], v[160:163], v[184:187], v[24:27]
	v_mfma_f32_16x16x32_bf16 v[12:15], v[152:155], v[192:195], v[12:15]
	v_mfma_f32_16x16x32_bf16 v[8:11], v[160:163], v[192:195], v[8:11]
	v_mfma_f32_16x16x32_bf16 v[60:63], v[156:159], v[172:175], v[60:63]
	v_mfma_f32_16x16x32_bf16 v[56:59], v[164:167], v[172:175], v[56:59]
	v_mfma_f32_16x16x32_bf16 v[44:47], v[156:159], v[180:183], v[44:47]
	v_mfma_f32_16x16x32_bf16 v[40:43], v[164:167], v[180:183], v[40:43]
	v_mfma_f32_16x16x32_bf16 v[28:31], v[156:159], v[188:191], v[28:31]
	v_mfma_f32_16x16x32_bf16 v[24:27], v[164:167], v[188:191], v[24:27]
	v_mfma_f32_16x16x32_bf16 v[12:15], v[156:159], v[196:199], v[12:15]
	v_mfma_f32_16x16x32_bf16 v[8:11], v[164:167], v[196:199], v[8:11]
	s_barrier
	s_add_u32 s4, s50, 0x80080
	s_addc_u32 s5, s51, 0
	s_add_i32 s42, s43, s21
	s_mov_b32 m0, s42
	s_nop 0
	global_load_lds_dwordx4 v134, s[4:5]
	s_add_i32 m0, s42, 0x2000
	s_nop 0
	global_load_lds_dwordx4 v130, s[4:5]
	s_waitcnt vmcnt(6)
	s_barrier
	v_mfma_f32_16x16x32_bf16 v[52:55], v[200:203], v[168:171], v[52:55]
	v_mfma_f32_16x16x32_bf16 v[48:51], v[208:211], v[168:171], v[48:51]
	v_mfma_f32_16x16x32_bf16 v[36:39], v[200:203], v[176:179], v[36:39]
	v_mfma_f32_16x16x32_bf16 v[32:35], v[208:211], v[176:179], v[32:35]
	v_mfma_f32_16x16x32_bf16 v[20:23], v[200:203], v[184:187], v[20:23]
	v_mfma_f32_16x16x32_bf16 v[16:19], v[208:211], v[184:187], v[16:19]
	v_mfma_f32_16x16x32_bf16 v[4:7], v[200:203], v[192:195], v[4:7]
	v_mfma_f32_16x16x32_bf16 v[0:3], v[208:211], v[192:195], v[0:3]
	v_mfma_f32_16x16x32_bf16 v[52:55], v[204:207], v[172:175], v[52:55]
	v_mfma_f32_16x16x32_bf16 v[48:51], v[212:215], v[172:175], v[48:51]
	v_mfma_f32_16x16x32_bf16 v[36:39], v[204:207], v[180:183], v[36:39]
	v_mfma_f32_16x16x32_bf16 v[32:35], v[212:215], v[180:183], v[32:35]
	v_mfma_f32_16x16x32_bf16 v[20:23], v[204:207], v[188:191], v[20:23]
	v_mfma_f32_16x16x32_bf16 v[16:19], v[212:215], v[188:191], v[16:19]
	v_mfma_f32_16x16x32_bf16 v[4:7], v[204:207], v[196:199], v[4:7]
	v_mfma_f32_16x16x32_bf16 v[0:3], v[212:215], v[196:199], v[0:3]
	s_add_i32 s64, s64, 2
	s_add_u32 s60, s60, 0x100
	s_addc_u32 s61, s61, 0
	s_add_u32 s36, s36, 0x100
	s_addc_u32 s37, s37, 0
	s_cmp_gt_u32 s64, 29
	s_barrier
	s_cbranch_scc0 .LBB0_986
	v_mul_f32_e32 v152, 0xbfb8aa3b, v124
	v_exp_f32_e32 v153, v152
	v_mul_f32_e32 v152, 0xbfb8aa3b, v120
	v_exp_f32_e32 v154, v152
	v_lshl_or_b32 v152, s53, 7, v147
	v_add_f32_e32 v153, 1.0, v153
	v_rcp_f32_e32 v155, v153
	v_add_f32_e32 v153, 1.0, v154
	v_rcp_f32_e32 v154, v153
	v_lshl_add_u32 v151, s18, 8, v129
	v_mul_f32_e32 v124, v124, v155
	v_mul_f32_e32 v116, v124, v116
	v_mul_f32_e32 v124, 0xbfb8aa3b, v125
	v_mul_f32_e32 v120, v120, v154
	v_exp_f32_e32 v124, v124
	v_mul_f32_e32 v154, 0xbfb8aa3b, v121
	v_exp_f32_e32 v154, v154
	v_mul_f32_e32 v112, v120, v112
	v_add_f32_e32 v120, 1.0, v124
	v_rcp_f32_e32 v120, v120
	v_add_f32_e32 v124, 1.0, v154
	v_mul_f32_e32 v154, 0xbfb8aa3b, v126
	v_rcp_f32_e32 v124, v124
	v_exp_f32_e32 v154, v154
	v_mul_f32_e32 v120, v125, v120
	v_mul_f32_e32 v117, v120, v117
	v_mul_f32_e32 v120, v121, v124
	v_add_f32_e32 v121, 1.0, v154
	v_rcp_f32_e32 v121, v121
	v_mul_f32_e32 v124, 0xbfb8aa3b, v122
	v_exp_f32_e32 v124, v124
	v_mul_f32_e32 v113, v120, v113
	v_mul_f32_e32 v120, v126, v121
	v_mul_f32_e32 v121, 0xbfb8aa3b, v127
	v_mul_f32_e32 v118, v120, v118
	v_add_f32_e32 v120, 1.0, v124
	v_exp_f32_e32 v121, v121
	v_mul_f32_e32 v124, 0xbfb8aa3b, v123
	v_rcp_f32_e32 v120, v120
	v_exp_f32_e32 v124, v124
	v_add_f32_e32 v121, 1.0, v121
	v_rcp_f32_e32 v121, v121
	v_mul_f32_e32 v120, v122, v120
	v_add_f32_e32 v122, 1.0, v124
	v_rcp_f32_e32 v122, v122
	v_mul_f32_e32 v114, v120, v114
	v_mul_f32_e32 v120, v127, v121
	v_mul_f32_e32 v119, v120, v119
	v_mul_f32_e32 v120, v123, v122
	v_mul_f32_e32 v122, 0xbfb8aa3b, v108
	v_exp_f32_e32 v122, v122
	v_mul_f32_e32 v123, 0xbfb8aa3b, v104
	v_exp_f32_e32 v123, v123
	v_ashrrev_i32_e32 v153, 31, v152
	v_add_f32_e32 v122, 1.0, v122
	v_rcp_f32_e32 v122, v122
	v_mul_f32_e32 v115, v120, v115
	s_nop 1
	v_cvt_pk_bf16_f32 v116, v116, v117
	s_nop 1
	v_cvt_pk_bf16_f32 v117, v118, v119
	s_nop 1
	v_cvt_pk_bf16_f32 v118, v112, v113
	v_mov_b64_e32 v[112:113], s[48:49]
	s_nop 1
	v_cvt_pk_bf16_f32 v119, v114, v115
	v_mad_i64_i32 v[120:121], s[0:1], v151, s47, v[112:113]
	v_lshlrev_b64 v[114:115], 1, v[152:153]
	v_add_f32_e32 v123, 1.0, v123
	v_mul_f32_e32 v108, v108, v122
	v_lshl_add_u64 v[120:121], v[120:121], 0, v[114:115]
	v_rcp_f32_e32 v123, v123
	v_mul_f32_e32 v100, v108, v100
	v_mul_f32_e32 v108, 0xbfb8aa3b, v109
	global_store_dwordx4 v[120:121], v[116:119], off
	v_exp_f32_e32 v108, v108
	v_mul_f32_e32 v104, v104, v123
	v_mul_f32_e32 v116, 0xbfb8aa3b, v105
	v_exp_f32_e32 v116, v116
	v_mul_f32_e32 v104, v104, v96
	v_add_f32_e32 v96, 1.0, v108
	v_rcp_f32_e32 v96, v96
	v_add_f32_e32 v108, 1.0, v116
	v_mul_f32_e32 v116, 0xbfb8aa3b, v110
	v_rcp_f32_e32 v108, v108
	v_exp_f32_e32 v116, v116
	v_mul_f32_e32 v96, v109, v96
	v_mul_f32_e32 v96, v96, v101
	v_mul_f32_e32 v101, v105, v108
	v_add_f32_e32 v105, 1.0, v116
	v_rcp_f32_e32 v105, v105
	v_mul_f32_e32 v108, 0xbfb8aa3b, v106
	v_exp_f32_e32 v108, v108
	v_mul_f32_e32 v101, v101, v97
	v_mul_f32_e32 v97, v110, v105
	v_mul_f32_e32 v105, 0xbfb8aa3b, v111
	v_mul_f32_e32 v97, v97, v102
	v_add_f32_e32 v102, 1.0, v108
	v_exp_f32_e32 v105, v105
	v_mul_f32_e32 v108, 0xbfb8aa3b, v107
	v_rcp_f32_e32 v102, v102
	v_exp_f32_e32 v108, v108
	v_add_f32_e32 v105, 1.0, v105
	v_rcp_f32_e32 v105, v105
	v_mul_f32_e32 v102, v106, v102
	v_add_f32_e32 v106, 1.0, v108
	v_rcp_f32_e32 v106, v106
	v_mul_f32_e32 v102, v102, v98
	v_mul_f32_e32 v98, v111, v105
	v_mul_f32_e32 v98, v98, v103
	v_mul_f32_e32 v103, v107, v106
	v_mul_f32_e32 v99, v103, v99
	s_nop 1
	v_cvt_pk_bf16_f32 v96, v100, v96
	s_nop 1
	v_cvt_pk_bf16_f32 v97, v97, v98
	s_nop 1
	v_cvt_pk_bf16_f32 v98, v104, v101
	s_nop 1
	v_cvt_pk_bf16_f32 v99, v102, v99
	v_mul_f32_e32 v102, 0xbfb8aa3b, v92
	v_exp_f32_e32 v102, v102
	v_mul_f32_e32 v103, 0xbfb8aa3b, v88
	v_exp_f32_e32 v103, v103
	v_or_b32_e32 v100, 16, v151
	v_add_f32_e32 v102, 1.0, v102
	v_rcp_f32_e32 v102, v102
	v_mad_i64_i32 v[100:101], s[0:1], v100, s47, v[112:113]
	v_add_f32_e32 v103, 1.0, v103
	v_mul_f32_e32 v92, v92, v102
	v_lshl_add_u64 v[100:101], v[100:101], 0, v[114:115]
	v_rcp_f32_e32 v103, v103
	v_mul_f32_e32 v84, v92, v84
	v_mul_f32_e32 v92, 0xbfb8aa3b, v93
	global_store_dwordx4 v[100:101], v[96:99], off
	v_exp_f32_e32 v92, v92
	v_mul_f32_e32 v88, v88, v103
	v_mul_f32_e32 v96, 0xbfb8aa3b, v89
	v_exp_f32_e32 v96, v96
	v_mul_f32_e32 v88, v88, v80
	v_add_f32_e32 v80, 1.0, v92
	v_rcp_f32_e32 v80, v80
	v_add_f32_e32 v92, 1.0, v96
	v_mul_f32_e32 v96, 0xbfb8aa3b, v94
	v_rcp_f32_e32 v92, v92
	v_exp_f32_e32 v96, v96
	v_mul_f32_e32 v80, v93, v80
	v_mul_f32_e32 v80, v80, v85
	v_mul_f32_e32 v85, v89, v92
	v_add_f32_e32 v89, 1.0, v96
	v_rcp_f32_e32 v89, v89
	v_mul_f32_e32 v92, 0xbfb8aa3b, v90
	v_exp_f32_e32 v92, v92
	v_mul_f32_e32 v85, v85, v81
	v_mul_f32_e32 v81, v94, v89
	v_mul_f32_e32 v89, 0xbfb8aa3b, v95
	v_mul_f32_e32 v81, v81, v86
	v_add_f32_e32 v86, 1.0, v92
	v_exp_f32_e32 v89, v89
	v_mul_f32_e32 v92, 0xbfb8aa3b, v91
	v_rcp_f32_e32 v86, v86
	v_exp_f32_e32 v92, v92
	v_add_f32_e32 v89, 1.0, v89
	v_rcp_f32_e32 v89, v89
	v_mul_f32_e32 v86, v90, v86
	v_add_f32_e32 v90, 1.0, v92
	v_rcp_f32_e32 v90, v90
	v_mul_f32_e32 v86, v86, v82
	v_mul_f32_e32 v82, v95, v89
	v_mul_f32_e32 v82, v82, v87
	v_mul_f32_e32 v87, v91, v90
	v_mul_f32_e32 v83, v87, v83
	s_nop 1
	v_cvt_pk_bf16_f32 v80, v84, v80
	s_nop 1
	v_cvt_pk_bf16_f32 v81, v81, v82
	s_nop 1
	v_cvt_pk_bf16_f32 v82, v88, v85
	s_nop 1
	v_cvt_pk_bf16_f32 v83, v86, v83
	v_mul_f32_e32 v86, 0xbfb8aa3b, v76
	v_exp_f32_e32 v86, v86
	v_mul_f32_e32 v87, 0xbfb8aa3b, v72
	v_exp_f32_e32 v87, v87
	v_or_b32_e32 v84, 32, v151
	v_add_f32_e32 v86, 1.0, v86
	v_rcp_f32_e32 v86, v86
	v_mad_i64_i32 v[84:85], s[0:1], v84, s47, v[112:113]
	v_add_f32_e32 v87, 1.0, v87
	v_mul_f32_e32 v76, v76, v86
	v_lshl_add_u64 v[84:85], v[84:85], 0, v[114:115]
	v_rcp_f32_e32 v87, v87
	v_mul_f32_e32 v68, v76, v68
	v_mul_f32_e32 v76, 0xbfb8aa3b, v77
	global_store_dwordx4 v[84:85], v[80:83], off
	v_exp_f32_e32 v76, v76
	v_mul_f32_e32 v72, v72, v87
	v_mul_f32_e32 v80, 0xbfb8aa3b, v73
	v_exp_f32_e32 v80, v80
	v_mul_f32_e32 v72, v72, v64
	v_add_f32_e32 v64, 1.0, v76
	v_rcp_f32_e32 v64, v64
	v_add_f32_e32 v76, 1.0, v80
	v_mul_f32_e32 v80, 0xbfb8aa3b, v78
	v_rcp_f32_e32 v76, v76
	v_exp_f32_e32 v80, v80
	v_mul_f32_e32 v64, v77, v64
	v_mul_f32_e32 v64, v64, v69
	v_mul_f32_e32 v69, v73, v76
	v_add_f32_e32 v73, 1.0, v80
	v_rcp_f32_e32 v73, v73
	v_mul_f32_e32 v76, 0xbfb8aa3b, v74
	v_exp_f32_e32 v76, v76
	v_mul_f32_e32 v69, v69, v65
	v_mul_f32_e32 v65, v78, v73
	v_mul_f32_e32 v73, 0xbfb8aa3b, v79
	v_mul_f32_e32 v65, v65, v70
	v_add_f32_e32 v70, 1.0, v76
	v_exp_f32_e32 v73, v73
	v_mul_f32_e32 v76, 0xbfb8aa3b, v75
	v_rcp_f32_e32 v70, v70
	v_exp_f32_e32 v76, v76
	v_add_f32_e32 v73, 1.0, v73
	v_rcp_f32_e32 v73, v73
	v_mul_f32_e32 v70, v74, v70
	v_add_f32_e32 v74, 1.0, v76
	v_rcp_f32_e32 v74, v74
	v_mul_f32_e32 v70, v70, v66
	v_mul_f32_e32 v66, v79, v73
	v_mul_f32_e32 v66, v66, v71
	v_mul_f32_e32 v71, v75, v74
	v_mul_f32_e32 v67, v71, v67
	s_nop 1
	v_cvt_pk_bf16_f32 v64, v68, v64
	s_nop 1
	v_cvt_pk_bf16_f32 v65, v65, v66
	s_nop 1
	v_cvt_pk_bf16_f32 v66, v72, v69
	s_nop 1
	v_cvt_pk_bf16_f32 v67, v70, v67
	v_mul_f32_e32 v70, 0xbfb8aa3b, v60
	v_exp_f32_e32 v70, v70
	v_or_b32_e32 v68, 48, v151
	v_mad_i64_i32 v[68:69], s[0:1], v68, s47, v[112:113]
	v_lshl_add_u64 v[68:69], v[68:69], 0, v[114:115]
	v_mul_f32_e32 v71, 0xbfb8aa3b, v56
	global_store_dwordx4 v[68:69], v[64:67], off
	v_exp_f32_e32 v71, v71
	s_and_b64 vcc, exec, s[6:7]
	v_add_f32_e32 v64, 1.0, v70
	v_rcp_f32_e32 v64, v64
	v_add_f32_e32 v65, 1.0, v71
	v_rcp_f32_e32 v65, v65
	v_add_u32_e32 v66, 0x80, v151
	v_mul_f32_e32 v60, v60, v64
	v_mul_f32_e32 v52, v60, v52
	v_mul_f32_e32 v60, 0xbfb8aa3b, v61
	v_exp_f32_e32 v60, v60
	v_mul_f32_e32 v64, 0xbfb8aa3b, v57
	v_exp_f32_e32 v64, v64
	v_mul_f32_e32 v56, v56, v65
	v_mul_f32_e32 v56, v56, v48
	v_add_f32_e32 v48, 1.0, v60
	v_rcp_f32_e32 v48, v48
	v_add_f32_e32 v60, 1.0, v64
	v_mul_f32_e32 v64, 0xbfb8aa3b, v62
	v_rcp_f32_e32 v60, v60
	v_exp_f32_e32 v64, v64
	v_mul_f32_e32 v48, v61, v48
	v_mul_f32_e32 v48, v48, v53
	v_mul_f32_e32 v53, v57, v60
	v_add_f32_e32 v57, 1.0, v64
	v_rcp_f32_e32 v57, v57
	v_mul_f32_e32 v60, 0xbfb8aa3b, v58
	v_exp_f32_e32 v60, v60
	v_mul_f32_e32 v53, v53, v49
	v_mul_f32_e32 v49, v62, v57
	v_mul_f32_e32 v57, 0xbfb8aa3b, v63
	v_mul_f32_e32 v49, v49, v54
	v_add_f32_e32 v54, 1.0, v60
	v_exp_f32_e32 v57, v57
	v_mul_f32_e32 v60, 0xbfb8aa3b, v59
	v_rcp_f32_e32 v54, v54
	v_exp_f32_e32 v60, v60
	v_add_f32_e32 v57, 1.0, v57
	v_rcp_f32_e32 v57, v57
	v_mul_f32_e32 v54, v58, v54
	v_add_f32_e32 v58, 1.0, v60
	v_rcp_f32_e32 v58, v58
	v_mul_f32_e32 v54, v54, v50
	v_mul_f32_e32 v50, v63, v57
	v_mul_f32_e32 v50, v50, v55
	v_mul_f32_e32 v55, v59, v58
	v_mul_f32_e32 v51, v55, v51
	s_nop 1
	v_cvt_pk_bf16_f32 v48, v52, v48
	s_nop 1
	v_cvt_pk_bf16_f32 v49, v49, v50
	s_nop 1
	v_cvt_pk_bf16_f32 v50, v56, v53
	s_nop 1
	v_cvt_pk_bf16_f32 v51, v54, v51
	v_mul_f32_e32 v54, 0xbfb8aa3b, v44
	v_exp_f32_e32 v54, v54
	v_mul_f32_e32 v55, 0xbfb8aa3b, v40
	v_exp_f32_e32 v55, v55
	v_mad_i64_i32 v[52:53], s[0:1], v66, s47, v[112:113]
	v_add_f32_e32 v54, 1.0, v54
	v_rcp_f32_e32 v54, v54
	v_add_f32_e32 v55, 1.0, v55
	v_lshl_add_u64 v[52:53], v[52:53], 0, v[114:115]
	v_rcp_f32_e32 v55, v55
	v_mul_f32_e32 v44, v44, v54
	v_mul_f32_e32 v36, v44, v36
	v_mul_f32_e32 v44, 0xbfb8aa3b, v45
	global_store_dwordx4 v[52:53], v[48:51], off
	v_exp_f32_e32 v44, v44
	v_mul_f32_e32 v40, v40, v55
	v_mul_f32_e32 v48, 0xbfb8aa3b, v41
	v_exp_f32_e32 v48, v48
	v_mul_f32_e32 v40, v40, v32
	v_add_f32_e32 v32, 1.0, v44
	v_rcp_f32_e32 v32, v32
	v_add_f32_e32 v44, 1.0, v48
	v_mul_f32_e32 v48, 0xbfb8aa3b, v46
	v_rcp_f32_e32 v44, v44
	v_exp_f32_e32 v48, v48
	v_mul_f32_e32 v32, v45, v32
	v_mul_f32_e32 v32, v32, v37
	v_mul_f32_e32 v37, v41, v44
	v_add_f32_e32 v41, 1.0, v48
	v_rcp_f32_e32 v41, v41
	v_mul_f32_e32 v44, 0xbfb8aa3b, v42
	v_exp_f32_e32 v44, v44
	v_mul_f32_e32 v37, v37, v33
	v_mul_f32_e32 v33, v46, v41
	v_mul_f32_e32 v41, 0xbfb8aa3b, v47
	v_mul_f32_e32 v33, v33, v38
	v_add_f32_e32 v38, 1.0, v44
	v_exp_f32_e32 v41, v41
	v_mul_f32_e32 v44, 0xbfb8aa3b, v43
	v_rcp_f32_e32 v38, v38
	v_exp_f32_e32 v44, v44
	v_add_f32_e32 v41, 1.0, v41
	v_rcp_f32_e32 v41, v41
	v_mul_f32_e32 v38, v42, v38
	v_add_f32_e32 v42, 1.0, v44
	v_rcp_f32_e32 v42, v42
	v_mul_f32_e32 v38, v38, v34
	v_mul_f32_e32 v34, v47, v41
	v_mul_f32_e32 v34, v34, v39
	v_mul_f32_e32 v39, v43, v42
	v_mul_f32_e32 v35, v39, v35
	s_nop 1
	v_cvt_pk_bf16_f32 v32, v36, v32
	s_nop 1
	v_cvt_pk_bf16_f32 v33, v33, v34
	s_nop 1
	v_cvt_pk_bf16_f32 v34, v40, v37
	s_nop 1
	v_cvt_pk_bf16_f32 v35, v38, v35
	v_mul_f32_e32 v38, 0xbfb8aa3b, v28
	v_exp_f32_e32 v38, v38
	v_mul_f32_e32 v39, 0xbfb8aa3b, v24
	v_exp_f32_e32 v39, v39
	v_add_u32_e32 v36, 0x90, v151
	v_add_f32_e32 v38, 1.0, v38
	v_rcp_f32_e32 v38, v38
	v_mad_i64_i32 v[36:37], s[0:1], v36, s47, v[112:113]
	v_add_f32_e32 v39, 1.0, v39
	v_mul_f32_e32 v28, v28, v38
	v_lshl_add_u64 v[36:37], v[36:37], 0, v[114:115]
	v_rcp_f32_e32 v39, v39
	v_mul_f32_e32 v20, v28, v20
	v_mul_f32_e32 v28, 0xbfb8aa3b, v29
	global_store_dwordx4 v[36:37], v[32:35], off
	v_exp_f32_e32 v28, v28
	v_mul_f32_e32 v24, v24, v39
	v_mul_f32_e32 v32, 0xbfb8aa3b, v25
	v_exp_f32_e32 v32, v32
	v_mul_f32_e32 v24, v24, v16
	v_add_f32_e32 v16, 1.0, v28
	v_rcp_f32_e32 v16, v16
	v_add_f32_e32 v28, 1.0, v32
	v_mul_f32_e32 v32, 0xbfb8aa3b, v30
	v_rcp_f32_e32 v28, v28
	v_exp_f32_e32 v32, v32
	v_mul_f32_e32 v16, v29, v16
	v_mul_f32_e32 v16, v16, v21
	v_mul_f32_e32 v21, v25, v28
	v_add_f32_e32 v25, 1.0, v32
	v_rcp_f32_e32 v25, v25
	v_mul_f32_e32 v28, 0xbfb8aa3b, v26
	v_exp_f32_e32 v28, v28
	v_mul_f32_e32 v21, v21, v17
	v_mul_f32_e32 v17, v30, v25
	v_mul_f32_e32 v25, 0xbfb8aa3b, v31
	v_mul_f32_e32 v17, v17, v22
	v_add_f32_e32 v22, 1.0, v28
	v_exp_f32_e32 v25, v25
	v_mul_f32_e32 v28, 0xbfb8aa3b, v27
	v_rcp_f32_e32 v22, v22
	v_exp_f32_e32 v28, v28
	v_add_f32_e32 v25, 1.0, v25
	v_rcp_f32_e32 v25, v25
	v_mul_f32_e32 v22, v26, v22
	v_add_f32_e32 v26, 1.0, v28
	v_rcp_f32_e32 v26, v26
	v_mul_f32_e32 v22, v22, v18
	v_mul_f32_e32 v18, v31, v25
	v_mul_f32_e32 v18, v18, v23
	v_mul_f32_e32 v23, v27, v26
	v_mul_f32_e32 v19, v23, v19
	s_nop 1
	v_cvt_pk_bf16_f32 v16, v20, v16
	s_nop 1
	v_cvt_pk_bf16_f32 v17, v17, v18
	s_nop 1
	v_cvt_pk_bf16_f32 v18, v24, v21
	s_nop 1
	v_cvt_pk_bf16_f32 v19, v22, v19
	v_mul_f32_e32 v22, 0xbfb8aa3b, v12
	v_exp_f32_e32 v22, v22
	v_mul_f32_e32 v23, 0xbfb8aa3b, v8
	v_exp_f32_e32 v23, v23
	v_add_u32_e32 v20, 0xa0, v151
	v_add_f32_e32 v22, 1.0, v22
	v_rcp_f32_e32 v22, v22
	v_mad_i64_i32 v[20:21], s[0:1], v20, s47, v[112:113]
	v_add_f32_e32 v23, 1.0, v23
	v_mul_f32_e32 v12, v12, v22
	v_lshl_add_u64 v[20:21], v[20:21], 0, v[114:115]
	v_rcp_f32_e32 v23, v23
	v_mul_f32_e32 v4, v12, v4
	v_mul_f32_e32 v12, 0xbfb8aa3b, v13
	global_store_dwordx4 v[20:21], v[16:19], off
	v_exp_f32_e32 v12, v12
	v_mul_f32_e32 v8, v8, v23
	v_mul_f32_e32 v16, 0xbfb8aa3b, v9
	v_exp_f32_e32 v16, v16
	v_mul_f32_e32 v8, v8, v0
	v_add_f32_e32 v0, 1.0, v12
	v_rcp_f32_e32 v0, v0
	v_add_f32_e32 v12, 1.0, v16
	v_mul_f32_e32 v16, 0xbfb8aa3b, v14
	v_rcp_f32_e32 v12, v12
	v_exp_f32_e32 v16, v16
	v_mul_f32_e32 v0, v13, v0
	v_mul_f32_e32 v0, v0, v5
	v_mul_f32_e32 v5, v9, v12
	v_add_f32_e32 v9, 1.0, v16
	v_rcp_f32_e32 v9, v9
	v_mul_f32_e32 v12, 0xbfb8aa3b, v10
	v_exp_f32_e32 v12, v12
	v_mul_f32_e32 v5, v5, v1
	v_mul_f32_e32 v1, v14, v9
	v_mul_f32_e32 v9, 0xbfb8aa3b, v15
	v_exp_f32_e32 v9, v9
	v_mul_f32_e32 v1, v1, v6
	v_add_f32_e32 v6, 1.0, v12
	v_mul_f32_e32 v12, 0xbfb8aa3b, v11
	v_rcp_f32_e32 v6, v6
	v_exp_f32_e32 v12, v12
	v_add_f32_e32 v9, 1.0, v9
	v_rcp_f32_e32 v9, v9
	v_mul_f32_e32 v6, v10, v6
	v_add_f32_e32 v10, 1.0, v12
	v_rcp_f32_e32 v10, v10
	v_mul_f32_e32 v6, v6, v2
	v_mul_f32_e32 v2, v15, v9
	v_mul_f32_e32 v2, v2, v7
	s_nop 1
	v_cvt_pk_bf16_f32 v0, v4, v0
	v_add_u32_e32 v4, 0xb0, v151
	v_mul_f32_e32 v7, v11, v10
	s_nop 1
	v_cvt_pk_bf16_f32 v1, v1, v2
	s_nop 1
	v_cvt_pk_bf16_f32 v2, v8, v5
	v_mad_i64_i32 v[4:5], s[0:1], v4, s47, v[112:113]
	v_mul_f32_e32 v3, v7, v3
	v_lshl_add_u64 v[4:5], v[4:5], 0, v[114:115]
	s_mov_b32 s53, s10
	s_mov_b32 s18, s12
	s_mov_b64 s[50:51], s[16:17]
	s_mov_b64 s[36:37], s[14:15]
	s_nop 1
	v_cvt_pk_bf16_f32 v3, v6, v3
	global_store_dwordx4 v[4:5], v[0:3], off
	s_cbranch_vccz .LBB0_983
	s_waitcnt vmcnt(0)
	s_cmpk_gt_u32 s20, 0xff
	s_cbranch_scc1 .LBB0_990
	s_barrier

.LBB0_1098:
	ds_read_b128 v[128:131], v221
	ds_read_b128 v[132:135], v221 offset:1024
	ds_read_b128 v[136:139], v221 offset:2048
	ds_read_b128 v[140:143], v221 offset:3072
	s_add_u32 s64, s62, 0x100
	s_addc_u32 s65, s63, 0
	s_cmpk_eq_i32 s76, 0x54
	s_cselect_b32 s5, s9, s65
	s_cselect_b32 s4, s8, s64
	s_cselect_b32 s67, s11, s1
	s_cselect_b32 s66, s10, s0
	s_add_i32 m0, s25, 0xc000
	ds_read_b128 v[144:147], v222
	ds_read_b128 v[148:151], v222 offset:1024
	ds_read_b128 v[152:155], v222 offset:2048
	ds_read_b128 v[156:159], v222 offset:3072
	ds_read_b128 v[160:163], v222 offset:4096
	ds_read_b128 v[176:179], v222 offset:5120
	ds_read_b128 v[180:183], v222 offset:6144
	ds_read_b128 v[184:187], v222 offset:7168
	global_load_lds_dwordx4 v168, s[62:63]
	s_add_i32 m0, s25, 0xe000
	s_nop 0
	global_load_lds_dwordx4 v170, s[62:63]
	s_waitcnt lgkmcnt(8)
	s_barrier
	s_waitcnt lgkmcnt(0)
	s_waitcnt lgkmcnt(0)
	v_mfma_f32_16x16x32_bf16 v[124:127], v[128:131], v[144:147], v[124:127]
	v_mfma_f32_16x16x32_bf16 v[100:103], v[136:139], v[144:147], v[100:103]
	v_mfma_f32_16x16x32_bf16 v[120:123], v[128:131], v[152:155], v[120:123]
	v_mfma_f32_16x16x32_bf16 v[96:99], v[136:139], v[152:155], v[96:99]
	v_mfma_f32_16x16x32_bf16 v[116:119], v[128:131], v[160:163], v[116:119]
	v_mfma_f32_16x16x32_bf16 v[92:95], v[136:139], v[160:163], v[92:95]
	v_mfma_f32_16x16x32_bf16 v[112:115], v[128:131], v[180:183], v[112:115]
	v_mfma_f32_16x16x32_bf16 v[84:87], v[136:139], v[180:183], v[84:87]
	v_mfma_f32_16x16x32_bf16 v[124:127], v[132:135], v[148:151], v[124:127]
	v_mfma_f32_16x16x32_bf16 v[100:103], v[140:143], v[148:151], v[100:103]
	v_mfma_f32_16x16x32_bf16 v[120:123], v[132:135], v[156:159], v[120:123]
	v_mfma_f32_16x16x32_bf16 v[96:99], v[140:143], v[156:159], v[96:99]
	v_mfma_f32_16x16x32_bf16 v[116:119], v[132:135], v[176:179], v[116:119]
	v_mfma_f32_16x16x32_bf16 v[92:95], v[140:143], v[176:179], v[92:95]
	v_mfma_f32_16x16x32_bf16 v[112:115], v[132:135], v[184:187], v[112:115]
	v_mfma_f32_16x16x32_bf16 v[84:87], v[140:143], v[184:187], v[84:87]
	s_barrier
	s_add_i32 s42, s41, s24
	s_add_u32 s98, s66, s18
	s_addc_u32 s99, s67, s19
	s_mov_b32 m0, s42
	ds_read_b128 v[188:191], v223
	ds_read_b128 v[192:195], v223 offset:1024
	ds_read_b128 v[196:199], v223 offset:2048
	ds_read_b128 v[200:203], v223 offset:3072
	global_load_lds_dwordx4 v166, s[66:67]
	s_add_i32 m0, s42, 0x2000
	s_nop 0
	global_load_lds_dwordx4 v164, s[66:67]
	s_barrier
	s_waitcnt lgkmcnt(0)
	s_waitcnt lgkmcnt(0)
	v_mfma_f32_16x16x32_bf16 v[72:75], v[188:191], v[144:147], v[72:75]
	v_mfma_f32_16x16x32_bf16 v[44:47], v[196:199], v[144:147], v[44:47]
	v_mfma_f32_16x16x32_bf16 v[64:67], v[188:191], v[152:155], v[64:67]
	v_mfma_f32_16x16x32_bf16 v[40:43], v[196:199], v[152:155], v[40:43]
	v_mfma_f32_16x16x32_bf16 v[56:59], v[188:191], v[160:163], v[56:59]
	v_mfma_f32_16x16x32_bf16 v[36:39], v[196:199], v[160:163], v[36:39]
	v_mfma_f32_16x16x32_bf16 v[48:51], v[188:191], v[180:183], v[48:51]
	v_mfma_f32_16x16x32_bf16 v[28:31], v[196:199], v[180:183], v[28:31]
	v_mfma_f32_16x16x32_bf16 v[72:75], v[192:195], v[148:151], v[72:75]
	v_mfma_f32_16x16x32_bf16 v[44:47], v[200:203], v[148:151], v[44:47]
	v_mfma_f32_16x16x32_bf16 v[64:67], v[192:195], v[156:159], v[64:67]
	v_mfma_f32_16x16x32_bf16 v[40:43], v[200:203], v[156:159], v[40:43]
	v_mfma_f32_16x16x32_bf16 v[56:59], v[192:195], v[176:179], v[56:59]
	v_mfma_f32_16x16x32_bf16 v[36:39], v[200:203], v[176:179], v[36:39]
	v_mfma_f32_16x16x32_bf16 v[48:51], v[192:195], v[184:187], v[48:51]
	v_mfma_f32_16x16x32_bf16 v[28:31], v[200:203], v[184:187], v[28:31]
	s_mov_b32 m0, s25
	s_add_u32 s100, s4, s18
	s_addc_u32 s101, s5, s19
	s_barrier
	ds_read_b128 v[144:147], v222 offset:16384
	ds_read_b128 v[148:151], v222 offset:17408
	ds_read_b128 v[152:155], v222 offset:18432
	ds_read_b128 v[156:159], v222 offset:19456
	ds_read_b128 v[160:163], v222 offset:20480
	ds_read_b128 v[176:179], v222 offset:21504
	ds_read_b128 v[180:183], v222 offset:22528
	ds_read_b128 v[184:187], v222 offset:23552
	global_load_lds_dwordx4 v166, s[4:5]
	s_mov_b32 m0, s28
	s_nop 0
	global_load_lds_dwordx4 v164, s[4:5]
	s_barrier
	s_waitcnt lgkmcnt(0)
	s_waitcnt lgkmcnt(0)
	v_mfma_f32_16x16x32_bf16 v[108:111], v[128:131], v[144:147], v[108:111]
	v_mfma_f32_16x16x32_bf16 v[76:79], v[136:139], v[144:147], v[76:79]
	v_mfma_f32_16x16x32_bf16 v[104:107], v[128:131], v[152:155], v[104:107]
	v_mfma_f32_16x16x32_bf16 v[68:71], v[136:139], v[152:155], v[68:71]
	v_mfma_f32_16x16x32_bf16 v[88:91], v[128:131], v[160:163], v[88:91]
	v_mfma_f32_16x16x32_bf16 v[60:63], v[136:139], v[160:163], v[60:63]
	v_mfma_f32_16x16x32_bf16 v[80:83], v[128:131], v[180:183], v[80:83]
	v_mfma_f32_16x16x32_bf16 v[52:55], v[136:139], v[180:183], v[52:55]
	v_mfma_f32_16x16x32_bf16 v[108:111], v[132:135], v[148:151], v[108:111]
	v_mfma_f32_16x16x32_bf16 v[76:79], v[140:143], v[148:151], v[76:79]
	v_mfma_f32_16x16x32_bf16 v[104:107], v[132:135], v[156:159], v[104:107]
	v_mfma_f32_16x16x32_bf16 v[68:71], v[140:143], v[156:159], v[68:71]
	v_mfma_f32_16x16x32_bf16 v[88:91], v[132:135], v[176:179], v[88:91]
	v_mfma_f32_16x16x32_bf16 v[60:63], v[140:143], v[176:179], v[60:63]
	v_mfma_f32_16x16x32_bf16 v[80:83], v[132:135], v[184:187], v[80:83]
	v_mfma_f32_16x16x32_bf16 v[52:55], v[140:143], v[184:187], v[52:55]
	s_barrier
	s_add_u32 s42, s66, 0x160000
	s_addc_u32 s43, s67, 0
	s_add_i32 s44, s53, s24
	s_mov_b32 m0, s44
	s_nop 0
	global_load_lds_dwordx4 v166, s[42:43]
	s_add_i32 m0, s44, 0x2000
	s_nop 0
	global_load_lds_dwordx4 v164, s[42:43]
	s_waitcnt vmcnt(6)
	s_barrier
	v_mfma_f32_16x16x32_bf16 v[32:35], v[188:191], v[144:147], v[32:35]
	v_mfma_f32_16x16x32_bf16 v[12:15], v[196:199], v[144:147], v[12:15]
	v_mfma_f32_16x16x32_bf16 v[24:27], v[188:191], v[152:155], v[24:27]
	v_mfma_f32_16x16x32_bf16 v[8:11], v[196:199], v[152:155], v[8:11]
	v_mfma_f32_16x16x32_bf16 v[20:23], v[188:191], v[160:163], v[20:23]
	v_mfma_f32_16x16x32_bf16 v[4:7], v[196:199], v[160:163], v[4:7]
	v_mfma_f32_16x16x32_bf16 v[16:19], v[188:191], v[180:183], v[16:19]
	v_mfma_f32_16x16x32_bf16 v[0:3], v[196:199], v[180:183], v[0:3]
	v_mfma_f32_16x16x32_bf16 v[32:35], v[192:195], v[148:151], v[32:35]
	v_mfma_f32_16x16x32_bf16 v[12:15], v[200:203], v[148:151], v[12:15]
	v_mfma_f32_16x16x32_bf16 v[24:27], v[192:195], v[156:159], v[24:27]
	v_mfma_f32_16x16x32_bf16 v[8:11], v[200:203], v[156:159], v[8:11]
	v_mfma_f32_16x16x32_bf16 v[20:23], v[192:195], v[176:179], v[20:23]
	v_mfma_f32_16x16x32_bf16 v[4:7], v[200:203], v[176:179], v[4:7]
	v_mfma_f32_16x16x32_bf16 v[16:19], v[192:195], v[184:187], v[16:19]
	v_mfma_f32_16x16x32_bf16 v[0:3], v[200:203], v[184:187], v[0:3]
	s_add_i32 s42, 0, 0x18000
	v_add_u32_e32 v140, s42, v219
	s_barrier
	ds_read_b128 v[128:131], v140
	ds_read_b128 v[132:135], v140 offset:1024
	ds_read_b128 v[136:139], v140 offset:2048
	ds_read_b128 v[140:143], v140 offset:3072
	s_add_u32 s4, s4, 0x160000
	s_addc_u32 s5, s5, 0
	s_mov_b32 m0, s29
	ds_read_b128 v[144:147], v222 offset:32768
	ds_read_b128 v[148:151], v222 offset:33792
	ds_read_b128 v[152:155], v222 offset:34816
	ds_read_b128 v[156:159], v222 offset:35840
	ds_read_b128 v[160:163], v222 offset:36864
	ds_read_b128 v[176:179], v222 offset:37888
	ds_read_b128 v[180:183], v222 offset:38912
	ds_read_b128 v[184:187], v222 offset:39936
	global_load_lds_dwordx4 v166, s[4:5]
	s_mov_b32 m0, s33
	s_nop 0
	global_load_lds_dwordx4 v164, s[4:5]
	s_waitcnt lgkmcnt(8)
	s_barrier
	s_waitcnt lgkmcnt(0)
	s_waitcnt lgkmcnt(0)
	v_mfma_f32_16x16x32_bf16 v[124:127], v[128:131], v[144:147], v[124:127]
	v_mfma_f32_16x16x32_bf16 v[100:103], v[136:139], v[144:147], v[100:103]
	v_mfma_f32_16x16x32_bf16 v[120:123], v[128:131], v[152:155], v[120:123]
	v_mfma_f32_16x16x32_bf16 v[96:99], v[136:139], v[152:155], v[96:99]
	v_mfma_f32_16x16x32_bf16 v[116:119], v[128:131], v[160:163], v[116:119]
	v_mfma_f32_16x16x32_bf16 v[92:95], v[136:139], v[160:163], v[92:95]
	v_mfma_f32_16x16x32_bf16 v[112:115], v[128:131], v[180:183], v[112:115]
	v_mfma_f32_16x16x32_bf16 v[84:87], v[136:139], v[180:183], v[84:87]
	v_mfma_f32_16x16x32_bf16 v[124:127], v[132:135], v[148:151], v[124:127]
	v_mfma_f32_16x16x32_bf16 v[100:103], v[140:143], v[148:151], v[100:103]
	v_mfma_f32_16x16x32_bf16 v[120:123], v[132:135], v[156:159], v[120:123]
	v_mfma_f32_16x16x32_bf16 v[96:99], v[140:143], v[156:159], v[96:99]
	v_mfma_f32_16x16x32_bf16 v[116:119], v[132:135], v[176:179], v[116:119]
	v_mfma_f32_16x16x32_bf16 v[92:95], v[140:143], v[176:179], v[92:95]
	v_mfma_f32_16x16x32_bf16 v[112:115], v[132:135], v[184:187], v[112:115]
	v_mfma_f32_16x16x32_bf16 v[84:87], v[140:143], v[184:187], v[84:87]
	s_barrier
	s_add_i32 s43, 0, 0x1c000
	s_add_i32 s4, s42, s24
	v_add_u32_e32 v200, s43, v219
	s_mov_b32 m0, s4
	ds_read_b128 v[188:191], v200
	ds_read_b128 v[192:195], v200 offset:1024
	ds_read_b128 v[196:199], v200 offset:2048
	ds_read_b128 v[200:203], v200 offset:3072
	global_load_lds_dwordx4 v166, s[98:99]
	s_add_i32 m0, s4, 0x2000
	s_nop 0
	global_load_lds_dwordx4 v164, s[98:99]
	s_barrier
	s_waitcnt lgkmcnt(0)
	s_waitcnt lgkmcnt(0)
	v_mfma_f32_16x16x32_bf16 v[72:75], v[188:191], v[144:147], v[72:75]
	v_mfma_f32_16x16x32_bf16 v[44:47], v[196:199], v[144:147], v[44:47]
	v_mfma_f32_16x16x32_bf16 v[64:67], v[188:191], v[152:155], v[64:67]
	v_mfma_f32_16x16x32_bf16 v[40:43], v[196:199], v[152:155], v[40:43]
	v_mfma_f32_16x16x32_bf16 v[56:59], v[188:191], v[160:163], v[56:59]
	v_mfma_f32_16x16x32_bf16 v[36:39], v[196:199], v[160:163], v[36:39]
	v_mfma_f32_16x16x32_bf16 v[48:51], v[188:191], v[180:183], v[48:51]
	v_mfma_f32_16x16x32_bf16 v[28:31], v[196:199], v[180:183], v[28:31]
	v_mfma_f32_16x16x32_bf16 v[72:75], v[192:195], v[148:151], v[72:75]
	v_mfma_f32_16x16x32_bf16 v[44:47], v[200:203], v[148:151], v[44:47]
	v_mfma_f32_16x16x32_bf16 v[64:67], v[192:195], v[156:159], v[64:67]
	v_mfma_f32_16x16x32_bf16 v[40:43], v[200:203], v[156:159], v[40:43]
	v_mfma_f32_16x16x32_bf16 v[56:59], v[192:195], v[176:179], v[56:59]
	v_mfma_f32_16x16x32_bf16 v[36:39], v[200:203], v[176:179], v[36:39]
	v_mfma_f32_16x16x32_bf16 v[48:51], v[192:195], v[184:187], v[48:51]
	v_mfma_f32_16x16x32_bf16 v[28:31], v[200:203], v[184:187], v[28:31]
	s_mov_b32 m0, s37
	s_barrier
	ds_read_b128 v[144:147], v222 offset:49152
	ds_read_b128 v[148:151], v222 offset:50176
	ds_read_b128 v[152:155], v222 offset:51200
	ds_read_b128 v[156:159], v222 offset:52224
	ds_read_b128 v[160:163], v222 offset:53248
	ds_read_b128 v[176:179], v222 offset:54272
	ds_read_b128 v[180:183], v222 offset:55296
	ds_read_b128 v[184:187], v222 offset:56320
	global_load_lds_dwordx4 v166, s[100:101]
	s_mov_b32 m0, s40
	s_nop 0
	global_load_lds_dwordx4 v164, s[100:101]
	s_barrier
	s_waitcnt lgkmcnt(0)
	s_waitcnt lgkmcnt(0)
	v_mfma_f32_16x16x32_bf16 v[108:111], v[128:131], v[144:147], v[108:111]
	v_mfma_f32_16x16x32_bf16 v[76:79], v[136:139], v[144:147], v[76:79]
	v_mfma_f32_16x16x32_bf16 v[104:107], v[128:131], v[152:155], v[104:107]
	v_mfma_f32_16x16x32_bf16 v[68:71], v[136:139], v[152:155], v[68:71]
	v_mfma_f32_16x16x32_bf16 v[88:91], v[128:131], v[160:163], v[88:91]
	v_mfma_f32_16x16x32_bf16 v[60:63], v[136:139], v[160:163], v[60:63]
	v_mfma_f32_16x16x32_bf16 v[80:83], v[128:131], v[180:183], v[80:83]
	v_mfma_f32_16x16x32_bf16 v[52:55], v[136:139], v[180:183], v[52:55]
	v_mfma_f32_16x16x32_bf16 v[108:111], v[132:135], v[148:151], v[108:111]
	v_mfma_f32_16x16x32_bf16 v[76:79], v[140:143], v[148:151], v[76:79]
	v_mfma_f32_16x16x32_bf16 v[104:107], v[132:135], v[156:159], v[104:107]
	v_mfma_f32_16x16x32_bf16 v[68:71], v[140:143], v[156:159], v[68:71]
	v_mfma_f32_16x16x32_bf16 v[88:91], v[132:135], v[176:179], v[88:91]
	v_mfma_f32_16x16x32_bf16 v[60:63], v[140:143], v[176:179], v[60:63]
	v_mfma_f32_16x16x32_bf16 v[80:83], v[132:135], v[184:187], v[80:83]
	v_mfma_f32_16x16x32_bf16 v[52:55], v[140:143], v[184:187], v[52:55]
	s_barrier
	s_add_u32 s4, s66, 0x160080
	s_addc_u32 s5, s67, 0
	s_add_i32 s42, s43, s24
	s_mov_b32 m0, s42
	s_nop 0
	global_load_lds_dwordx4 v166, s[4:5]
	s_add_i32 m0, s42, 0x2000
	s_nop 0
	global_load_lds_dwordx4 v164, s[4:5]
	s_waitcnt vmcnt(6)
	s_barrier
	v_mfma_f32_16x16x32_bf16 v[32:35], v[188:191], v[144:147], v[32:35]
	v_mfma_f32_16x16x32_bf16 v[12:15], v[196:199], v[144:147], v[12:15]
	v_mfma_f32_16x16x32_bf16 v[24:27], v[188:191], v[152:155], v[24:27]
	v_mfma_f32_16x16x32_bf16 v[8:11], v[196:199], v[152:155], v[8:11]
	v_mfma_f32_16x16x32_bf16 v[20:23], v[188:191], v[160:163], v[20:23]
	v_mfma_f32_16x16x32_bf16 v[4:7], v[196:199], v[160:163], v[4:7]
	v_mfma_f32_16x16x32_bf16 v[16:19], v[188:191], v[180:183], v[16:19]
	v_mfma_f32_16x16x32_bf16 v[0:3], v[196:199], v[180:183], v[0:3]
	v_mfma_f32_16x16x32_bf16 v[32:35], v[192:195], v[148:151], v[32:35]
	v_mfma_f32_16x16x32_bf16 v[12:15], v[200:203], v[148:151], v[12:15]
	v_mfma_f32_16x16x32_bf16 v[24:27], v[192:195], v[156:159], v[24:27]
	v_mfma_f32_16x16x32_bf16 v[8:11], v[200:203], v[156:159], v[8:11]
	v_mfma_f32_16x16x32_bf16 v[20:23], v[192:195], v[176:179], v[20:23]
	v_mfma_f32_16x16x32_bf16 v[4:7], v[200:203], v[176:179], v[4:7]
	v_mfma_f32_16x16x32_bf16 v[16:19], v[192:195], v[184:187], v[16:19]
	v_mfma_f32_16x16x32_bf16 v[0:3], v[200:203], v[184:187], v[0:3]
	s_add_i32 s76, s76, 2
	s_add_u32 s0, s0, 0x100
	s_addc_u32 s1, s1, 0
	s_cmpk_gt_u32 s76, 0x55
	s_mov_b64 s[62:63], s[64:65]
	s_barrier
	s_cbranch_scc0 .LBB0_1098
	v_lshl_add_u32 v144, s74, 8, v218
	v_lshl_or_b32 v184, s75, 8, v220
	v_ashrrev_i32_e32 v145, 31, v144
	v_ashrrev_i32_e32 v185, 31, v184
	v_lshlrev_b64 v[132:133], 13, v[144:145]
	v_lshlrev_b64 v[146:147], 2, v[184:185]
	v_lshl_add_u64 v[132:133], s[12:13], 0, v[132:133]
	v_lshl_add_u64 v[176:177], v[132:133], 0, v[146:147]
	v_or_b32_e32 v136, 16, v144
	v_add_co_u32_e32 v186, vcc, s68, v176
	v_ashrrev_i32_e32 v137, 31, v136
	v_or_b32_e32 v140, 32, v144
	v_or_b32_e32 v144, 48, v144
	v_addc_co_u32_e32 v187, vcc, 0, v177, vcc
	v_lshlrev_b64 v[136:137], 13, v[136:137]
	v_ashrrev_i32_e32 v141, 31, v140
	v_ashrrev_i32_e32 v145, 31, v144
	v_add_co_u32_e32 v190, vcc, s69, v176
	v_lshl_add_u64 v[128:129], s[16:17], 0, v[146:147]
	v_lshl_add_u64 v[136:137], s[12:13], 0, v[136:137]
	v_lshlrev_b64 v[140:141], 13, v[140:141]
	v_lshlrev_b64 v[144:145], 13, v[144:145]
	v_addc_co_u32_e32 v191, vcc, 0, v177, vcc
	global_load_dwordx4 v[128:131], v[128:129], off
	v_lshl_add_u64 v[178:179], v[136:137], 0, v[146:147]
	global_load_dwordx4 v[132:135], v[176:177], off
	global_load_dwordx4 v[136:139], v[178:179], off
	v_lshl_add_u64 v[140:141], s[12:13], 0, v[140:141]
	v_lshl_add_u64 v[144:145], s[12:13], 0, v[144:145]
	v_add_co_u32_e32 v192, vcc, s70, v176
	v_lshl_add_u64 v[180:181], v[140:141], 0, v[146:147]
	v_lshl_add_u64 v[182:183], v[144:145], 0, v[146:147]
	v_addc_co_u32_e32 v193, vcc, 0, v177, vcc
	global_load_dwordx4 v[140:143], v[180:181], off
	global_load_dwordx4 v[144:147], v[182:183], off
	global_load_dwordx4 v[148:151], v[186:187], off
	global_load_dwordx4 v[160:163], v[190:191], off
	global_load_dwordx4 v[156:159], v[192:193], off
	v_add_co_u32_e32 v188, vcc, s71, v176
	v_pk_add_f32 v[212:213], v[126:127], 0 op_sel_hi:[1,0]
	s_nop 0
	v_addc_co_u32_e32 v189, vcc, 0, v177, vcc
	global_load_dwordx4 v[152:155], v[188:189], off
	v_pk_add_f32 v[214:215], v[124:125], 0 op_sel_hi:[1,0]
	v_pk_add_f32 v[126:127], v[122:123], 0 op_sel_hi:[1,0]
	v_pk_add_f32 v[194:195], v[120:121], 0 op_sel_hi:[1,0]
	v_pk_add_f32 v[196:197], v[118:119], 0 op_sel_hi:[1,0]
	v_pk_add_f32 v[198:199], v[116:117], 0 op_sel_hi:[1,0]
	v_pk_add_f32 v[200:201], v[114:115], 0 op_sel_hi:[1,0]
	v_pk_add_f32 v[202:203], v[112:113], 0 op_sel_hi:[1,0]
	v_pk_add_f32 v[204:205], v[110:111], 0 op_sel_hi:[1,0]
	v_pk_add_f32 v[206:207], v[108:109], 0 op_sel_hi:[1,0]
	v_pk_add_f32 v[208:209], v[106:107], 0 op_sel_hi:[1,0]
	v_pk_add_f32 v[210:211], v[104:105], 0 op_sel_hi:[1,0]
	v_lshl_add_u64 v[120:121], v[176:177], 0, s[20:21]
	v_lshl_add_u64 v[122:123], v[176:177], 0, s[46:47]
	global_load_dwordx4 v[104:107], v[176:177], off offset:64
	global_load_dwordx4 v[108:111], v[178:179], off offset:64
	global_load_dwordx4 v[112:115], v[180:181], off offset:64
	global_load_dwordx4 v[116:119], v[182:183], off offset:64
	global_load_dwordx4 v[224:227], v[120:121], off offset:576
	global_load_dwordx4 v[228:231], v[122:123], off offset:576
	v_lshl_add_u64 v[124:125], v[176:177], 0, s[60:61]
	v_pk_add_f32 v[102:103], v[102:103], 0 op_sel_hi:[1,0]
	v_pk_add_f32 v[100:101], v[100:101], 0 op_sel_hi:[1,0]
	v_pk_add_f32 v[98:99], v[98:99], 0 op_sel_hi:[1,0]
	v_pk_add_f32 v[96:97], v[96:97], 0 op_sel_hi:[1,0]
	v_pk_add_f32 v[74:75], v[74:75], 0 op_sel_hi:[1,0]
	v_pk_add_f32 v[72:73], v[72:73], 0 op_sel_hi:[1,0]
	v_pk_add_f32 v[66:67], v[66:67], 0 op_sel_hi:[1,0]
	v_pk_add_f32 v[64:65], v[64:65], 0 op_sel_hi:[1,0]
	v_pk_add_f32 v[58:59], v[58:59], 0 op_sel_hi:[1,0]
	v_pk_add_f32 v[56:57], v[56:57], 0 op_sel_hi:[1,0]
	v_pk_add_f32 v[46:47], v[46:47], 0 op_sel_hi:[1,0]
	v_pk_add_f32 v[44:45], v[44:45], 0 op_sel_hi:[1,0]
	v_pk_add_f32 v[42:43], v[42:43], 0 op_sel_hi:[1,0]
	v_pk_add_f32 v[40:41], v[40:41], 0 op_sel_hi:[1,0]
	v_pk_add_f32 v[38:39], v[38:39], 0 op_sel_hi:[1,0]
	v_pk_add_f32 v[36:37], v[36:37], 0 op_sel_hi:[1,0]
	v_pk_add_f32 v[30:31], v[30:31], 0 op_sel_hi:[1,0]
	v_pk_add_f32 v[28:29], v[28:29], 0 op_sel_hi:[1,0]
	s_and_b64 vcc, exec, s[6:7]
	s_mov_b32 s75, s72
	s_mov_b32 s74, s73
	s_mov_b64 s[64:65], s[10:11]
	s_mov_b64 s[62:63], s[8:9]
	s_waitcnt vmcnt(0)
	v_pk_fma_f32 v[134:135], v[212:213], v[130:131], v[134:135]
	v_pk_fma_f32 v[132:133], v[214:215], v[128:129], v[132:133]
	global_store_dwordx4 v[176:177], v[132:135], off
	s_nop 1
	v_pk_fma_f32 v[134:135], v[126:127], v[130:131], v[138:139]
	v_pk_fma_f32 v[132:133], v[194:195], v[128:129], v[136:137]
	v_pk_add_f32 v[126:127], v[90:91], 0 op_sel_hi:[1,0]
	v_pk_fma_f32 v[138:139], v[196:197], v[130:131], v[142:143]
	v_pk_fma_f32 v[136:137], v[198:199], v[128:129], v[140:141]
	v_pk_fma_f32 v[142:143], v[200:201], v[130:131], v[146:147]
	v_pk_fma_f32 v[140:141], v[202:203], v[128:129], v[144:145]
	v_pk_fma_f32 v[146:147], v[204:205], v[130:131], v[150:151]
	v_pk_fma_f32 v[144:145], v[206:207], v[128:129], v[148:149]
	v_pk_fma_f32 v[150:151], v[208:209], v[130:131], v[162:163]
	v_pk_fma_f32 v[148:149], v[210:211], v[128:129], v[160:161]
	global_store_dwordx4 v[178:179], v[132:135], off
	global_store_dwordx4 v[180:181], v[136:139], off
	global_store_dwordx4 v[182:183], v[140:143], off
	global_store_dwordx4 v[186:187], v[144:147], off
	global_store_dwordx4 v[190:191], v[148:151], off
	v_pk_add_f32 v[132:133], v[88:89], 0 op_sel_hi:[1,0]
	v_pk_fma_f32 v[134:135], v[126:127], v[130:131], v[158:159]
	v_pk_fma_f32 v[132:133], v[132:133], v[128:129], v[156:157]
	v_pk_add_f32 v[126:127], v[82:83], 0 op_sel_hi:[1,0]
	global_store_dwordx4 v[192:193], v[132:135], off
	v_pk_fma_f32 v[130:131], v[126:127], v[130:131], v[154:155]
	v_or_b32_e32 v126, 16, v184
	v_pk_add_f32 v[132:133], v[80:81], 0 op_sel_hi:[1,0]
	v_ashrrev_i32_e32 v127, 31, v126
	v_pk_fma_f32 v[128:129], v[132:133], v[128:129], v[152:153]
	v_lshl_add_u64 v[146:147], v[176:177], 0, s[14:15]
	global_store_dwordx4 v[188:189], v[128:131], off
	v_lshl_add_u64 v[126:127], v[126:127], 2, s[16:17]
	global_load_dwordx4 v[88:91], v[124:125], off offset:576
	global_load_dwordx4 v[80:83], v[146:147], off offset:576
	s_nop 0
	global_load_dwordx4 v[126:129], v[126:127], off
	s_nop 0
	global_load_dwordx4 v[130:133], v[120:121], off offset:64
	global_load_dwordx4 v[134:137], v[122:123], off offset:64
	global_load_dwordx4 v[138:141], v[124:125], off offset:64
	global_load_dwordx4 v[142:145], v[146:147], off offset:64
	v_pk_add_f32 v[192:193], v[52:53], 0 op_sel_hi:[1,0]
	v_or_b32_e32 v52, 0x80, v184
	v_pk_add_f32 v[148:149], v[94:95], 0 op_sel_hi:[1,0]
	v_pk_add_f32 v[150:151], v[92:93], 0 op_sel_hi:[1,0]
	v_pk_add_f32 v[152:153], v[86:87], 0 op_sel_hi:[1,0]
	v_pk_add_f32 v[154:155], v[84:85], 0 op_sel_hi:[1,0]
	v_pk_add_f32 v[156:157], v[78:79], 0 op_sel_hi:[1,0]
	v_pk_add_f32 v[158:159], v[76:77], 0 op_sel_hi:[1,0]
	v_pk_add_f32 v[160:161], v[70:71], 0 op_sel_hi:[1,0]
	v_pk_add_f32 v[162:163], v[68:69], 0 op_sel_hi:[1,0]
	v_pk_add_f32 v[186:187], v[62:63], 0 op_sel_hi:[1,0]
	v_pk_add_f32 v[188:189], v[60:61], 0 op_sel_hi:[1,0]
	v_pk_add_f32 v[190:191], v[54:55], 0 op_sel_hi:[1,0]
	v_ashrrev_i32_e32 v53, 31, v52
	v_lshl_add_u64 v[194:195], v[52:53], 2, s[16:17]
	global_load_dwordx4 v[52:55], v[176:177], off offset:512
	global_load_dwordx4 v[60:63], v[120:121], off offset:512
	global_load_dwordx4 v[68:71], v[122:123], off offset:512
	global_load_dwordx4 v[76:79], v[124:125], off offset:512
	global_load_dwordx4 v[84:87], v[146:147], off offset:512
	s_waitcnt vmcnt(0)
	v_pk_fma_f32 v[94:95], v[102:103], v[128:129], v[106:107]
	v_pk_fma_f32 v[92:93], v[100:101], v[126:127], v[104:105]
	v_pk_fma_f32 v[98:99], v[98:99], v[128:129], v[110:111]
	v_pk_fma_f32 v[96:97], v[96:97], v[126:127], v[108:109]
	v_pk_fma_f32 v[102:103], v[148:149], v[128:129], v[114:115]
	v_pk_fma_f32 v[100:101], v[150:151], v[126:127], v[112:113]
	v_pk_fma_f32 v[106:107], v[152:153], v[128:129], v[118:119]
	v_pk_fma_f32 v[104:105], v[154:155], v[126:127], v[116:117]
	v_pk_fma_f32 v[110:111], v[156:157], v[128:129], v[132:133]
	v_pk_fma_f32 v[108:109], v[158:159], v[126:127], v[130:131]
	v_pk_fma_f32 v[114:115], v[160:161], v[128:129], v[136:137]
	v_pk_fma_f32 v[112:113], v[162:163], v[126:127], v[134:135]
	v_pk_fma_f32 v[118:119], v[186:187], v[128:129], v[140:141]
	v_pk_fma_f32 v[116:117], v[188:189], v[126:127], v[138:139]
	v_pk_fma_f32 v[128:129], v[190:191], v[128:129], v[144:145]
	v_pk_fma_f32 v[126:127], v[192:193], v[126:127], v[142:143]
	global_store_dwordx4 v[176:177], v[92:95], off offset:64
	global_store_dwordx4 v[178:179], v[96:99], off offset:64
	global_store_dwordx4 v[180:181], v[100:103], off offset:64
	global_store_dwordx4 v[182:183], v[104:107], off offset:64
	global_store_dwordx4 v[120:121], v[108:111], off offset:64
	global_store_dwordx4 v[122:123], v[112:115], off offset:64
	global_store_dwordx4 v[124:125], v[116:119], off offset:64
	global_store_dwordx4 v[146:147], v[126:129], off offset:64
	global_load_dwordx4 v[92:95], v[194:195], off
	global_load_dwordx4 v[96:99], v[178:179], off offset:512
	global_load_dwordx4 v[100:103], v[180:181], off offset:512
	global_load_dwordx4 v[104:107], v[182:183], off offset:512
	v_pk_add_f32 v[132:133], v[16:17], 0 op_sel_hi:[1,0]
	v_or_b32_e32 v16, 0x90, v184
	v_pk_add_f32 v[108:109], v[50:51], 0 op_sel_hi:[1,0]
	v_pk_add_f32 v[110:111], v[48:49], 0 op_sel_hi:[1,0]
	v_pk_add_f32 v[112:113], v[34:35], 0 op_sel_hi:[1,0]
	v_pk_add_f32 v[114:115], v[32:33], 0 op_sel_hi:[1,0]
	v_pk_add_f32 v[116:117], v[26:27], 0 op_sel_hi:[1,0]
	v_pk_add_f32 v[118:119], v[24:25], 0 op_sel_hi:[1,0]
	v_pk_add_f32 v[126:127], v[22:23], 0 op_sel_hi:[1,0]
	v_pk_add_f32 v[128:129], v[20:21], 0 op_sel_hi:[1,0]
	v_pk_add_f32 v[130:131], v[18:19], 0 op_sel_hi:[1,0]
	v_ashrrev_i32_e32 v17, 31, v16
	v_lshl_add_u64 v[134:135], v[16:17], 2, s[16:17]
	global_load_dwordx4 v[16:19], v[176:177], off offset:576
	global_load_dwordx4 v[20:23], v[178:179], off offset:576
	global_load_dwordx4 v[24:27], v[180:181], off offset:576
	global_load_dwordx4 v[32:35], v[182:183], off offset:576
	s_waitcnt vmcnt(0)
	v_pk_fma_f32 v[50:51], v[74:75], v[94:95], v[54:55]
	v_pk_fma_f32 v[48:49], v[72:73], v[92:93], v[52:53]
	v_pk_fma_f32 v[54:55], v[66:67], v[94:95], v[98:99]
	v_pk_fma_f32 v[52:53], v[64:65], v[92:93], v[96:97]
	v_pk_fma_f32 v[58:59], v[58:59], v[94:95], v[102:103]
	v_pk_fma_f32 v[56:57], v[56:57], v[92:93], v[100:101]
	v_pk_fma_f32 v[66:67], v[108:109], v[94:95], v[106:107]
	v_pk_fma_f32 v[64:65], v[110:111], v[92:93], v[104:105]
	v_pk_fma_f32 v[62:63], v[112:113], v[94:95], v[62:63]
	v_pk_fma_f32 v[60:61], v[114:115], v[92:93], v[60:61]
	v_pk_fma_f32 v[70:71], v[116:117], v[94:95], v[70:71]
	v_pk_fma_f32 v[68:69], v[118:119], v[92:93], v[68:69]
	v_pk_fma_f32 v[74:75], v[126:127], v[94:95], v[78:79]
	v_pk_fma_f32 v[72:73], v[128:129], v[92:93], v[76:77]
	v_pk_fma_f32 v[78:79], v[130:131], v[94:95], v[86:87]
	v_pk_fma_f32 v[76:77], v[132:133], v[92:93], v[84:85]
	global_store_dwordx4 v[176:177], v[48:51], off offset:512
	global_store_dwordx4 v[178:179], v[52:55], off offset:512
	global_store_dwordx4 v[180:181], v[56:59], off offset:512
	global_store_dwordx4 v[182:183], v[64:67], off offset:512
	global_store_dwordx4 v[120:121], v[60:63], off offset:512
	global_store_dwordx4 v[122:123], v[68:71], off offset:512
	global_store_dwordx4 v[124:125], v[72:75], off offset:512
	global_store_dwordx4 v[146:147], v[76:79], off offset:512
	global_load_dwordx4 v[48:51], v[134:135], off
	v_pk_add_f32 v[52:53], v[14:15], 0 op_sel_hi:[1,0]
	v_pk_add_f32 v[54:55], v[12:13], 0 op_sel_hi:[1,0]
	v_pk_add_f32 v[56:57], v[10:11], 0 op_sel_hi:[1,0]
	v_pk_add_f32 v[58:59], v[8:9], 0 op_sel_hi:[1,0]
	v_pk_add_f32 v[60:61], v[6:7], 0 op_sel_hi:[1,0]
	v_pk_add_f32 v[62:63], v[4:5], 0 op_sel_hi:[1,0]
	v_pk_add_f32 v[64:65], v[2:3], 0 op_sel_hi:[1,0]
	v_pk_add_f32 v[66:67], v[0:1], 0 op_sel_hi:[1,0]
	s_waitcnt vmcnt(0)
	v_pk_fma_f32 v[2:3], v[46:47], v[50:51], v[18:19]
	v_pk_fma_f32 v[0:1], v[44:45], v[48:49], v[16:17]
	v_pk_fma_f32 v[6:7], v[42:43], v[50:51], v[22:23]
	v_pk_fma_f32 v[4:5], v[40:41], v[48:49], v[20:21]
	v_pk_fma_f32 v[10:11], v[38:39], v[50:51], v[26:27]
	v_pk_fma_f32 v[8:9], v[36:37], v[48:49], v[24:25]
	v_pk_fma_f32 v[14:15], v[30:31], v[50:51], v[34:35]
	v_pk_fma_f32 v[12:13], v[28:29], v[48:49], v[32:33]
	v_pk_fma_f32 v[18:19], v[52:53], v[50:51], v[226:227]
	v_pk_fma_f32 v[16:17], v[54:55], v[48:49], v[224:225]
	v_pk_fma_f32 v[22:23], v[56:57], v[50:51], v[230:231]
	v_pk_fma_f32 v[20:21], v[58:59], v[48:49], v[228:229]
	v_pk_fma_f32 v[26:27], v[60:61], v[50:51], v[90:91]
	v_pk_fma_f32 v[24:25], v[62:63], v[48:49], v[88:89]
	v_pk_fma_f32 v[30:31], v[64:65], v[50:51], v[82:83]
	v_pk_fma_f32 v[28:29], v[66:67], v[48:49], v[80:81]
	global_store_dwordx4 v[176:177], v[0:3], off offset:576
	global_store_dwordx4 v[178:179], v[4:7], off offset:576
	global_store_dwordx4 v[180:181], v[8:11], off offset:576
	global_store_dwordx4 v[182:183], v[12:15], off offset:576
	global_store_dwordx4 v[120:121], v[16:19], off offset:576
	global_store_dwordx4 v[122:123], v[20:23], off offset:576
	global_store_dwordx4 v[124:125], v[24:27], off offset:576
	global_store_dwordx4 v[146:147], v[28:31], off offset:576
	s_cbranch_vccz .LBB0_1087
	s_waitcnt vmcnt(0)
	s_cmpk_gt_u32 s23, 0xff
	s_cbranch_scc1 .LBB0_1102
	s_barrier

.LBB0_1234:
	ds_read_b128 v[128:131], v171
	ds_read_b128 v[132:135], v171 offset:1024
	ds_read_b128 v[152:155], v171 offset:2048
	ds_read_b128 v[156:159], v171 offset:3072
	s_add_u32 s4, s46, 0xfff80080
	s_addc_u32 s5, s47, -1
	s_cmp_eq_u32 s64, 28
	s_cselect_b32 s5, s0, s5
	s_cselect_b32 s4, s1, s4
	s_cselect_b32 s59, s13, s37
	s_cselect_b32 s58, s15, s36
	s_add_i32 m0, s21, 0xc000
	ds_read_b128 v[160:163], v172
	ds_read_b128 v[164:167], v172 offset:1024
	ds_read_b128 v[174:177], v172 offset:2048
	ds_read_b128 v[178:181], v172 offset:3072
	ds_read_b128 v[182:185], v172 offset:4096
	ds_read_b128 v[186:189], v172 offset:5120
	ds_read_b128 v[190:193], v172 offset:6144
	ds_read_b128 v[194:197], v172 offset:7168
	global_load_lds_dwordx4 v144, s[46:47]
	s_add_i32 m0, s21, 0xe000
	s_nop 0
	global_load_lds_dwordx4 v146, s[46:47]
	s_waitcnt lgkmcnt(8)
	s_barrier
	s_waitcnt lgkmcnt(0)
	s_waitcnt lgkmcnt(0)
	v_mfma_f32_16x16x32_bf16 v[124:127], v[128:131], v[160:163], v[124:127]
	v_mfma_f32_16x16x32_bf16 v[120:123], v[152:155], v[160:163], v[120:123]
	v_mfma_f32_16x16x32_bf16 v[116:119], v[128:131], v[174:177], v[116:119]
	v_mfma_f32_16x16x32_bf16 v[112:115], v[152:155], v[174:177], v[112:115]
	v_mfma_f32_16x16x32_bf16 v[108:111], v[128:131], v[182:185], v[108:111]
	v_mfma_f32_16x16x32_bf16 v[104:107], v[152:155], v[182:185], v[104:107]
	v_mfma_f32_16x16x32_bf16 v[100:103], v[128:131], v[190:193], v[100:103]
	v_mfma_f32_16x16x32_bf16 v[96:99], v[152:155], v[190:193], v[96:99]
	v_mfma_f32_16x16x32_bf16 v[124:127], v[132:135], v[164:167], v[124:127]
	v_mfma_f32_16x16x32_bf16 v[120:123], v[156:159], v[164:167], v[120:123]
	v_mfma_f32_16x16x32_bf16 v[116:119], v[132:135], v[178:181], v[116:119]
	v_mfma_f32_16x16x32_bf16 v[112:115], v[156:159], v[178:181], v[112:115]
	v_mfma_f32_16x16x32_bf16 v[108:111], v[132:135], v[186:189], v[108:111]
	v_mfma_f32_16x16x32_bf16 v[104:107], v[156:159], v[186:189], v[104:107]
	v_mfma_f32_16x16x32_bf16 v[100:103], v[132:135], v[194:197], v[100:103]
	v_mfma_f32_16x16x32_bf16 v[96:99], v[156:159], v[194:197], v[96:99]
	s_barrier
	s_add_i32 s42, s60, s24
	s_add_u32 s98, s58, s10
	s_addc_u32 s99, s59, s11
	s_mov_b32 m0, s42
	ds_read_b128 v[198:201], v173
	ds_read_b128 v[202:205], v173 offset:1024
	ds_read_b128 v[206:209], v173 offset:2048
	ds_read_b128 v[210:213], v173 offset:3072
	global_load_lds_dwordx4 v140, s[58:59]
	s_add_i32 m0, s42, 0x2000
	s_nop 0
	global_load_lds_dwordx4 v136, s[58:59]
	s_barrier
	s_waitcnt lgkmcnt(0)
	s_waitcnt lgkmcnt(0)
	v_mfma_f32_16x16x32_bf16 v[68:71], v[198:201], v[160:163], v[68:71]
	v_mfma_f32_16x16x32_bf16 v[64:67], v[206:209], v[160:163], v[64:67]
	v_mfma_f32_16x16x32_bf16 v[52:55], v[198:201], v[174:177], v[52:55]
	v_mfma_f32_16x16x32_bf16 v[48:51], v[206:209], v[174:177], v[48:51]
	v_mfma_f32_16x16x32_bf16 v[44:47], v[198:201], v[182:185], v[44:47]
	v_mfma_f32_16x16x32_bf16 v[40:43], v[206:209], v[182:185], v[40:43]
	v_mfma_f32_16x16x32_bf16 v[36:39], v[198:201], v[190:193], v[36:39]
	v_mfma_f32_16x16x32_bf16 v[32:35], v[206:209], v[190:193], v[32:35]
	v_mfma_f32_16x16x32_bf16 v[68:71], v[202:205], v[164:167], v[68:71]
	v_mfma_f32_16x16x32_bf16 v[64:67], v[210:213], v[164:167], v[64:67]
	v_mfma_f32_16x16x32_bf16 v[52:55], v[202:205], v[178:181], v[52:55]
	v_mfma_f32_16x16x32_bf16 v[48:51], v[210:213], v[178:181], v[48:51]
	v_mfma_f32_16x16x32_bf16 v[44:47], v[202:205], v[186:189], v[44:47]
	v_mfma_f32_16x16x32_bf16 v[40:43], v[210:213], v[186:189], v[40:43]
	v_mfma_f32_16x16x32_bf16 v[36:39], v[202:205], v[194:197], v[36:39]
	v_mfma_f32_16x16x32_bf16 v[32:35], v[210:213], v[194:197], v[32:35]
	s_mov_b32 m0, s21
	s_add_u32 s100, s4, s10
	s_addc_u32 s101, s5, s11
	s_barrier
	ds_read_b128 v[160:163], v172 offset:16384
	ds_read_b128 v[164:167], v172 offset:17408
	ds_read_b128 v[174:177], v172 offset:18432
	ds_read_b128 v[178:181], v172 offset:19456
	ds_read_b128 v[182:185], v172 offset:20480
	ds_read_b128 v[186:189], v172 offset:21504
	ds_read_b128 v[190:193], v172 offset:22528
	ds_read_b128 v[194:197], v172 offset:23552
	global_load_lds_dwordx4 v142, s[4:5]
	s_mov_b32 m0, s28
	s_nop 0
	global_load_lds_dwordx4 v138, s[4:5]
	s_barrier
	s_waitcnt lgkmcnt(0)
	s_waitcnt lgkmcnt(0)
	v_mfma_f32_16x16x32_bf16 v[92:95], v[128:131], v[160:163], v[92:95]
	v_mfma_f32_16x16x32_bf16 v[88:91], v[152:155], v[160:163], v[88:91]
	v_mfma_f32_16x16x32_bf16 v[84:87], v[128:131], v[174:177], v[84:87]
	v_mfma_f32_16x16x32_bf16 v[80:83], v[152:155], v[174:177], v[80:83]
	v_mfma_f32_16x16x32_bf16 v[76:79], v[128:131], v[182:185], v[76:79]
	v_mfma_f32_16x16x32_bf16 v[72:75], v[152:155], v[182:185], v[72:75]
	v_mfma_f32_16x16x32_bf16 v[60:63], v[128:131], v[190:193], v[60:63]
	v_mfma_f32_16x16x32_bf16 v[56:59], v[152:155], v[190:193], v[56:59]
	v_mfma_f32_16x16x32_bf16 v[92:95], v[132:135], v[164:167], v[92:95]
	v_mfma_f32_16x16x32_bf16 v[88:91], v[156:159], v[164:167], v[88:91]
	v_mfma_f32_16x16x32_bf16 v[84:87], v[132:135], v[178:181], v[84:87]
	v_mfma_f32_16x16x32_bf16 v[80:83], v[156:159], v[178:181], v[80:83]
	v_mfma_f32_16x16x32_bf16 v[76:79], v[132:135], v[186:189], v[76:79]
	v_mfma_f32_16x16x32_bf16 v[72:75], v[156:159], v[186:189], v[72:75]
	v_mfma_f32_16x16x32_bf16 v[60:63], v[132:135], v[194:197], v[60:63]
	v_mfma_f32_16x16x32_bf16 v[56:59], v[156:159], v[194:197], v[56:59]
	s_barrier
	s_add_u32 s42, s58, 0x80000
	s_addc_u32 s43, s59, 0
	s_add_i32 s44, s61, s24
	s_mov_b32 m0, s44
	s_nop 0
	global_load_lds_dwordx4 v140, s[42:43]
	s_add_i32 m0, s44, 0x2000
	s_nop 0
	global_load_lds_dwordx4 v136, s[42:43]
	s_waitcnt vmcnt(6)
	s_barrier
	v_mfma_f32_16x16x32_bf16 v[28:31], v[198:201], v[160:163], v[28:31]
	v_mfma_f32_16x16x32_bf16 v[24:27], v[206:209], v[160:163], v[24:27]
	v_mfma_f32_16x16x32_bf16 v[20:23], v[198:201], v[174:177], v[20:23]
	v_mfma_f32_16x16x32_bf16 v[16:19], v[206:209], v[174:177], v[16:19]
	v_mfma_f32_16x16x32_bf16 v[12:15], v[198:201], v[182:185], v[12:15]
	v_mfma_f32_16x16x32_bf16 v[8:11], v[206:209], v[182:185], v[8:11]
	v_mfma_f32_16x16x32_bf16 v[4:7], v[198:201], v[190:193], v[4:7]
	v_mfma_f32_16x16x32_bf16 v[0:3], v[206:209], v[190:193], v[0:3]
	v_mfma_f32_16x16x32_bf16 v[28:31], v[202:205], v[164:167], v[28:31]
	v_mfma_f32_16x16x32_bf16 v[24:27], v[210:213], v[164:167], v[24:27]
	v_mfma_f32_16x16x32_bf16 v[20:23], v[202:205], v[178:181], v[20:23]
	v_mfma_f32_16x16x32_bf16 v[16:19], v[210:213], v[178:181], v[16:19]
	v_mfma_f32_16x16x32_bf16 v[12:15], v[202:205], v[186:189], v[12:15]
	v_mfma_f32_16x16x32_bf16 v[8:11], v[210:213], v[186:189], v[8:11]
	v_mfma_f32_16x16x32_bf16 v[4:7], v[202:205], v[194:197], v[4:7]
	v_mfma_f32_16x16x32_bf16 v[0:3], v[210:213], v[194:197], v[0:3]
	s_add_i32 s42, 0, 0x18000
	v_add_u32_e32 v156, s42, v169
	s_barrier
	ds_read_b128 v[128:131], v156
	ds_read_b128 v[132:135], v156 offset:1024
	ds_read_b128 v[152:155], v156 offset:2048
	ds_read_b128 v[156:159], v156 offset:3072
	s_add_u32 s4, s4, 0x80000
	s_addc_u32 s5, s5, 0
	s_mov_b32 m0, s29
	ds_read_b128 v[160:163], v172 offset:32768
	ds_read_b128 v[164:167], v172 offset:33792
	ds_read_b128 v[174:177], v172 offset:34816
	ds_read_b128 v[178:181], v172 offset:35840
	ds_read_b128 v[182:185], v172 offset:36864
	ds_read_b128 v[186:189], v172 offset:37888
	ds_read_b128 v[190:193], v172 offset:38912
	ds_read_b128 v[194:197], v172 offset:39936
	global_load_lds_dwordx4 v142, s[4:5]
	s_mov_b32 m0, s33
	s_nop 0
	global_load_lds_dwordx4 v138, s[4:5]
	s_waitcnt lgkmcnt(8)
	s_barrier
	s_waitcnt lgkmcnt(0)
	s_waitcnt lgkmcnt(0)
	v_mfma_f32_16x16x32_bf16 v[124:127], v[128:131], v[160:163], v[124:127]
	v_mfma_f32_16x16x32_bf16 v[120:123], v[152:155], v[160:163], v[120:123]
	v_mfma_f32_16x16x32_bf16 v[116:119], v[128:131], v[174:177], v[116:119]
	v_mfma_f32_16x16x32_bf16 v[112:115], v[152:155], v[174:177], v[112:115]
	v_mfma_f32_16x16x32_bf16 v[108:111], v[128:131], v[182:185], v[108:111]
	v_mfma_f32_16x16x32_bf16 v[104:107], v[152:155], v[182:185], v[104:107]
	v_mfma_f32_16x16x32_bf16 v[100:103], v[128:131], v[190:193], v[100:103]
	v_mfma_f32_16x16x32_bf16 v[96:99], v[152:155], v[190:193], v[96:99]
	v_mfma_f32_16x16x32_bf16 v[124:127], v[132:135], v[164:167], v[124:127]
	v_mfma_f32_16x16x32_bf16 v[120:123], v[156:159], v[164:167], v[120:123]
	v_mfma_f32_16x16x32_bf16 v[116:119], v[132:135], v[178:181], v[116:119]
	v_mfma_f32_16x16x32_bf16 v[112:115], v[156:159], v[178:181], v[112:115]
	v_mfma_f32_16x16x32_bf16 v[108:111], v[132:135], v[186:189], v[108:111]
	v_mfma_f32_16x16x32_bf16 v[104:107], v[156:159], v[186:189], v[104:107]
	v_mfma_f32_16x16x32_bf16 v[100:103], v[132:135], v[194:197], v[100:103]
	v_mfma_f32_16x16x32_bf16 v[96:99], v[156:159], v[194:197], v[96:99]
	s_barrier
	s_add_i32 s43, 0, 0x1c000
	s_add_i32 s4, s42, s24
	v_add_u32_e32 v210, s43, v169
	s_mov_b32 m0, s4
	ds_read_b128 v[198:201], v210
	ds_read_b128 v[202:205], v210 offset:1024
	ds_read_b128 v[206:209], v210 offset:2048
	ds_read_b128 v[210:213], v210 offset:3072
	global_load_lds_dwordx4 v140, s[98:99]
	s_add_i32 m0, s4, 0x2000
	s_nop 0
	global_load_lds_dwordx4 v136, s[98:99]
	s_barrier
	s_waitcnt lgkmcnt(0)
	s_waitcnt lgkmcnt(0)
	v_mfma_f32_16x16x32_bf16 v[68:71], v[198:201], v[160:163], v[68:71]
	v_mfma_f32_16x16x32_bf16 v[64:67], v[206:209], v[160:163], v[64:67]
	v_mfma_f32_16x16x32_bf16 v[52:55], v[198:201], v[174:177], v[52:55]
	v_mfma_f32_16x16x32_bf16 v[48:51], v[206:209], v[174:177], v[48:51]
	v_mfma_f32_16x16x32_bf16 v[44:47], v[198:201], v[182:185], v[44:47]
	v_mfma_f32_16x16x32_bf16 v[40:43], v[206:209], v[182:185], v[40:43]
	v_mfma_f32_16x16x32_bf16 v[36:39], v[198:201], v[190:193], v[36:39]
	v_mfma_f32_16x16x32_bf16 v[32:35], v[206:209], v[190:193], v[32:35]
	v_mfma_f32_16x16x32_bf16 v[68:71], v[202:205], v[164:167], v[68:71]
	v_mfma_f32_16x16x32_bf16 v[64:67], v[210:213], v[164:167], v[64:67]
	v_mfma_f32_16x16x32_bf16 v[52:55], v[202:205], v[178:181], v[52:55]
	v_mfma_f32_16x16x32_bf16 v[48:51], v[210:213], v[178:181], v[48:51]
	v_mfma_f32_16x16x32_bf16 v[44:47], v[202:205], v[186:189], v[44:47]
	v_mfma_f32_16x16x32_bf16 v[40:43], v[210:213], v[186:189], v[40:43]
	v_mfma_f32_16x16x32_bf16 v[36:39], v[202:205], v[194:197], v[36:39]
	v_mfma_f32_16x16x32_bf16 v[32:35], v[210:213], v[194:197], v[32:35]
	s_mov_b32 m0, s41
	s_barrier
	ds_read_b128 v[160:163], v172 offset:49152
	ds_read_b128 v[164:167], v172 offset:50176
	ds_read_b128 v[174:177], v172 offset:51200
	ds_read_b128 v[178:181], v172 offset:52224
	ds_read_b128 v[182:185], v172 offset:53248
	ds_read_b128 v[186:189], v172 offset:54272
	ds_read_b128 v[190:193], v172 offset:55296
	ds_read_b128 v[194:197], v172 offset:56320
	global_load_lds_dwordx4 v142, s[100:101]
	s_mov_b32 m0, s53
	s_nop 0
	global_load_lds_dwordx4 v138, s[100:101]
	s_barrier
	s_waitcnt lgkmcnt(0)
	s_waitcnt lgkmcnt(0)
	v_mfma_f32_16x16x32_bf16 v[92:95], v[128:131], v[160:163], v[92:95]
	v_mfma_f32_16x16x32_bf16 v[88:91], v[152:155], v[160:163], v[88:91]
	v_mfma_f32_16x16x32_bf16 v[84:87], v[128:131], v[174:177], v[84:87]
	v_mfma_f32_16x16x32_bf16 v[80:83], v[152:155], v[174:177], v[80:83]
	v_mfma_f32_16x16x32_bf16 v[76:79], v[128:131], v[182:185], v[76:79]
	v_mfma_f32_16x16x32_bf16 v[72:75], v[152:155], v[182:185], v[72:75]
	v_mfma_f32_16x16x32_bf16 v[60:63], v[128:131], v[190:193], v[60:63]
	v_mfma_f32_16x16x32_bf16 v[56:59], v[152:155], v[190:193], v[56:59]
	v_mfma_f32_16x16x32_bf16 v[92:95], v[132:135], v[164:167], v[92:95]
	v_mfma_f32_16x16x32_bf16 v[88:91], v[156:159], v[164:167], v[88:91]
	v_mfma_f32_16x16x32_bf16 v[84:87], v[132:135], v[178:181], v[84:87]
	v_mfma_f32_16x16x32_bf16 v[80:83], v[156:159], v[178:181], v[80:83]
	v_mfma_f32_16x16x32_bf16 v[76:79], v[132:135], v[186:189], v[76:79]
	v_mfma_f32_16x16x32_bf16 v[72:75], v[156:159], v[186:189], v[72:75]
	v_mfma_f32_16x16x32_bf16 v[60:63], v[132:135], v[194:197], v[60:63]
	v_mfma_f32_16x16x32_bf16 v[56:59], v[156:159], v[194:197], v[56:59]
	s_barrier
	s_add_u32 s4, s58, 0x80080
	s_addc_u32 s5, s59, 0
	s_add_i32 s42, s43, s24
	s_mov_b32 m0, s42
	s_nop 0
	global_load_lds_dwordx4 v140, s[4:5]
	s_add_i32 m0, s42, 0x2000
	s_nop 0
	global_load_lds_dwordx4 v136, s[4:5]
	s_waitcnt vmcnt(6)
	s_barrier
	v_mfma_f32_16x16x32_bf16 v[28:31], v[198:201], v[160:163], v[28:31]
	v_mfma_f32_16x16x32_bf16 v[24:27], v[206:209], v[160:163], v[24:27]
	v_mfma_f32_16x16x32_bf16 v[20:23], v[198:201], v[174:177], v[20:23]
	v_mfma_f32_16x16x32_bf16 v[16:19], v[206:209], v[174:177], v[16:19]
	v_mfma_f32_16x16x32_bf16 v[12:15], v[198:201], v[182:185], v[12:15]
	v_mfma_f32_16x16x32_bf16 v[8:11], v[206:209], v[182:185], v[8:11]
	v_mfma_f32_16x16x32_bf16 v[4:7], v[198:201], v[190:193], v[4:7]
	v_mfma_f32_16x16x32_bf16 v[0:3], v[206:209], v[190:193], v[0:3]
	v_mfma_f32_16x16x32_bf16 v[28:31], v[202:205], v[164:167], v[28:31]
	v_mfma_f32_16x16x32_bf16 v[24:27], v[210:213], v[164:167], v[24:27]
	v_mfma_f32_16x16x32_bf16 v[20:23], v[202:205], v[178:181], v[20:23]
	v_mfma_f32_16x16x32_bf16 v[16:19], v[210:213], v[178:181], v[16:19]
	v_mfma_f32_16x16x32_bf16 v[12:15], v[202:205], v[186:189], v[12:15]
	v_mfma_f32_16x16x32_bf16 v[8:11], v[210:213], v[186:189], v[8:11]
	v_mfma_f32_16x16x32_bf16 v[4:7], v[202:205], v[194:197], v[4:7]
	v_mfma_f32_16x16x32_bf16 v[0:3], v[210:213], v[194:197], v[0:3]
	s_add_i32 s64, s64, 2
	s_add_u32 s46, s46, 0x100
	s_addc_u32 s47, s47, 0
	s_add_u32 s36, s36, 0x100
	s_addc_u32 s37, s37, 0
	s_cmp_gt_u32 s64, 29
	s_barrier
	s_cbranch_scc0 .LBB0_1234
	v_lshl_or_b32 v152, s63, 8, v170
	v_ashrrev_i32_e32 v153, 31, v152
	v_lshl_add_u64 v[164:165], v[152:153], 2, s[8:9]
	flat_load_dwordx4 v[132:135], v[164:165]
	flat_load_dwordx4 v[128:131], v[164:165] offset:16
	v_lshl_add_u32 v182, s20, 8, v168
	v_mov_b64_e32 v[166:167], s[48:49]
	v_add_u32_e32 v159, 0x80, v182
	v_mad_i64_i32 v[154:155], s[0:1], v182, s62, v[166:167]
	v_or_b32_e32 v156, 16, v182
	v_or_b32_e32 v157, 32, v182
	v_or_b32_e32 v158, 48, v182
	v_lshlrev_b64 v[174:175], 1, v[152:153]
	v_mad_i64_i32 v[178:179], s[0:1], v159, s62, v[166:167]
	v_add_u32_e32 v160, 0x90, v182
	v_mad_i64_i32 v[152:153], s[0:1], v156, s62, v[166:167]
	v_mad_i64_i32 v[156:157], s[0:1], v157, s62, v[166:167]
	v_mad_i64_i32 v[176:177], s[0:1], v158, s62, v[166:167]
	v_lshl_add_u64 v[162:163], v[154:155], 0, v[174:175]
	v_lshl_add_u64 v[154:155], v[178:179], 0, v[174:175]
	v_mad_i64_i32 v[180:181], s[0:1], v160, s62, v[166:167]
	v_lshl_add_u64 v[160:161], v[152:153], 0, v[174:175]
	v_lshl_add_u64 v[158:159], v[156:157], 0, v[174:175]
	v_lshl_add_u64 v[156:157], v[176:177], 0, v[174:175]
	v_lshl_add_u64 v[152:153], v[180:181], 0, v[174:175]
	s_and_b64 vcc, exec, s[6:7]
	s_mov_b32 s63, s12
	s_mov_b32 s20, s14
	s_mov_b64 s[58:59], s[18:19]
	s_mov_b64 s[36:37], s[16:17]
	s_waitcnt vmcnt(0) lgkmcnt(0)
	v_pk_add_f32 v[124:125], v[124:125], v[132:133]
	v_pk_add_f32 v[178:179], v[72:73], v[128:129]
	s_nop 1
	v_cvt_pk_bf16_f32 v72, v124, v125
	v_pk_add_f32 v[126:127], v[126:127], v[134:135]
	v_pk_add_f32 v[122:123], v[122:123], v[130:131]
	v_pk_add_f32 v[120:121], v[120:121], v[128:129]
	v_pk_add_f32 v[116:117], v[116:117], v[132:133]
	v_pk_add_f32 v[176:177], v[74:75], v[130:131]
	s_nop 1
	v_cvt_pk_bf16_f32 v73, v126, v127
	s_nop 1
	v_cvt_pk_bf16_f32 v74, v120, v121
	s_nop 1
	v_cvt_pk_bf16_f32 v75, v122, v123
	global_store_dwordx4 v[162:163], v[72:75], off
	v_pk_add_f32 v[118:119], v[118:119], v[134:135]
	v_pk_add_f32 v[114:115], v[114:115], v[130:131]
	s_nop 1
	v_cvt_pk_bf16_f32 v72, v116, v117
	v_pk_add_f32 v[112:113], v[112:113], v[128:129]
	v_pk_add_f32 v[108:109], v[108:109], v[132:133]
	s_nop 1
	v_cvt_pk_bf16_f32 v73, v118, v119
	s_nop 1
	v_cvt_pk_bf16_f32 v74, v112, v113
	s_nop 1
	v_cvt_pk_bf16_f32 v75, v114, v115
	global_store_dwordx4 v[160:161], v[72:75], off
	v_pk_add_f32 v[110:111], v[110:111], v[134:135]
	v_pk_add_f32 v[106:107], v[106:107], v[130:131]
	s_nop 1
	v_cvt_pk_bf16_f32 v72, v108, v109
	v_pk_add_f32 v[104:105], v[104:105], v[128:129]
	v_pk_add_f32 v[100:101], v[100:101], v[132:133]
	s_nop 1
	v_cvt_pk_bf16_f32 v73, v110, v111
	s_nop 1
	v_cvt_pk_bf16_f32 v74, v104, v105
	s_nop 1
	v_cvt_pk_bf16_f32 v75, v106, v107
	global_store_dwordx4 v[158:159], v[72:75], off
	v_pk_add_f32 v[102:103], v[102:103], v[134:135]
	v_pk_add_f32 v[98:99], v[98:99], v[130:131]
	s_nop 1
	v_cvt_pk_bf16_f32 v72, v100, v101
	v_pk_add_f32 v[96:97], v[96:97], v[128:129]
	v_pk_add_f32 v[92:93], v[92:93], v[132:133]
	s_nop 1
	v_cvt_pk_bf16_f32 v73, v102, v103
	s_nop 1
	v_cvt_pk_bf16_f32 v74, v96, v97
	s_nop 1
	v_cvt_pk_bf16_f32 v75, v98, v99
	global_store_dwordx4 v[156:157], v[72:75], off
	v_pk_add_f32 v[94:95], v[94:95], v[134:135]
	v_pk_add_f32 v[90:91], v[90:91], v[130:131]
	s_nop 1
	v_cvt_pk_bf16_f32 v72, v92, v93
	v_pk_add_f32 v[88:89], v[88:89], v[128:129]
	v_pk_add_f32 v[84:85], v[84:85], v[132:133]
	v_pk_add_f32 v[76:77], v[76:77], v[132:133]
	s_nop 1
	v_cvt_pk_bf16_f32 v73, v94, v95
	s_nop 1
	v_cvt_pk_bf16_f32 v74, v88, v89
	s_nop 1
	v_cvt_pk_bf16_f32 v75, v90, v91
	global_store_dwordx4 v[154:155], v[72:75], off
	v_pk_add_f32 v[86:87], v[86:87], v[134:135]
	v_pk_add_f32 v[82:83], v[82:83], v[130:131]
	s_nop 1
	v_cvt_pk_bf16_f32 v72, v84, v85
	v_pk_add_f32 v[80:81], v[80:81], v[128:129]
	s_nop 1
	v_cvt_pk_bf16_f32 v73, v86, v87
	v_pk_add_f32 v[78:79], v[78:79], v[134:135]
	s_nop 1
	v_cvt_pk_bf16_f32 v74, v80, v81
	s_nop 1
	v_cvt_pk_bf16_f32 v75, v82, v83
	global_store_dwordx4 v[152:153], v[72:75], off
	v_pk_add_f32 v[60:61], v[60:61], v[132:133]
	v_pk_add_f32 v[62:63], v[62:63], v[134:135]
	s_nop 1
	v_cvt_pk_bf16_f32 v72, v76, v77
	v_add_u32_e32 v76, 0xa0, v182
	v_mad_i64_i32 v[76:77], s[0:1], v76, s62, v[166:167]
	s_nop 1
	v_cvt_pk_bf16_f32 v73, v78, v79
	v_lshl_add_u64 v[76:77], v[76:77], 0, v[174:175]
	s_nop 1
	v_cvt_pk_bf16_f32 v74, v178, v179
	s_nop 1
	v_cvt_pk_bf16_f32 v75, v176, v177
	global_store_dwordx4 v[76:77], v[72:75], off
	s_nop 1
	v_pk_add_f32 v[72:73], v[58:59], v[130:131]
	v_pk_add_f32 v[58:59], v[56:57], v[128:129]
	s_nop 1
	v_cvt_pk_bf16_f32 v56, v60, v61
	v_add_u32_e32 v60, 0xb0, v182
	v_mad_i64_i32 v[60:61], s[0:1], v60, s62, v[166:167]
	s_nop 1
	v_cvt_pk_bf16_f32 v57, v62, v63
	s_nop 1
	v_cvt_pk_bf16_f32 v58, v58, v59
	s_nop 1
	v_cvt_pk_bf16_f32 v59, v72, v73
	v_lshl_add_u64 v[72:73], v[60:61], 0, v[174:175]
	global_store_dwordx4 v[72:73], v[56:59], off
	flat_load_dwordx4 v[56:59], v[164:165] offset:512
	s_nop 0
	flat_load_dwordx4 v[60:63], v[164:165] offset:528
	s_waitcnt vmcnt(0) lgkmcnt(0)
	v_pk_add_f32 v[70:71], v[70:71], v[58:59]
	v_pk_add_f32 v[68:69], v[68:69], v[56:57]
	v_pk_add_f32 v[66:67], v[66:67], v[62:63]
	v_pk_add_f32 v[64:65], v[64:65], v[60:61]
	v_pk_add_f32 v[54:55], v[54:55], v[58:59]
	v_pk_add_f32 v[52:53], v[52:53], v[56:57]
	v_pk_add_f32 v[46:47], v[46:47], v[58:59]
	v_pk_add_f32 v[44:45], v[44:45], v[56:57]
	v_pk_add_f32 v[38:39], v[38:39], v[58:59]
	v_pk_add_f32 v[36:37], v[36:37], v[56:57]
	v_pk_add_f32 v[30:31], v[30:31], v[58:59]
	v_pk_add_f32 v[28:29], v[28:29], v[56:57]
	v_pk_add_f32 v[22:23], v[22:23], v[58:59]
	v_pk_add_f32 v[20:21], v[20:21], v[56:57]
	v_pk_add_f32 v[14:15], v[14:15], v[58:59]
	v_pk_add_f32 v[12:13], v[12:13], v[56:57]
	v_pk_add_f32 v[6:7], v[6:7], v[58:59]
	v_pk_add_f32 v[4:5], v[4:5], v[56:57]
	v_pk_add_f32 v[56:57], v[2:3], v[62:63]
	v_pk_add_f32 v[58:59], v[0:1], v[60:61]
	s_nop 1
	v_cvt_pk_bf16_f32 v0, v68, v69
	s_nop 1
	v_cvt_pk_bf16_f32 v1, v70, v71
	s_nop 1
	v_cvt_pk_bf16_f32 v2, v64, v65
	s_nop 1
	v_cvt_pk_bf16_f32 v3, v66, v67
	v_pk_add_f32 v[50:51], v[50:51], v[62:63]
	v_pk_add_f32 v[48:49], v[48:49], v[60:61]
	global_store_dwordx4 v[162:163], v[0:3], off offset:256
	v_pk_add_f32 v[42:43], v[42:43], v[62:63]
	v_pk_add_f32 v[40:41], v[40:41], v[60:61]
	s_nop 1
	v_cvt_pk_bf16_f32 v0, v52, v53
	s_nop 1
	v_cvt_pk_bf16_f32 v1, v54, v55
	s_nop 1
	v_cvt_pk_bf16_f32 v2, v48, v49
	s_nop 1
	v_cvt_pk_bf16_f32 v3, v50, v51
	global_store_dwordx4 v[160:161], v[0:3], off offset:256
	v_pk_add_f32 v[34:35], v[34:35], v[62:63]
	v_pk_add_f32 v[32:33], v[32:33], v[60:61]
	s_nop 1
	v_cvt_pk_bf16_f32 v0, v44, v45
	s_nop 1
	v_cvt_pk_bf16_f32 v1, v46, v47
	s_nop 1
	v_cvt_pk_bf16_f32 v2, v40, v41
	s_nop 1
	v_cvt_pk_bf16_f32 v3, v42, v43
	global_store_dwordx4 v[158:159], v[0:3], off offset:256
	v_pk_add_f32 v[26:27], v[26:27], v[62:63]
	v_pk_add_f32 v[24:25], v[24:25], v[60:61]
	s_nop 1
	v_cvt_pk_bf16_f32 v0, v36, v37
	s_nop 1
	v_cvt_pk_bf16_f32 v1, v38, v39
	s_nop 1
	v_cvt_pk_bf16_f32 v2, v32, v33
	s_nop 1
	v_cvt_pk_bf16_f32 v3, v34, v35
	global_store_dwordx4 v[156:157], v[0:3], off offset:256
	v_pk_add_f32 v[18:19], v[18:19], v[62:63]
	v_pk_add_f32 v[16:17], v[16:17], v[60:61]
	s_nop 1
	v_cvt_pk_bf16_f32 v0, v28, v29
	s_nop 1
	v_cvt_pk_bf16_f32 v1, v30, v31
	s_nop 1
	v_cvt_pk_bf16_f32 v2, v24, v25
	s_nop 1
	v_cvt_pk_bf16_f32 v3, v26, v27
	global_store_dwordx4 v[154:155], v[0:3], off offset:256
	v_pk_add_f32 v[10:11], v[10:11], v[62:63]
	v_pk_add_f32 v[8:9], v[8:9], v[60:61]
	s_nop 1
	v_cvt_pk_bf16_f32 v0, v20, v21
	s_nop 1
	v_cvt_pk_bf16_f32 v1, v22, v23
	s_nop 1
	v_cvt_pk_bf16_f32 v2, v16, v17
	s_nop 1
	v_cvt_pk_bf16_f32 v3, v18, v19
	global_store_dwordx4 v[152:153], v[0:3], off offset:256
	s_nop 1
	s_nop 1
	v_cvt_pk_bf16_f32 v0, v12, v13
	s_nop 1
	v_cvt_pk_bf16_f32 v1, v14, v15
	s_nop 1
	v_cvt_pk_bf16_f32 v2, v8, v9
	s_nop 1
	v_cvt_pk_bf16_f32 v3, v10, v11
	global_store_dwordx4 v[76:77], v[0:3], off offset:256
	s_nop 1
	s_nop 1
	v_cvt_pk_bf16_f32 v0, v4, v5
	s_nop 1
	v_cvt_pk_bf16_f32 v1, v6, v7
	s_nop 1
	v_cvt_pk_bf16_f32 v2, v58, v59
	s_nop 1
	v_cvt_pk_bf16_f32 v3, v56, v57
	global_store_dwordx4 v[72:73], v[0:3], off offset:256
	s_cbranch_vccz .LBB0_1231
	s_waitcnt vmcnt(0)
	s_cmpk_gt_u32 s23, 0xff
	s_cbranch_scc1 .LBB0_1238
	s_barrier

.LBB0_1533:
	ds_read_b128 v[128:131], v165
	ds_read_b128 v[132:135], v165 offset:1024
	ds_read_b128 v[150:153], v165 offset:2048
	ds_read_b128 v[154:157], v165 offset:3072
	s_add_u32 s68, s8, 0x100
	s_addc_u32 s69, s9, 0
	s_cmp_eq_u32 s78, 28
	s_cselect_b32 s5, s0, s69
	s_cselect_b32 s4, s1, s68
	s_cselect_b32 s71, s59, s77
	s_cselect_b32 s70, s61, s76
	s_add_i32 m0, s25, 0xc000
	ds_read_b128 v[158:161], v166
	ds_read_b128 v[168:171], v166 offset:1024
	ds_read_b128 v[172:175], v166 offset:2048
	ds_read_b128 v[176:179], v166 offset:3072
	ds_read_b128 v[180:183], v166 offset:4096
	ds_read_b128 v[184:187], v166 offset:5120
	ds_read_b128 v[188:191], v166 offset:6144
	ds_read_b128 v[192:195], v166 offset:7168
	global_load_lds_dwordx4 v142, s[8:9]
	s_add_i32 m0, s25, 0xe000
	s_nop 0
	global_load_lds_dwordx4 v144, s[8:9]
	s_waitcnt lgkmcnt(8)
	s_barrier
	s_waitcnt lgkmcnt(0)
	s_waitcnt lgkmcnt(0)
	v_mfma_f32_16x16x32_bf16 v[124:127], v[128:131], v[158:161], v[124:127]
	v_mfma_f32_16x16x32_bf16 v[92:95], v[150:153], v[158:161], v[92:95]
	v_mfma_f32_16x16x32_bf16 v[120:123], v[128:131], v[172:175], v[120:123]
	v_mfma_f32_16x16x32_bf16 v[88:91], v[150:153], v[172:175], v[88:91]
	v_mfma_f32_16x16x32_bf16 v[116:119], v[128:131], v[180:183], v[116:119]
	v_mfma_f32_16x16x32_bf16 v[84:87], v[150:153], v[180:183], v[84:87]
	v_mfma_f32_16x16x32_bf16 v[112:115], v[128:131], v[188:191], v[112:115]
	v_mfma_f32_16x16x32_bf16 v[80:83], v[150:153], v[188:191], v[80:83]
	v_mfma_f32_16x16x32_bf16 v[124:127], v[132:135], v[168:171], v[124:127]
	v_mfma_f32_16x16x32_bf16 v[92:95], v[154:157], v[168:171], v[92:95]
	v_mfma_f32_16x16x32_bf16 v[120:123], v[132:135], v[176:179], v[120:123]
	v_mfma_f32_16x16x32_bf16 v[88:91], v[154:157], v[176:179], v[88:91]
	v_mfma_f32_16x16x32_bf16 v[116:119], v[132:135], v[184:187], v[116:119]
	v_mfma_f32_16x16x32_bf16 v[84:87], v[154:157], v[184:187], v[84:87]
	v_mfma_f32_16x16x32_bf16 v[112:115], v[132:135], v[192:195], v[112:115]
	v_mfma_f32_16x16x32_bf16 v[80:83], v[154:157], v[192:195], v[80:83]
	s_barrier
	s_add_i32 s8, s41, s24
	s_add_u32 s98, s70, s16
	s_addc_u32 s99, s71, s17
	s_mov_b32 m0, s8
	ds_read_b128 v[196:199], v167
	ds_read_b128 v[200:203], v167 offset:1024
	ds_read_b128 v[204:207], v167 offset:2048
	ds_read_b128 v[208:211], v167 offset:3072
	global_load_lds_dwordx4 v140, s[70:71]
	s_add_i32 m0, s8, 0x2000
	s_nop 0
	global_load_lds_dwordx4 v138, s[70:71]
	s_barrier
	s_waitcnt lgkmcnt(0)
	s_waitcnt lgkmcnt(0)
	v_mfma_f32_16x16x32_bf16 v[60:63], v[196:199], v[158:161], v[60:63]
	v_mfma_f32_16x16x32_bf16 v[28:31], v[204:207], v[158:161], v[28:31]
	v_mfma_f32_16x16x32_bf16 v[56:59], v[196:199], v[172:175], v[56:59]
	v_mfma_f32_16x16x32_bf16 v[24:27], v[204:207], v[172:175], v[24:27]
	v_mfma_f32_16x16x32_bf16 v[52:55], v[196:199], v[180:183], v[52:55]
	v_mfma_f32_16x16x32_bf16 v[20:23], v[204:207], v[180:183], v[20:23]
	v_mfma_f32_16x16x32_bf16 v[48:51], v[196:199], v[188:191], v[48:51]
	v_mfma_f32_16x16x32_bf16 v[16:19], v[204:207], v[188:191], v[16:19]
	v_mfma_f32_16x16x32_bf16 v[60:63], v[200:203], v[168:171], v[60:63]
	v_mfma_f32_16x16x32_bf16 v[28:31], v[208:211], v[168:171], v[28:31]
	v_mfma_f32_16x16x32_bf16 v[56:59], v[200:203], v[176:179], v[56:59]
	v_mfma_f32_16x16x32_bf16 v[24:27], v[208:211], v[176:179], v[24:27]
	v_mfma_f32_16x16x32_bf16 v[52:55], v[200:203], v[184:187], v[52:55]
	v_mfma_f32_16x16x32_bf16 v[20:23], v[208:211], v[184:187], v[20:23]
	v_mfma_f32_16x16x32_bf16 v[48:51], v[200:203], v[192:195], v[48:51]
	v_mfma_f32_16x16x32_bf16 v[16:19], v[208:211], v[192:195], v[16:19]
	s_mov_b32 m0, s25
	s_add_u32 s100, s4, s16
	s_addc_u32 s101, s5, s17
	s_barrier
	ds_read_b128 v[158:161], v166 offset:16384
	ds_read_b128 v[168:171], v166 offset:17408
	ds_read_b128 v[172:175], v166 offset:18432
	ds_read_b128 v[176:179], v166 offset:19456
	ds_read_b128 v[180:183], v166 offset:20480
	ds_read_b128 v[184:187], v166 offset:21504
	ds_read_b128 v[188:191], v166 offset:22528
	ds_read_b128 v[192:195], v166 offset:23552
	global_load_lds_dwordx4 v140, s[4:5]
	s_mov_b32 m0, s28
	s_nop 0
	global_load_lds_dwordx4 v138, s[4:5]
	s_barrier
	s_waitcnt lgkmcnt(0)
	s_waitcnt lgkmcnt(0)
	v_mfma_f32_16x16x32_bf16 v[108:111], v[128:131], v[158:161], v[108:111]
	v_mfma_f32_16x16x32_bf16 v[76:79], v[150:153], v[158:161], v[76:79]
	v_mfma_f32_16x16x32_bf16 v[104:107], v[128:131], v[172:175], v[104:107]
	v_mfma_f32_16x16x32_bf16 v[72:75], v[150:153], v[172:175], v[72:75]
	v_mfma_f32_16x16x32_bf16 v[100:103], v[128:131], v[180:183], v[100:103]
	v_mfma_f32_16x16x32_bf16 v[68:71], v[150:153], v[180:183], v[68:71]
	v_mfma_f32_16x16x32_bf16 v[96:99], v[128:131], v[188:191], v[96:99]
	v_mfma_f32_16x16x32_bf16 v[64:67], v[150:153], v[188:191], v[64:67]
	v_mfma_f32_16x16x32_bf16 v[108:111], v[132:135], v[168:171], v[108:111]
	v_mfma_f32_16x16x32_bf16 v[76:79], v[154:157], v[168:171], v[76:79]
	v_mfma_f32_16x16x32_bf16 v[104:107], v[132:135], v[176:179], v[104:107]
	v_mfma_f32_16x16x32_bf16 v[72:75], v[154:157], v[176:179], v[72:75]
	v_mfma_f32_16x16x32_bf16 v[100:103], v[132:135], v[184:187], v[100:103]
	v_mfma_f32_16x16x32_bf16 v[68:71], v[154:157], v[184:187], v[68:71]
	v_mfma_f32_16x16x32_bf16 v[96:99], v[132:135], v[192:195], v[96:99]
	v_mfma_f32_16x16x32_bf16 v[64:67], v[154:157], v[192:195], v[64:67]
	s_barrier
	s_add_u32 s8, s70, 0x80000
	s_addc_u32 s9, s71, 0
	s_add_i32 s42, s53, s24
	s_mov_b32 m0, s42
	s_nop 0
	global_load_lds_dwordx4 v140, s[8:9]
	s_add_i32 m0, s42, 0x2000
	s_nop 0
	global_load_lds_dwordx4 v138, s[8:9]
	s_waitcnt vmcnt(6)
	s_barrier
	v_mfma_f32_16x16x32_bf16 v[44:47], v[196:199], v[158:161], v[44:47]
	v_mfma_f32_16x16x32_bf16 v[12:15], v[204:207], v[158:161], v[12:15]
	v_mfma_f32_16x16x32_bf16 v[40:43], v[196:199], v[172:175], v[40:43]
	v_mfma_f32_16x16x32_bf16 v[8:11], v[204:207], v[172:175], v[8:11]
	v_mfma_f32_16x16x32_bf16 v[36:39], v[196:199], v[180:183], v[36:39]
	v_mfma_f32_16x16x32_bf16 v[4:7], v[204:207], v[180:183], v[4:7]
	v_mfma_f32_16x16x32_bf16 v[32:35], v[196:199], v[188:191], v[32:35]
	v_mfma_f32_16x16x32_bf16 v[0:3], v[204:207], v[188:191], v[0:3]
	v_mfma_f32_16x16x32_bf16 v[44:47], v[200:203], v[168:171], v[44:47]
	v_mfma_f32_16x16x32_bf16 v[12:15], v[208:211], v[168:171], v[12:15]
	v_mfma_f32_16x16x32_bf16 v[40:43], v[200:203], v[176:179], v[40:43]
	v_mfma_f32_16x16x32_bf16 v[8:11], v[208:211], v[176:179], v[8:11]
	v_mfma_f32_16x16x32_bf16 v[36:39], v[200:203], v[184:187], v[36:39]
	v_mfma_f32_16x16x32_bf16 v[4:7], v[208:211], v[184:187], v[4:7]
	v_mfma_f32_16x16x32_bf16 v[32:35], v[200:203], v[192:195], v[32:35]
	v_mfma_f32_16x16x32_bf16 v[0:3], v[208:211], v[192:195], v[0:3]
	s_add_i32 s8, 0, 0x18000
	v_add_u32_e32 v154, s8, v163
	s_barrier
	ds_read_b128 v[128:131], v154
	ds_read_b128 v[132:135], v154 offset:1024
	ds_read_b128 v[150:153], v154 offset:2048
	ds_read_b128 v[154:157], v154 offset:3072
	s_add_u32 s4, s4, 0x80000
	s_addc_u32 s5, s5, 0
	s_mov_b32 m0, s29
	ds_read_b128 v[158:161], v166 offset:32768
	ds_read_b128 v[168:171], v166 offset:33792
	ds_read_b128 v[172:175], v166 offset:34816
	ds_read_b128 v[176:179], v166 offset:35840
	ds_read_b128 v[180:183], v166 offset:36864
	ds_read_b128 v[184:187], v166 offset:37888
	ds_read_b128 v[188:191], v166 offset:38912
	ds_read_b128 v[192:195], v166 offset:39936
	global_load_lds_dwordx4 v140, s[4:5]
	s_mov_b32 m0, s33
	s_nop 0
	global_load_lds_dwordx4 v138, s[4:5]
	s_waitcnt lgkmcnt(8)
	s_barrier
	s_waitcnt lgkmcnt(0)
	s_waitcnt lgkmcnt(0)
	v_mfma_f32_16x16x32_bf16 v[124:127], v[128:131], v[158:161], v[124:127]
	v_mfma_f32_16x16x32_bf16 v[92:95], v[150:153], v[158:161], v[92:95]
	v_mfma_f32_16x16x32_bf16 v[120:123], v[128:131], v[172:175], v[120:123]
	v_mfma_f32_16x16x32_bf16 v[88:91], v[150:153], v[172:175], v[88:91]
	v_mfma_f32_16x16x32_bf16 v[116:119], v[128:131], v[180:183], v[116:119]
	v_mfma_f32_16x16x32_bf16 v[84:87], v[150:153], v[180:183], v[84:87]
	v_mfma_f32_16x16x32_bf16 v[112:115], v[128:131], v[188:191], v[112:115]
	v_mfma_f32_16x16x32_bf16 v[80:83], v[150:153], v[188:191], v[80:83]
	v_mfma_f32_16x16x32_bf16 v[124:127], v[132:135], v[168:171], v[124:127]
	v_mfma_f32_16x16x32_bf16 v[92:95], v[154:157], v[168:171], v[92:95]
	v_mfma_f32_16x16x32_bf16 v[120:123], v[132:135], v[176:179], v[120:123]
	v_mfma_f32_16x16x32_bf16 v[88:91], v[154:157], v[176:179], v[88:91]
	v_mfma_f32_16x16x32_bf16 v[116:119], v[132:135], v[184:187], v[116:119]
	v_mfma_f32_16x16x32_bf16 v[84:87], v[154:157], v[184:187], v[84:87]
	v_mfma_f32_16x16x32_bf16 v[112:115], v[132:135], v[192:195], v[112:115]
	v_mfma_f32_16x16x32_bf16 v[80:83], v[154:157], v[192:195], v[80:83]
	s_barrier
	s_add_i32 s9, 0, 0x1c000
	s_add_i32 s4, s8, s24
	v_add_u32_e32 v208, s9, v163
	s_mov_b32 m0, s4
	ds_read_b128 v[196:199], v208
	ds_read_b128 v[200:203], v208 offset:1024
	ds_read_b128 v[204:207], v208 offset:2048
	ds_read_b128 v[208:211], v208 offset:3072
	global_load_lds_dwordx4 v140, s[98:99]
	s_add_i32 m0, s4, 0x2000
	s_nop 0
	global_load_lds_dwordx4 v138, s[98:99]
	s_barrier
	s_waitcnt lgkmcnt(0)
	s_waitcnt lgkmcnt(0)
	v_mfma_f32_16x16x32_bf16 v[60:63], v[196:199], v[158:161], v[60:63]
	v_mfma_f32_16x16x32_bf16 v[28:31], v[204:207], v[158:161], v[28:31]
	v_mfma_f32_16x16x32_bf16 v[56:59], v[196:199], v[172:175], v[56:59]
	v_mfma_f32_16x16x32_bf16 v[24:27], v[204:207], v[172:175], v[24:27]
	v_mfma_f32_16x16x32_bf16 v[52:55], v[196:199], v[180:183], v[52:55]
	v_mfma_f32_16x16x32_bf16 v[20:23], v[204:207], v[180:183], v[20:23]
	v_mfma_f32_16x16x32_bf16 v[48:51], v[196:199], v[188:191], v[48:51]
	v_mfma_f32_16x16x32_bf16 v[16:19], v[204:207], v[188:191], v[16:19]
	v_mfma_f32_16x16x32_bf16 v[60:63], v[200:203], v[168:171], v[60:63]
	v_mfma_f32_16x16x32_bf16 v[28:31], v[208:211], v[168:171], v[28:31]
	v_mfma_f32_16x16x32_bf16 v[56:59], v[200:203], v[176:179], v[56:59]
	v_mfma_f32_16x16x32_bf16 v[24:27], v[208:211], v[176:179], v[24:27]
	v_mfma_f32_16x16x32_bf16 v[52:55], v[200:203], v[184:187], v[52:55]
	v_mfma_f32_16x16x32_bf16 v[20:23], v[208:211], v[184:187], v[20:23]
	v_mfma_f32_16x16x32_bf16 v[48:51], v[200:203], v[192:195], v[48:51]
	v_mfma_f32_16x16x32_bf16 v[16:19], v[208:211], v[192:195], v[16:19]
	s_mov_b32 m0, s37
	s_barrier
	ds_read_b128 v[158:161], v166 offset:49152
	ds_read_b128 v[168:171], v166 offset:50176
	ds_read_b128 v[172:175], v166 offset:51200
	ds_read_b128 v[176:179], v166 offset:52224
	ds_read_b128 v[180:183], v166 offset:53248
	ds_read_b128 v[184:187], v166 offset:54272
	ds_read_b128 v[188:191], v166 offset:55296
	ds_read_b128 v[192:195], v166 offset:56320
	global_load_lds_dwordx4 v140, s[100:101]
	s_mov_b32 m0, s40
	s_nop 0
	global_load_lds_dwordx4 v138, s[100:101]
	s_barrier
	s_waitcnt lgkmcnt(0)
	s_waitcnt lgkmcnt(0)
	v_mfma_f32_16x16x32_bf16 v[108:111], v[128:131], v[158:161], v[108:111]
	v_mfma_f32_16x16x32_bf16 v[76:79], v[150:153], v[158:161], v[76:79]
	v_mfma_f32_16x16x32_bf16 v[104:107], v[128:131], v[172:175], v[104:107]
	v_mfma_f32_16x16x32_bf16 v[72:75], v[150:153], v[172:175], v[72:75]
	v_mfma_f32_16x16x32_bf16 v[100:103], v[128:131], v[180:183], v[100:103]
	v_mfma_f32_16x16x32_bf16 v[68:71], v[150:153], v[180:183], v[68:71]
	v_mfma_f32_16x16x32_bf16 v[96:99], v[128:131], v[188:191], v[96:99]
	v_mfma_f32_16x16x32_bf16 v[64:67], v[150:153], v[188:191], v[64:67]
	v_mfma_f32_16x16x32_bf16 v[108:111], v[132:135], v[168:171], v[108:111]
	v_mfma_f32_16x16x32_bf16 v[76:79], v[154:157], v[168:171], v[76:79]
	v_mfma_f32_16x16x32_bf16 v[104:107], v[132:135], v[176:179], v[104:107]
	v_mfma_f32_16x16x32_bf16 v[72:75], v[154:157], v[176:179], v[72:75]
	v_mfma_f32_16x16x32_bf16 v[100:103], v[132:135], v[184:187], v[100:103]
	v_mfma_f32_16x16x32_bf16 v[68:71], v[154:157], v[184:187], v[68:71]
	v_mfma_f32_16x16x32_bf16 v[96:99], v[132:135], v[192:195], v[96:99]
	v_mfma_f32_16x16x32_bf16 v[64:67], v[154:157], v[192:195], v[64:67]
	s_barrier
	s_add_u32 s4, s70, 0x80080
	s_addc_u32 s5, s71, 0
	s_add_i32 s8, s9, s24
	s_mov_b32 m0, s8
	s_nop 0
	global_load_lds_dwordx4 v140, s[4:5]
	s_add_i32 m0, s8, 0x2000
	s_nop 0
	global_load_lds_dwordx4 v138, s[4:5]
	s_waitcnt vmcnt(6)
	s_barrier
	v_mfma_f32_16x16x32_bf16 v[44:47], v[196:199], v[158:161], v[44:47]
	v_mfma_f32_16x16x32_bf16 v[12:15], v[204:207], v[158:161], v[12:15]
	v_mfma_f32_16x16x32_bf16 v[40:43], v[196:199], v[172:175], v[40:43]
	v_mfma_f32_16x16x32_bf16 v[8:11], v[204:207], v[172:175], v[8:11]
	v_mfma_f32_16x16x32_bf16 v[36:39], v[196:199], v[180:183], v[36:39]
	v_mfma_f32_16x16x32_bf16 v[4:7], v[204:207], v[180:183], v[4:7]
	v_mfma_f32_16x16x32_bf16 v[32:35], v[196:199], v[188:191], v[32:35]
	v_mfma_f32_16x16x32_bf16 v[0:3], v[204:207], v[188:191], v[0:3]
	v_mfma_f32_16x16x32_bf16 v[44:47], v[200:203], v[168:171], v[44:47]
	v_mfma_f32_16x16x32_bf16 v[12:15], v[208:211], v[168:171], v[12:15]
	v_mfma_f32_16x16x32_bf16 v[40:43], v[200:203], v[176:179], v[40:43]
	v_mfma_f32_16x16x32_bf16 v[8:11], v[208:211], v[176:179], v[8:11]
	v_mfma_f32_16x16x32_bf16 v[36:39], v[200:203], v[184:187], v[36:39]
	v_mfma_f32_16x16x32_bf16 v[4:7], v[208:211], v[184:187], v[4:7]
	v_mfma_f32_16x16x32_bf16 v[32:35], v[200:203], v[192:195], v[32:35]
	v_mfma_f32_16x16x32_bf16 v[0:3], v[208:211], v[192:195], v[0:3]
	s_add_i32 s78, s78, 2
	s_add_u32 s76, s76, 0x100
	s_addc_u32 s77, s77, 0
	s_cmp_gt_u32 s78, 29
	s_mov_b64 s[8:9], s[68:69]
	s_barrier
	s_cbranch_scc0 .LBB0_1533
	v_lshl_or_b32 v160, s75, 8, v164
	v_ashrrev_i32_e32 v161, 31, v160
	v_lshl_add_u64 v[128:129], v[160:161], 2, s[14:15]
	global_load_dwordx4 v[130:133], v[128:129], off
	v_cndmask_b32_e64 v129, 0, 1, s[18:19]
	v_mov_b32_e32 v128, 0
	v_cmp_ne_u32_e64 s[8:9], 1, v129
	s_andn2_b64 vcc, exec, s[18:19]
	v_lshl_add_u64 v[158:159], v[160:161], 2, s[10:11]
	v_mov_b32_e32 v134, 0
	v_mov_b32_e32 v135, 0
	v_mov_b32_e32 v136, 0
	v_mov_b32_e32 v137, 0
	s_cbranch_vccnz .LBB0_1536
	flat_load_dwordx4 v[134:137], v[158:159]

.LBB0_1676:
	ds_read_b128 v[150:153], v147
	ds_read_b128 v[154:157], v147 offset:1024
	ds_read_b128 v[158:161], v147 offset:2048
	ds_read_b128 v[162:165], v147 offset:3072
	s_add_u32 s4, s20, 0xfff80080
	s_addc_u32 s5, s21, -1
	s_cmp_eq_u32 s53, 28
	s_cselect_b32 s5, s0, s5
	s_cselect_b32 s4, s1, s4
	s_cselect_b32 s45, s11, s52
	s_cselect_b32 s44, s13, s51
	s_add_i32 m0, s19, 0xc000
	ds_read_b128 v[166:169], v148
	ds_read_b128 v[170:173], v148 offset:1024
	ds_read_b128 v[174:177], v148 offset:2048
	ds_read_b128 v[178:181], v148 offset:3072
	ds_read_b128 v[182:185], v148 offset:4096
	ds_read_b128 v[186:189], v148 offset:5120
	ds_read_b128 v[190:193], v148 offset:6144
	ds_read_b128 v[194:197], v148 offset:7168
	global_load_lds_dwordx4 v136, s[20:21]
	s_add_i32 m0, s19, 0xe000
	s_nop 0
	global_load_lds_dwordx4 v138, s[20:21]
	s_waitcnt lgkmcnt(8)
	s_barrier
	s_waitcnt lgkmcnt(0)
	s_waitcnt lgkmcnt(0)
	v_mfma_f32_16x16x32_bf16 v[124:127], v[150:153], v[166:169], v[124:127]
	v_mfma_f32_16x16x32_bf16 v[120:123], v[158:161], v[166:169], v[120:123]
	v_mfma_f32_16x16x32_bf16 v[108:111], v[150:153], v[174:177], v[108:111]
	v_mfma_f32_16x16x32_bf16 v[104:107], v[158:161], v[174:177], v[104:107]
	v_mfma_f32_16x16x32_bf16 v[92:95], v[150:153], v[182:185], v[92:95]
	v_mfma_f32_16x16x32_bf16 v[88:91], v[158:161], v[182:185], v[88:91]
	v_mfma_f32_16x16x32_bf16 v[76:79], v[150:153], v[190:193], v[76:79]
	v_mfma_f32_16x16x32_bf16 v[72:75], v[158:161], v[190:193], v[72:75]
	v_mfma_f32_16x16x32_bf16 v[124:127], v[154:157], v[170:173], v[124:127]
	v_mfma_f32_16x16x32_bf16 v[120:123], v[162:165], v[170:173], v[120:123]
	v_mfma_f32_16x16x32_bf16 v[108:111], v[154:157], v[178:181], v[108:111]
	v_mfma_f32_16x16x32_bf16 v[104:107], v[162:165], v[178:181], v[104:107]
	v_mfma_f32_16x16x32_bf16 v[92:95], v[154:157], v[186:189], v[92:95]
	v_mfma_f32_16x16x32_bf16 v[88:91], v[162:165], v[186:189], v[88:91]
	v_mfma_f32_16x16x32_bf16 v[76:79], v[154:157], v[194:197], v[76:79]
	v_mfma_f32_16x16x32_bf16 v[72:75], v[162:165], v[194:197], v[72:75]
	s_barrier
	s_add_i32 s42, s41, s24
	s_add_u32 s98, s44, s8
	s_addc_u32 s99, s45, s9
	s_mov_b32 m0, s42
	ds_read_b128 v[198:201], v149
	ds_read_b128 v[202:205], v149 offset:1024
	ds_read_b128 v[206:209], v149 offset:2048
	ds_read_b128 v[210:213], v149 offset:3072
	global_load_lds_dwordx4 v132, s[44:45]
	s_add_i32 m0, s42, 0x2000
	s_nop 0
	global_load_lds_dwordx4 v128, s[44:45]
	s_barrier
	s_waitcnt lgkmcnt(0)
	s_waitcnt lgkmcnt(0)
	v_mfma_f32_16x16x32_bf16 v[116:119], v[198:201], v[166:169], v[116:119]
	v_mfma_f32_16x16x32_bf16 v[112:115], v[206:209], v[166:169], v[112:115]
	v_mfma_f32_16x16x32_bf16 v[100:103], v[198:201], v[174:177], v[100:103]
	v_mfma_f32_16x16x32_bf16 v[96:99], v[206:209], v[174:177], v[96:99]
	v_mfma_f32_16x16x32_bf16 v[84:87], v[198:201], v[182:185], v[84:87]
	v_mfma_f32_16x16x32_bf16 v[80:83], v[206:209], v[182:185], v[80:83]
	v_mfma_f32_16x16x32_bf16 v[68:71], v[198:201], v[190:193], v[68:71]
	v_mfma_f32_16x16x32_bf16 v[64:67], v[206:209], v[190:193], v[64:67]
	v_mfma_f32_16x16x32_bf16 v[116:119], v[202:205], v[170:173], v[116:119]
	v_mfma_f32_16x16x32_bf16 v[112:115], v[210:213], v[170:173], v[112:115]
	v_mfma_f32_16x16x32_bf16 v[100:103], v[202:205], v[178:181], v[100:103]
	v_mfma_f32_16x16x32_bf16 v[96:99], v[210:213], v[178:181], v[96:99]
	v_mfma_f32_16x16x32_bf16 v[84:87], v[202:205], v[186:189], v[84:87]
	v_mfma_f32_16x16x32_bf16 v[80:83], v[210:213], v[186:189], v[80:83]
	v_mfma_f32_16x16x32_bf16 v[68:71], v[202:205], v[194:197], v[68:71]
	v_mfma_f32_16x16x32_bf16 v[64:67], v[210:213], v[194:197], v[64:67]
	s_mov_b32 m0, s19
	s_add_u32 s100, s4, s8
	s_addc_u32 s101, s5, s9
	s_barrier
	ds_read_b128 v[166:169], v148 offset:16384
	ds_read_b128 v[170:173], v148 offset:17408
	ds_read_b128 v[174:177], v148 offset:18432
	ds_read_b128 v[178:181], v148 offset:19456
	ds_read_b128 v[182:185], v148 offset:20480
	ds_read_b128 v[186:189], v148 offset:21504
	ds_read_b128 v[190:193], v148 offset:22528
	ds_read_b128 v[194:197], v148 offset:23552
	global_load_lds_dwordx4 v134, s[4:5]
	s_mov_b32 m0, s28
	s_nop 0
	global_load_lds_dwordx4 v130, s[4:5]
	s_barrier
	s_waitcnt lgkmcnt(0)
	s_waitcnt lgkmcnt(0)
	v_mfma_f32_16x16x32_bf16 v[60:63], v[150:153], v[166:169], v[60:63]
	v_mfma_f32_16x16x32_bf16 v[56:59], v[158:161], v[166:169], v[56:59]
	v_mfma_f32_16x16x32_bf16 v[44:47], v[150:153], v[174:177], v[44:47]
	v_mfma_f32_16x16x32_bf16 v[40:43], v[158:161], v[174:177], v[40:43]
	v_mfma_f32_16x16x32_bf16 v[28:31], v[150:153], v[182:185], v[28:31]
	v_mfma_f32_16x16x32_bf16 v[24:27], v[158:161], v[182:185], v[24:27]
	v_mfma_f32_16x16x32_bf16 v[12:15], v[150:153], v[190:193], v[12:15]
	v_mfma_f32_16x16x32_bf16 v[8:11], v[158:161], v[190:193], v[8:11]
	v_mfma_f32_16x16x32_bf16 v[60:63], v[154:157], v[170:173], v[60:63]
	v_mfma_f32_16x16x32_bf16 v[56:59], v[162:165], v[170:173], v[56:59]
	v_mfma_f32_16x16x32_bf16 v[44:47], v[154:157], v[178:181], v[44:47]
	v_mfma_f32_16x16x32_bf16 v[40:43], v[162:165], v[178:181], v[40:43]
	v_mfma_f32_16x16x32_bf16 v[28:31], v[154:157], v[186:189], v[28:31]
	v_mfma_f32_16x16x32_bf16 v[24:27], v[162:165], v[186:189], v[24:27]
	v_mfma_f32_16x16x32_bf16 v[12:15], v[154:157], v[194:197], v[12:15]
	v_mfma_f32_16x16x32_bf16 v[8:11], v[162:165], v[194:197], v[8:11]
	s_barrier
	s_add_u32 s42, s44, 0x80000
	s_addc_u32 s43, s45, 0
	s_add_i32 s54, s46, s24
	s_mov_b32 m0, s54
	s_nop 0
	global_load_lds_dwordx4 v132, s[42:43]
	s_add_i32 m0, s54, 0x2000
	s_nop 0
	global_load_lds_dwordx4 v128, s[42:43]
	s_waitcnt vmcnt(6)
	s_barrier
	v_mfma_f32_16x16x32_bf16 v[52:55], v[198:201], v[166:169], v[52:55]
	v_mfma_f32_16x16x32_bf16 v[48:51], v[206:209], v[166:169], v[48:51]
	v_mfma_f32_16x16x32_bf16 v[36:39], v[198:201], v[174:177], v[36:39]
	v_mfma_f32_16x16x32_bf16 v[32:35], v[206:209], v[174:177], v[32:35]
	v_mfma_f32_16x16x32_bf16 v[20:23], v[198:201], v[182:185], v[20:23]
	v_mfma_f32_16x16x32_bf16 v[16:19], v[206:209], v[182:185], v[16:19]
	v_mfma_f32_16x16x32_bf16 v[4:7], v[198:201], v[190:193], v[4:7]
	v_mfma_f32_16x16x32_bf16 v[0:3], v[206:209], v[190:193], v[0:3]
	v_mfma_f32_16x16x32_bf16 v[52:55], v[202:205], v[170:173], v[52:55]
	v_mfma_f32_16x16x32_bf16 v[48:51], v[210:213], v[170:173], v[48:51]
	v_mfma_f32_16x16x32_bf16 v[36:39], v[202:205], v[178:181], v[36:39]
	v_mfma_f32_16x16x32_bf16 v[32:35], v[210:213], v[178:181], v[32:35]
	v_mfma_f32_16x16x32_bf16 v[20:23], v[202:205], v[186:189], v[20:23]
	v_mfma_f32_16x16x32_bf16 v[16:19], v[210:213], v[186:189], v[16:19]
	v_mfma_f32_16x16x32_bf16 v[4:7], v[202:205], v[194:197], v[4:7]
	v_mfma_f32_16x16x32_bf16 v[0:3], v[210:213], v[194:197], v[0:3]
	s_add_i32 s42, 0, 0x18000
	v_add_u32_e32 v162, s42, v145
	s_barrier
	ds_read_b128 v[150:153], v162
	ds_read_b128 v[154:157], v162 offset:1024
	ds_read_b128 v[158:161], v162 offset:2048
	ds_read_b128 v[162:165], v162 offset:3072
	s_add_u32 s4, s4, 0x80000
	s_addc_u32 s5, s5, 0
	s_mov_b32 m0, s29
	ds_read_b128 v[166:169], v148 offset:32768
	ds_read_b128 v[170:173], v148 offset:33792
	ds_read_b128 v[174:177], v148 offset:34816
	ds_read_b128 v[178:181], v148 offset:35840
	ds_read_b128 v[182:185], v148 offset:36864
	ds_read_b128 v[186:189], v148 offset:37888
	ds_read_b128 v[190:193], v148 offset:38912
	ds_read_b128 v[194:197], v148 offset:39936
	global_load_lds_dwordx4 v134, s[4:5]
	s_mov_b32 m0, s33
	s_nop 0
	global_load_lds_dwordx4 v130, s[4:5]
	s_waitcnt lgkmcnt(8)
	s_barrier
	s_waitcnt lgkmcnt(0)
	s_waitcnt lgkmcnt(0)
	v_mfma_f32_16x16x32_bf16 v[124:127], v[150:153], v[166:169], v[124:127]
	v_mfma_f32_16x16x32_bf16 v[120:123], v[158:161], v[166:169], v[120:123]
	v_mfma_f32_16x16x32_bf16 v[108:111], v[150:153], v[174:177], v[108:111]
	v_mfma_f32_16x16x32_bf16 v[104:107], v[158:161], v[174:177], v[104:107]
	v_mfma_f32_16x16x32_bf16 v[92:95], v[150:153], v[182:185], v[92:95]
	v_mfma_f32_16x16x32_bf16 v[88:91], v[158:161], v[182:185], v[88:91]
	v_mfma_f32_16x16x32_bf16 v[76:79], v[150:153], v[190:193], v[76:79]
	v_mfma_f32_16x16x32_bf16 v[72:75], v[158:161], v[190:193], v[72:75]
	v_mfma_f32_16x16x32_bf16 v[124:127], v[154:157], v[170:173], v[124:127]
	v_mfma_f32_16x16x32_bf16 v[120:123], v[162:165], v[170:173], v[120:123]
	v_mfma_f32_16x16x32_bf16 v[108:111], v[154:157], v[178:181], v[108:111]
	v_mfma_f32_16x16x32_bf16 v[104:107], v[162:165], v[178:181], v[104:107]
	v_mfma_f32_16x16x32_bf16 v[92:95], v[154:157], v[186:189], v[92:95]
	v_mfma_f32_16x16x32_bf16 v[88:91], v[162:165], v[186:189], v[88:91]
	v_mfma_f32_16x16x32_bf16 v[76:79], v[154:157], v[194:197], v[76:79]
	v_mfma_f32_16x16x32_bf16 v[72:75], v[162:165], v[194:197], v[72:75]
	s_barrier
	s_add_i32 s43, 0, 0x1c000
	s_add_i32 s4, s42, s24
	v_add_u32_e32 v210, s43, v145
	s_mov_b32 m0, s4
	ds_read_b128 v[198:201], v210
	ds_read_b128 v[202:205], v210 offset:1024
	ds_read_b128 v[206:209], v210 offset:2048
	ds_read_b128 v[210:213], v210 offset:3072
	global_load_lds_dwordx4 v132, s[98:99]
	s_add_i32 m0, s4, 0x2000
	s_nop 0
	global_load_lds_dwordx4 v128, s[98:99]
	s_barrier
	s_waitcnt lgkmcnt(0)
	s_waitcnt lgkmcnt(0)
	v_mfma_f32_16x16x32_bf16 v[116:119], v[198:201], v[166:169], v[116:119]
	v_mfma_f32_16x16x32_bf16 v[112:115], v[206:209], v[166:169], v[112:115]
	v_mfma_f32_16x16x32_bf16 v[100:103], v[198:201], v[174:177], v[100:103]
	v_mfma_f32_16x16x32_bf16 v[96:99], v[206:209], v[174:177], v[96:99]
	v_mfma_f32_16x16x32_bf16 v[84:87], v[198:201], v[182:185], v[84:87]
	v_mfma_f32_16x16x32_bf16 v[80:83], v[206:209], v[182:185], v[80:83]
	v_mfma_f32_16x16x32_bf16 v[68:71], v[198:201], v[190:193], v[68:71]
	v_mfma_f32_16x16x32_bf16 v[64:67], v[206:209], v[190:193], v[64:67]
	v_mfma_f32_16x16x32_bf16 v[116:119], v[202:205], v[170:173], v[116:119]
	v_mfma_f32_16x16x32_bf16 v[112:115], v[210:213], v[170:173], v[112:115]
	v_mfma_f32_16x16x32_bf16 v[100:103], v[202:205], v[178:181], v[100:103]
	v_mfma_f32_16x16x32_bf16 v[96:99], v[210:213], v[178:181], v[96:99]
	v_mfma_f32_16x16x32_bf16 v[84:87], v[202:205], v[186:189], v[84:87]
	v_mfma_f32_16x16x32_bf16 v[80:83], v[210:213], v[186:189], v[80:83]
	v_mfma_f32_16x16x32_bf16 v[68:71], v[202:205], v[194:197], v[68:71]
	v_mfma_f32_16x16x32_bf16 v[64:67], v[210:213], v[194:197], v[64:67]
	s_mov_b32 m0, s37
	s_barrier
	ds_read_b128 v[166:169], v148 offset:49152
	ds_read_b128 v[170:173], v148 offset:50176
	ds_read_b128 v[174:177], v148 offset:51200
	ds_read_b128 v[178:181], v148 offset:52224
	ds_read_b128 v[182:185], v148 offset:53248
	ds_read_b128 v[186:189], v148 offset:54272
	ds_read_b128 v[190:193], v148 offset:55296
	ds_read_b128 v[194:197], v148 offset:56320
	global_load_lds_dwordx4 v134, s[100:101]
	s_mov_b32 m0, s40
	s_nop 0
	global_load_lds_dwordx4 v130, s[100:101]
	s_barrier
	s_waitcnt lgkmcnt(0)
	s_waitcnt lgkmcnt(0)
	v_mfma_f32_16x16x32_bf16 v[60:63], v[150:153], v[166:169], v[60:63]
	v_mfma_f32_16x16x32_bf16 v[56:59], v[158:161], v[166:169], v[56:59]
	v_mfma_f32_16x16x32_bf16 v[44:47], v[150:153], v[174:177], v[44:47]
	v_mfma_f32_16x16x32_bf16 v[40:43], v[158:161], v[174:177], v[40:43]
	v_mfma_f32_16x16x32_bf16 v[28:31], v[150:153], v[182:185], v[28:31]
	v_mfma_f32_16x16x32_bf16 v[24:27], v[158:161], v[182:185], v[24:27]
	v_mfma_f32_16x16x32_bf16 v[12:15], v[150:153], v[190:193], v[12:15]
	v_mfma_f32_16x16x32_bf16 v[8:11], v[158:161], v[190:193], v[8:11]
	v_mfma_f32_16x16x32_bf16 v[60:63], v[154:157], v[170:173], v[60:63]
	v_mfma_f32_16x16x32_bf16 v[56:59], v[162:165], v[170:173], v[56:59]
	v_mfma_f32_16x16x32_bf16 v[44:47], v[154:157], v[178:181], v[44:47]
	v_mfma_f32_16x16x32_bf16 v[40:43], v[162:165], v[178:181], v[40:43]
	v_mfma_f32_16x16x32_bf16 v[28:31], v[154:157], v[186:189], v[28:31]
	v_mfma_f32_16x16x32_bf16 v[24:27], v[162:165], v[186:189], v[24:27]
	v_mfma_f32_16x16x32_bf16 v[12:15], v[154:157], v[194:197], v[12:15]
	v_mfma_f32_16x16x32_bf16 v[8:11], v[162:165], v[194:197], v[8:11]
	s_barrier
	s_add_u32 s4, s44, 0x80080
	s_addc_u32 s5, s45, 0
	s_add_i32 s42, s43, s24
	s_mov_b32 m0, s42
	s_nop 0
	global_load_lds_dwordx4 v132, s[4:5]
	s_add_i32 m0, s42, 0x2000
	s_nop 0
	global_load_lds_dwordx4 v128, s[4:5]
	s_waitcnt vmcnt(6)
	s_barrier
	v_mfma_f32_16x16x32_bf16 v[52:55], v[198:201], v[166:169], v[52:55]
	v_mfma_f32_16x16x32_bf16 v[48:51], v[206:209], v[166:169], v[48:51]
	v_mfma_f32_16x16x32_bf16 v[36:39], v[198:201], v[174:177], v[36:39]
	v_mfma_f32_16x16x32_bf16 v[32:35], v[206:209], v[174:177], v[32:35]
	v_mfma_f32_16x16x32_bf16 v[20:23], v[198:201], v[182:185], v[20:23]
	v_mfma_f32_16x16x32_bf16 v[16:19], v[206:209], v[182:185], v[16:19]
	v_mfma_f32_16x16x32_bf16 v[4:7], v[198:201], v[190:193], v[4:7]
	v_mfma_f32_16x16x32_bf16 v[0:3], v[206:209], v[190:193], v[0:3]
	v_mfma_f32_16x16x32_bf16 v[52:55], v[202:205], v[170:173], v[52:55]
	v_mfma_f32_16x16x32_bf16 v[48:51], v[210:213], v[170:173], v[48:51]
	v_mfma_f32_16x16x32_bf16 v[36:39], v[202:205], v[178:181], v[36:39]
	v_mfma_f32_16x16x32_bf16 v[32:35], v[210:213], v[178:181], v[32:35]
	v_mfma_f32_16x16x32_bf16 v[20:23], v[202:205], v[186:189], v[20:23]
	v_mfma_f32_16x16x32_bf16 v[16:19], v[210:213], v[186:189], v[16:19]
	v_mfma_f32_16x16x32_bf16 v[4:7], v[202:205], v[194:197], v[4:7]
	v_mfma_f32_16x16x32_bf16 v[0:3], v[210:213], v[194:197], v[0:3]
	s_add_i32 s53, s53, 2
	s_add_u32 s20, s20, 0x100
	s_addc_u32 s21, s21, 0
	s_add_u32 s51, s51, 0x100
	s_addc_u32 s52, s52, 0
	s_cmp_gt_u32 s53, 29
	s_barrier
	s_cbranch_scc0 .LBB0_1676
	v_mul_f32_e32 v151, 0xbfb8aa3b, v124
	v_exp_f32_e32 v151, v151
	v_mul_f32_e32 v152, 0xbfb8aa3b, v120
	v_exp_f32_e32 v153, v152
	v_lshl_or_b32 v152, s50, 7, v146
	v_add_f32_e32 v151, 1.0, v151
	v_rcp_f32_e32 v151, v151
	v_add_f32_e32 v153, 1.0, v153
	v_rcp_f32_e32 v154, v153
	v_lshl_add_u32 v150, s18, 8, v144
	v_mul_f32_e32 v124, v124, v151
	v_mul_f32_e32 v116, v124, v116
	v_mul_f32_e32 v124, 0xbfb8aa3b, v125
	v_exp_f32_e32 v124, v124
	v_mul_f32_e32 v151, 0xbfb8aa3b, v121
	v_exp_f32_e32 v151, v151
	v_mul_f32_e32 v120, v120, v154
	v_mul_f32_e32 v112, v120, v112
	v_add_f32_e32 v120, 1.0, v124
	v_rcp_f32_e32 v120, v120
	v_add_f32_e32 v124, 1.0, v151
	v_mul_f32_e32 v151, 0xbfb8aa3b, v126
	v_rcp_f32_e32 v124, v124
	v_exp_f32_e32 v151, v151
	v_mul_f32_e32 v120, v125, v120
	v_mul_f32_e32 v117, v120, v117
	v_mul_f32_e32 v120, v121, v124
	v_add_f32_e32 v121, 1.0, v151
	v_rcp_f32_e32 v121, v121
	v_mul_f32_e32 v124, 0xbfb8aa3b, v122
	v_exp_f32_e32 v124, v124
	v_mul_f32_e32 v113, v120, v113
	v_mul_f32_e32 v120, v126, v121
	v_mul_f32_e32 v121, 0xbfb8aa3b, v127
	v_mul_f32_e32 v118, v120, v118
	v_add_f32_e32 v120, 1.0, v124
	v_exp_f32_e32 v121, v121
	v_mul_f32_e32 v124, 0xbfb8aa3b, v123
	v_rcp_f32_e32 v120, v120
	v_exp_f32_e32 v124, v124
	v_add_f32_e32 v121, 1.0, v121
	v_rcp_f32_e32 v121, v121
	v_mul_f32_e32 v120, v122, v120
	v_add_f32_e32 v122, 1.0, v124
	v_rcp_f32_e32 v122, v122
	v_mul_f32_e32 v114, v120, v114
	v_mul_f32_e32 v120, v127, v121
	v_mul_f32_e32 v119, v120, v119
	v_mul_f32_e32 v120, v123, v122
	v_mul_f32_e32 v122, 0xbfb8aa3b, v108
	v_exp_f32_e32 v122, v122
	v_mul_f32_e32 v123, 0xbfb8aa3b, v104
	v_exp_f32_e32 v123, v123
	v_ashrrev_i32_e32 v153, 31, v152
	v_add_f32_e32 v122, 1.0, v122
	v_rcp_f32_e32 v122, v122
	v_mul_f32_e32 v115, v120, v115
	s_nop 1
	v_cvt_pk_bf16_f32 v116, v116, v117
	s_nop 1
	v_cvt_pk_bf16_f32 v117, v118, v119
	s_nop 1
	v_cvt_pk_bf16_f32 v118, v112, v113
	v_mov_b64_e32 v[112:113], s[48:49]
	s_nop 1
	v_cvt_pk_bf16_f32 v119, v114, v115
	v_mad_i64_i32 v[120:121], s[0:1], v150, s47, v[112:113]
	v_lshlrev_b64 v[114:115], 1, v[152:153]
	v_add_f32_e32 v123, 1.0, v123
	v_mul_f32_e32 v108, v108, v122
	v_lshl_add_u64 v[120:121], v[120:121], 0, v[114:115]
	v_rcp_f32_e32 v123, v123
	v_mul_f32_e32 v100, v108, v100
	v_mul_f32_e32 v108, 0xbfb8aa3b, v109
	global_store_dwordx4 v[120:121], v[116:119], off
	v_exp_f32_e32 v108, v108
	v_mul_f32_e32 v104, v104, v123
	v_mul_f32_e32 v116, 0xbfb8aa3b, v105
	v_exp_f32_e32 v116, v116
	v_mul_f32_e32 v104, v104, v96
	v_add_f32_e32 v96, 1.0, v108
	v_rcp_f32_e32 v96, v96
	v_add_f32_e32 v108, 1.0, v116
	v_mul_f32_e32 v116, 0xbfb8aa3b, v110
	v_rcp_f32_e32 v108, v108
	v_exp_f32_e32 v116, v116
	v_mul_f32_e32 v96, v109, v96
	v_mul_f32_e32 v96, v96, v101
	v_mul_f32_e32 v101, v105, v108
	v_add_f32_e32 v105, 1.0, v116
	v_rcp_f32_e32 v105, v105
	v_mul_f32_e32 v108, 0xbfb8aa3b, v106
	v_exp_f32_e32 v108, v108
	v_mul_f32_e32 v101, v101, v97
	v_mul_f32_e32 v97, v110, v105
	v_mul_f32_e32 v105, 0xbfb8aa3b, v111
	v_mul_f32_e32 v97, v97, v102
	v_add_f32_e32 v102, 1.0, v108
	v_exp_f32_e32 v105, v105
	v_mul_f32_e32 v108, 0xbfb8aa3b, v107
	v_rcp_f32_e32 v102, v102
	v_exp_f32_e32 v108, v108
	v_add_f32_e32 v105, 1.0, v105
	v_rcp_f32_e32 v105, v105
	v_mul_f32_e32 v102, v106, v102
	v_add_f32_e32 v106, 1.0, v108
	v_rcp_f32_e32 v106, v106
	v_mul_f32_e32 v102, v102, v98
	v_mul_f32_e32 v98, v111, v105
	v_mul_f32_e32 v98, v98, v103
	v_mul_f32_e32 v103, v107, v106
	v_mul_f32_e32 v99, v103, v99
	s_nop 1
	v_cvt_pk_bf16_f32 v96, v100, v96
	s_nop 1
	v_cvt_pk_bf16_f32 v97, v97, v98
	s_nop 1
	v_cvt_pk_bf16_f32 v98, v104, v101
	s_nop 1
	v_cvt_pk_bf16_f32 v99, v102, v99
	v_mul_f32_e32 v102, 0xbfb8aa3b, v92
	v_exp_f32_e32 v102, v102
	v_mul_f32_e32 v103, 0xbfb8aa3b, v88
	v_exp_f32_e32 v103, v103
	v_or_b32_e32 v100, 16, v150
	v_add_f32_e32 v102, 1.0, v102
	v_rcp_f32_e32 v102, v102
	v_mad_i64_i32 v[100:101], s[0:1], v100, s47, v[112:113]
	v_add_f32_e32 v103, 1.0, v103
	v_mul_f32_e32 v92, v92, v102
	v_lshl_add_u64 v[100:101], v[100:101], 0, v[114:115]
	v_rcp_f32_e32 v103, v103
	v_mul_f32_e32 v84, v92, v84
	v_mul_f32_e32 v92, 0xbfb8aa3b, v93
	global_store_dwordx4 v[100:101], v[96:99], off
	v_exp_f32_e32 v92, v92
	v_mul_f32_e32 v88, v88, v103
	v_mul_f32_e32 v96, 0xbfb8aa3b, v89
	v_exp_f32_e32 v96, v96
	v_mul_f32_e32 v88, v88, v80
	v_add_f32_e32 v80, 1.0, v92
	v_rcp_f32_e32 v80, v80
	v_add_f32_e32 v92, 1.0, v96
	v_mul_f32_e32 v96, 0xbfb8aa3b, v94
	v_rcp_f32_e32 v92, v92
	v_exp_f32_e32 v96, v96
	v_mul_f32_e32 v80, v93, v80
	v_mul_f32_e32 v80, v80, v85
	v_mul_f32_e32 v85, v89, v92
	v_add_f32_e32 v89, 1.0, v96
	v_rcp_f32_e32 v89, v89
	v_mul_f32_e32 v92, 0xbfb8aa3b, v90
	v_exp_f32_e32 v92, v92
	v_mul_f32_e32 v85, v85, v81
	v_mul_f32_e32 v81, v94, v89
	v_mul_f32_e32 v89, 0xbfb8aa3b, v95
	v_mul_f32_e32 v81, v81, v86
	v_add_f32_e32 v86, 1.0, v92
	v_exp_f32_e32 v89, v89
	v_mul_f32_e32 v92, 0xbfb8aa3b, v91
	v_rcp_f32_e32 v86, v86
	v_exp_f32_e32 v92, v92
	v_add_f32_e32 v89, 1.0, v89
	v_rcp_f32_e32 v89, v89
	v_mul_f32_e32 v86, v90, v86
	v_add_f32_e32 v90, 1.0, v92
	v_rcp_f32_e32 v90, v90
	v_mul_f32_e32 v86, v86, v82
	v_mul_f32_e32 v82, v95, v89
	v_mul_f32_e32 v82, v82, v87
	v_mul_f32_e32 v87, v91, v90
	v_mul_f32_e32 v83, v87, v83
	s_nop 1
	v_cvt_pk_bf16_f32 v80, v84, v80
	s_nop 1
	v_cvt_pk_bf16_f32 v81, v81, v82
	s_nop 1
	v_cvt_pk_bf16_f32 v82, v88, v85
	s_nop 1
	v_cvt_pk_bf16_f32 v83, v86, v83
	v_mul_f32_e32 v86, 0xbfb8aa3b, v76
	v_exp_f32_e32 v86, v86
	v_mul_f32_e32 v87, 0xbfb8aa3b, v72
	v_exp_f32_e32 v87, v87
	v_or_b32_e32 v84, 32, v150
	v_add_f32_e32 v86, 1.0, v86
	v_rcp_f32_e32 v86, v86
	v_mad_i64_i32 v[84:85], s[0:1], v84, s47, v[112:113]
	v_add_f32_e32 v87, 1.0, v87
	v_mul_f32_e32 v76, v76, v86
	v_lshl_add_u64 v[84:85], v[84:85], 0, v[114:115]
	v_rcp_f32_e32 v87, v87
	v_mul_f32_e32 v68, v76, v68
	v_mul_f32_e32 v76, 0xbfb8aa3b, v77
	global_store_dwordx4 v[84:85], v[80:83], off
	v_exp_f32_e32 v76, v76
	v_mul_f32_e32 v72, v72, v87
	v_mul_f32_e32 v80, 0xbfb8aa3b, v73
	v_exp_f32_e32 v80, v80
	v_mul_f32_e32 v72, v72, v64
	v_add_f32_e32 v64, 1.0, v76
	v_rcp_f32_e32 v64, v64
	v_add_f32_e32 v76, 1.0, v80
	v_mul_f32_e32 v80, 0xbfb8aa3b, v78
	v_rcp_f32_e32 v76, v76
	v_exp_f32_e32 v80, v80
	v_mul_f32_e32 v64, v77, v64
	v_mul_f32_e32 v64, v64, v69
	v_mul_f32_e32 v69, v73, v76
	v_add_f32_e32 v73, 1.0, v80
	v_rcp_f32_e32 v73, v73
	v_mul_f32_e32 v76, 0xbfb8aa3b, v74
	v_exp_f32_e32 v76, v76
	v_mul_f32_e32 v69, v69, v65
	v_mul_f32_e32 v65, v78, v73
	v_mul_f32_e32 v73, 0xbfb8aa3b, v79
	v_mul_f32_e32 v65, v65, v70
	v_add_f32_e32 v70, 1.0, v76
	v_exp_f32_e32 v73, v73
	v_mul_f32_e32 v76, 0xbfb8aa3b, v75
	v_rcp_f32_e32 v70, v70
	v_exp_f32_e32 v76, v76
	v_add_f32_e32 v73, 1.0, v73
	v_rcp_f32_e32 v73, v73
	v_mul_f32_e32 v70, v74, v70
	v_add_f32_e32 v74, 1.0, v76
	v_rcp_f32_e32 v74, v74
	v_mul_f32_e32 v70, v70, v66
	v_mul_f32_e32 v66, v79, v73
	v_mul_f32_e32 v66, v66, v71
	v_mul_f32_e32 v71, v75, v74
	v_mul_f32_e32 v67, v71, v67
	s_nop 1
	v_cvt_pk_bf16_f32 v64, v68, v64
	s_nop 1
	v_cvt_pk_bf16_f32 v65, v65, v66
	s_nop 1
	v_cvt_pk_bf16_f32 v66, v72, v69
	s_nop 1
	v_cvt_pk_bf16_f32 v67, v70, v67
	v_mul_f32_e32 v70, 0xbfb8aa3b, v60
	v_exp_f32_e32 v70, v70
	v_or_b32_e32 v68, 48, v150
	v_mad_i64_i32 v[68:69], s[0:1], v68, s47, v[112:113]
	v_lshl_add_u64 v[68:69], v[68:69], 0, v[114:115]
	v_mul_f32_e32 v71, 0xbfb8aa3b, v56
	global_store_dwordx4 v[68:69], v[64:67], off
	v_exp_f32_e32 v71, v71
	s_and_b64 vcc, exec, s[6:7]
	v_add_f32_e32 v64, 1.0, v70
	v_rcp_f32_e32 v64, v64
	v_add_f32_e32 v65, 1.0, v71
	v_rcp_f32_e32 v65, v65
	v_add_u32_e32 v66, 0x80, v150
	v_mul_f32_e32 v60, v60, v64
	v_mul_f32_e32 v52, v60, v52
	v_mul_f32_e32 v60, 0xbfb8aa3b, v61
	v_exp_f32_e32 v60, v60
	v_mul_f32_e32 v64, 0xbfb8aa3b, v57
	v_exp_f32_e32 v64, v64
	v_mul_f32_e32 v56, v56, v65
	v_mul_f32_e32 v56, v56, v48
	v_add_f32_e32 v48, 1.0, v60
	v_rcp_f32_e32 v48, v48
	v_add_f32_e32 v60, 1.0, v64
	v_mul_f32_e32 v64, 0xbfb8aa3b, v62
	v_rcp_f32_e32 v60, v60
	v_exp_f32_e32 v64, v64
	v_mul_f32_e32 v48, v61, v48
	v_mul_f32_e32 v48, v48, v53
	v_mul_f32_e32 v53, v57, v60
	v_add_f32_e32 v57, 1.0, v64
	v_rcp_f32_e32 v57, v57
	v_mul_f32_e32 v60, 0xbfb8aa3b, v58
	v_exp_f32_e32 v60, v60
	v_mul_f32_e32 v53, v53, v49
	v_mul_f32_e32 v49, v62, v57
	v_mul_f32_e32 v57, 0xbfb8aa3b, v63
	v_mul_f32_e32 v49, v49, v54
	v_add_f32_e32 v54, 1.0, v60
	v_exp_f32_e32 v57, v57
	v_mul_f32_e32 v60, 0xbfb8aa3b, v59
	v_rcp_f32_e32 v54, v54
	v_exp_f32_e32 v60, v60
	v_add_f32_e32 v57, 1.0, v57
	v_rcp_f32_e32 v57, v57
	v_mul_f32_e32 v54, v58, v54
	v_add_f32_e32 v58, 1.0, v60
	v_rcp_f32_e32 v58, v58
	v_mul_f32_e32 v54, v54, v50
	v_mul_f32_e32 v50, v63, v57
	v_mul_f32_e32 v50, v50, v55
	v_mul_f32_e32 v55, v59, v58
	v_mul_f32_e32 v51, v55, v51
	s_nop 1
	v_cvt_pk_bf16_f32 v48, v52, v48
	s_nop 1
	v_cvt_pk_bf16_f32 v49, v49, v50
	s_nop 1
	v_cvt_pk_bf16_f32 v50, v56, v53
	s_nop 1
	v_cvt_pk_bf16_f32 v51, v54, v51
	v_mul_f32_e32 v54, 0xbfb8aa3b, v44
	v_exp_f32_e32 v54, v54
	v_mul_f32_e32 v55, 0xbfb8aa3b, v40
	v_exp_f32_e32 v55, v55
	v_mad_i64_i32 v[52:53], s[0:1], v66, s47, v[112:113]
	v_add_f32_e32 v54, 1.0, v54
	v_rcp_f32_e32 v54, v54
	v_add_f32_e32 v55, 1.0, v55
	v_lshl_add_u64 v[52:53], v[52:53], 0, v[114:115]
	v_rcp_f32_e32 v55, v55
	v_mul_f32_e32 v44, v44, v54
	v_mul_f32_e32 v36, v44, v36
	v_mul_f32_e32 v44, 0xbfb8aa3b, v45
	global_store_dwordx4 v[52:53], v[48:51], off
	v_exp_f32_e32 v44, v44
	v_mul_f32_e32 v40, v40, v55
	v_mul_f32_e32 v48, 0xbfb8aa3b, v41
	v_exp_f32_e32 v48, v48
	v_mul_f32_e32 v40, v40, v32
	v_add_f32_e32 v32, 1.0, v44
	v_rcp_f32_e32 v32, v32
	v_add_f32_e32 v44, 1.0, v48
	v_mul_f32_e32 v48, 0xbfb8aa3b, v46
	v_rcp_f32_e32 v44, v44
	v_exp_f32_e32 v48, v48
	v_mul_f32_e32 v32, v45, v32
	v_mul_f32_e32 v32, v32, v37
	v_mul_f32_e32 v37, v41, v44
	v_add_f32_e32 v41, 1.0, v48
	v_rcp_f32_e32 v41, v41
	v_mul_f32_e32 v44, 0xbfb8aa3b, v42
	v_exp_f32_e32 v44, v44
	v_mul_f32_e32 v37, v37, v33
	v_mul_f32_e32 v33, v46, v41
	v_mul_f32_e32 v41, 0xbfb8aa3b, v47
	v_mul_f32_e32 v33, v33, v38
	v_add_f32_e32 v38, 1.0, v44
	v_exp_f32_e32 v41, v41
	v_mul_f32_e32 v44, 0xbfb8aa3b, v43
	v_rcp_f32_e32 v38, v38
	v_exp_f32_e32 v44, v44
	v_add_f32_e32 v41, 1.0, v41
	v_rcp_f32_e32 v41, v41
	v_mul_f32_e32 v38, v42, v38
	v_add_f32_e32 v42, 1.0, v44
	v_rcp_f32_e32 v42, v42
	v_mul_f32_e32 v38, v38, v34
	v_mul_f32_e32 v34, v47, v41
	v_mul_f32_e32 v34, v34, v39
	v_mul_f32_e32 v39, v43, v42
	v_mul_f32_e32 v35, v39, v35
	s_nop 1
	v_cvt_pk_bf16_f32 v32, v36, v32
	s_nop 1
	v_cvt_pk_bf16_f32 v33, v33, v34
	s_nop 1
	v_cvt_pk_bf16_f32 v34, v40, v37
	s_nop 1
	v_cvt_pk_bf16_f32 v35, v38, v35
	v_mul_f32_e32 v38, 0xbfb8aa3b, v28
	v_exp_f32_e32 v38, v38
	v_mul_f32_e32 v39, 0xbfb8aa3b, v24
	v_exp_f32_e32 v39, v39
	v_add_u32_e32 v36, 0x90, v150
	v_add_f32_e32 v38, 1.0, v38
	v_rcp_f32_e32 v38, v38
	v_mad_i64_i32 v[36:37], s[0:1], v36, s47, v[112:113]
	v_add_f32_e32 v39, 1.0, v39
	v_mul_f32_e32 v28, v28, v38
	v_lshl_add_u64 v[36:37], v[36:37], 0, v[114:115]
	v_rcp_f32_e32 v39, v39
	v_mul_f32_e32 v20, v28, v20
	v_mul_f32_e32 v28, 0xbfb8aa3b, v29
	global_store_dwordx4 v[36:37], v[32:35], off
	v_exp_f32_e32 v28, v28
	v_mul_f32_e32 v24, v24, v39
	v_mul_f32_e32 v32, 0xbfb8aa3b, v25
	v_exp_f32_e32 v32, v32
	v_mul_f32_e32 v24, v24, v16
	v_add_f32_e32 v16, 1.0, v28
	v_rcp_f32_e32 v16, v16
	v_add_f32_e32 v28, 1.0, v32
	v_mul_f32_e32 v32, 0xbfb8aa3b, v30
	v_rcp_f32_e32 v28, v28
	v_exp_f32_e32 v32, v32
	v_mul_f32_e32 v16, v29, v16
	v_mul_f32_e32 v16, v16, v21
	v_mul_f32_e32 v21, v25, v28
	v_add_f32_e32 v25, 1.0, v32
	v_rcp_f32_e32 v25, v25
	v_mul_f32_e32 v28, 0xbfb8aa3b, v26
	v_exp_f32_e32 v28, v28
	v_mul_f32_e32 v21, v21, v17
	v_mul_f32_e32 v17, v30, v25
	v_mul_f32_e32 v25, 0xbfb8aa3b, v31
	v_mul_f32_e32 v17, v17, v22
	v_add_f32_e32 v22, 1.0, v28
	v_exp_f32_e32 v25, v25
	v_mul_f32_e32 v28, 0xbfb8aa3b, v27
	v_rcp_f32_e32 v22, v22
	v_exp_f32_e32 v28, v28
	v_add_f32_e32 v25, 1.0, v25
	v_rcp_f32_e32 v25, v25
	v_mul_f32_e32 v22, v26, v22
	v_add_f32_e32 v26, 1.0, v28
	v_rcp_f32_e32 v26, v26
	v_mul_f32_e32 v22, v22, v18
	v_mul_f32_e32 v18, v31, v25
	v_mul_f32_e32 v18, v18, v23
	v_mul_f32_e32 v23, v27, v26
	v_mul_f32_e32 v19, v23, v19
	s_nop 1
	v_cvt_pk_bf16_f32 v16, v20, v16
	s_nop 1
	v_cvt_pk_bf16_f32 v17, v17, v18
	s_nop 1
	v_cvt_pk_bf16_f32 v18, v24, v21
	s_nop 1
	v_cvt_pk_bf16_f32 v19, v22, v19
	v_mul_f32_e32 v22, 0xbfb8aa3b, v12
	v_exp_f32_e32 v22, v22
	v_mul_f32_e32 v23, 0xbfb8aa3b, v8
	v_exp_f32_e32 v23, v23
	v_add_u32_e32 v20, 0xa0, v150
	v_add_f32_e32 v22, 1.0, v22
	v_rcp_f32_e32 v22, v22
	v_mad_i64_i32 v[20:21], s[0:1], v20, s47, v[112:113]
	v_add_f32_e32 v23, 1.0, v23
	v_mul_f32_e32 v12, v12, v22
	v_lshl_add_u64 v[20:21], v[20:21], 0, v[114:115]
	v_rcp_f32_e32 v23, v23
	v_mul_f32_e32 v4, v12, v4
	v_mul_f32_e32 v12, 0xbfb8aa3b, v13
	global_store_dwordx4 v[20:21], v[16:19], off
	v_exp_f32_e32 v12, v12
	v_mul_f32_e32 v8, v8, v23
	v_mul_f32_e32 v16, 0xbfb8aa3b, v9
	v_exp_f32_e32 v16, v16
	v_mul_f32_e32 v8, v8, v0
	v_add_f32_e32 v0, 1.0, v12
	v_rcp_f32_e32 v0, v0
	v_add_f32_e32 v12, 1.0, v16
	v_mul_f32_e32 v16, 0xbfb8aa3b, v14
	v_rcp_f32_e32 v12, v12
	v_exp_f32_e32 v16, v16
	v_mul_f32_e32 v0, v13, v0
	v_mul_f32_e32 v0, v0, v5
	v_mul_f32_e32 v5, v9, v12
	v_add_f32_e32 v9, 1.0, v16
	v_rcp_f32_e32 v9, v9
	v_mul_f32_e32 v12, 0xbfb8aa3b, v10
	v_exp_f32_e32 v12, v12
	v_mul_f32_e32 v5, v5, v1
	v_mul_f32_e32 v1, v14, v9
	v_mul_f32_e32 v9, 0xbfb8aa3b, v15
	v_exp_f32_e32 v9, v9
	v_mul_f32_e32 v1, v1, v6
	v_add_f32_e32 v6, 1.0, v12
	v_mul_f32_e32 v12, 0xbfb8aa3b, v11
	v_rcp_f32_e32 v6, v6
	v_exp_f32_e32 v12, v12
	v_add_f32_e32 v9, 1.0, v9
	v_rcp_f32_e32 v9, v9
	v_mul_f32_e32 v6, v10, v6
	v_add_f32_e32 v10, 1.0, v12
	v_rcp_f32_e32 v10, v10
	v_mul_f32_e32 v6, v6, v2
	v_mul_f32_e32 v2, v15, v9
	v_mul_f32_e32 v2, v2, v7
	s_nop 1
	v_cvt_pk_bf16_f32 v0, v4, v0
	v_add_u32_e32 v4, 0xb0, v150
	v_mul_f32_e32 v7, v11, v10
	s_nop 1
	v_cvt_pk_bf16_f32 v1, v1, v2
	s_nop 1
	v_cvt_pk_bf16_f32 v2, v8, v5
	v_mad_i64_i32 v[4:5], s[0:1], v4, s47, v[112:113]
	v_mul_f32_e32 v3, v7, v3
	v_lshl_add_u64 v[4:5], v[4:5], 0, v[114:115]
	s_mov_b32 s50, s10
	s_mov_b32 s18, s12
	s_mov_b64 s[44:45], s[16:17]
	s_mov_b64 s[20:21], s[14:15]
	s_nop 1
	v_cvt_pk_bf16_f32 v3, v6, v3
	global_store_dwordx4 v[4:5], v[0:3], off
	s_cbranch_vccz .LBB0_1673
	s_waitcnt vmcnt(0)
	s_cmpk_gt_u32 s23, 0xff
	s_cbranch_scc1 .LBB0_1680
	s_barrier

.LBB0_1749:
	ds_read_b128 v[128:131], v221
	ds_read_b128 v[132:135], v221 offset:1024
	ds_read_b128 v[136:139], v221 offset:2048
	ds_read_b128 v[140:143], v221 offset:3072
	s_add_u32 s44, s42, 0x100
	s_addc_u32 s45, s43, 0
	s_cmpk_eq_i32 s61, 0x54
	s_cselect_b32 s5, s9, s45
	s_cselect_b32 s4, s8, s44
	s_cselect_b32 s47, s11, s1
	s_cselect_b32 s46, s10, s0
	s_add_i32 m0, s25, 0xc000
	ds_read_b128 v[144:147], v222
	ds_read_b128 v[148:151], v222 offset:1024
	ds_read_b128 v[152:155], v222 offset:2048
	ds_read_b128 v[156:159], v222 offset:3072
	ds_read_b128 v[160:163], v222 offset:4096
	ds_read_b128 v[176:179], v222 offset:5120
	ds_read_b128 v[180:183], v222 offset:6144
	ds_read_b128 v[184:187], v222 offset:7168
	global_load_lds_dwordx4 v168, s[42:43]
	s_add_i32 m0, s25, 0xe000
	s_nop 0
	global_load_lds_dwordx4 v170, s[42:43]
	s_waitcnt lgkmcnt(8)
	s_barrier
	s_waitcnt lgkmcnt(0)
	s_waitcnt lgkmcnt(0)
	v_mfma_f32_16x16x32_bf16 v[124:127], v[128:131], v[144:147], v[124:127]
	v_mfma_f32_16x16x32_bf16 v[100:103], v[136:139], v[144:147], v[100:103]
	v_mfma_f32_16x16x32_bf16 v[120:123], v[128:131], v[152:155], v[120:123]
	v_mfma_f32_16x16x32_bf16 v[96:99], v[136:139], v[152:155], v[96:99]
	v_mfma_f32_16x16x32_bf16 v[116:119], v[128:131], v[160:163], v[116:119]
	v_mfma_f32_16x16x32_bf16 v[92:95], v[136:139], v[160:163], v[92:95]
	v_mfma_f32_16x16x32_bf16 v[112:115], v[128:131], v[180:183], v[112:115]
	v_mfma_f32_16x16x32_bf16 v[84:87], v[136:139], v[180:183], v[84:87]
	v_mfma_f32_16x16x32_bf16 v[124:127], v[132:135], v[148:151], v[124:127]
	v_mfma_f32_16x16x32_bf16 v[100:103], v[140:143], v[148:151], v[100:103]
	v_mfma_f32_16x16x32_bf16 v[120:123], v[132:135], v[156:159], v[120:123]
	v_mfma_f32_16x16x32_bf16 v[96:99], v[140:143], v[156:159], v[96:99]
	v_mfma_f32_16x16x32_bf16 v[116:119], v[132:135], v[176:179], v[116:119]
	v_mfma_f32_16x16x32_bf16 v[92:95], v[140:143], v[176:179], v[92:95]
	v_mfma_f32_16x16x32_bf16 v[112:115], v[132:135], v[184:187], v[112:115]
	v_mfma_f32_16x16x32_bf16 v[84:87], v[140:143], v[184:187], v[84:87]
	s_barrier
	s_add_i32 s42, s51, s24
	s_add_u32 s98, s46, s18
	s_addc_u32 s99, s47, s19
	s_mov_b32 m0, s42
	ds_read_b128 v[188:191], v223
	ds_read_b128 v[192:195], v223 offset:1024
	ds_read_b128 v[196:199], v223 offset:2048
	ds_read_b128 v[200:203], v223 offset:3072
	global_load_lds_dwordx4 v166, s[46:47]
	s_add_i32 m0, s42, 0x2000
	s_nop 0
	global_load_lds_dwordx4 v164, s[46:47]
	s_barrier
	s_waitcnt lgkmcnt(0)
	s_waitcnt lgkmcnt(0)
	v_mfma_f32_16x16x32_bf16 v[72:75], v[188:191], v[144:147], v[72:75]
	v_mfma_f32_16x16x32_bf16 v[44:47], v[196:199], v[144:147], v[44:47]
	v_mfma_f32_16x16x32_bf16 v[64:67], v[188:191], v[152:155], v[64:67]
	v_mfma_f32_16x16x32_bf16 v[40:43], v[196:199], v[152:155], v[40:43]
	v_mfma_f32_16x16x32_bf16 v[56:59], v[188:191], v[160:163], v[56:59]
	v_mfma_f32_16x16x32_bf16 v[36:39], v[196:199], v[160:163], v[36:39]
	v_mfma_f32_16x16x32_bf16 v[48:51], v[188:191], v[180:183], v[48:51]
	v_mfma_f32_16x16x32_bf16 v[28:31], v[196:199], v[180:183], v[28:31]
	v_mfma_f32_16x16x32_bf16 v[72:75], v[192:195], v[148:151], v[72:75]
	v_mfma_f32_16x16x32_bf16 v[44:47], v[200:203], v[148:151], v[44:47]
	v_mfma_f32_16x16x32_bf16 v[64:67], v[192:195], v[156:159], v[64:67]
	v_mfma_f32_16x16x32_bf16 v[40:43], v[200:203], v[156:159], v[40:43]
	v_mfma_f32_16x16x32_bf16 v[56:59], v[192:195], v[176:179], v[56:59]
	v_mfma_f32_16x16x32_bf16 v[36:39], v[200:203], v[176:179], v[36:39]
	v_mfma_f32_16x16x32_bf16 v[48:51], v[192:195], v[184:187], v[48:51]
	v_mfma_f32_16x16x32_bf16 v[28:31], v[200:203], v[184:187], v[28:31]
	s_mov_b32 m0, s25
	s_add_u32 s100, s4, s18
	s_addc_u32 s101, s5, s19
	s_barrier
	ds_read_b128 v[144:147], v222 offset:16384
	ds_read_b128 v[148:151], v222 offset:17408
	ds_read_b128 v[152:155], v222 offset:18432
	ds_read_b128 v[156:159], v222 offset:19456
	ds_read_b128 v[160:163], v222 offset:20480
	ds_read_b128 v[176:179], v222 offset:21504
	ds_read_b128 v[180:183], v222 offset:22528
	ds_read_b128 v[184:187], v222 offset:23552
	global_load_lds_dwordx4 v166, s[4:5]
	s_mov_b32 m0, s28
	s_nop 0
	global_load_lds_dwordx4 v164, s[4:5]
	s_barrier
	s_waitcnt lgkmcnt(0)
	s_waitcnt lgkmcnt(0)
	v_mfma_f32_16x16x32_bf16 v[108:111], v[128:131], v[144:147], v[108:111]
	v_mfma_f32_16x16x32_bf16 v[76:79], v[136:139], v[144:147], v[76:79]
	v_mfma_f32_16x16x32_bf16 v[104:107], v[128:131], v[152:155], v[104:107]
	v_mfma_f32_16x16x32_bf16 v[68:71], v[136:139], v[152:155], v[68:71]
	v_mfma_f32_16x16x32_bf16 v[88:91], v[128:131], v[160:163], v[88:91]
	v_mfma_f32_16x16x32_bf16 v[60:63], v[136:139], v[160:163], v[60:63]
	v_mfma_f32_16x16x32_bf16 v[80:83], v[128:131], v[180:183], v[80:83]
	v_mfma_f32_16x16x32_bf16 v[52:55], v[136:139], v[180:183], v[52:55]
	v_mfma_f32_16x16x32_bf16 v[108:111], v[132:135], v[148:151], v[108:111]
	v_mfma_f32_16x16x32_bf16 v[76:79], v[140:143], v[148:151], v[76:79]
	v_mfma_f32_16x16x32_bf16 v[104:107], v[132:135], v[156:159], v[104:107]
	v_mfma_f32_16x16x32_bf16 v[68:71], v[140:143], v[156:159], v[68:71]
	v_mfma_f32_16x16x32_bf16 v[88:91], v[132:135], v[176:179], v[88:91]
	v_mfma_f32_16x16x32_bf16 v[60:63], v[140:143], v[176:179], v[60:63]
	v_mfma_f32_16x16x32_bf16 v[80:83], v[132:135], v[184:187], v[80:83]
	v_mfma_f32_16x16x32_bf16 v[52:55], v[140:143], v[184:187], v[52:55]
	s_barrier
	s_add_u32 s42, s46, 0x160000
	s_addc_u32 s43, s47, 0
	s_add_i32 s62, s52, s24
	s_mov_b32 m0, s62
	s_nop 0
	global_load_lds_dwordx4 v166, s[42:43]
	s_add_i32 m0, s62, 0x2000
	s_nop 0
	global_load_lds_dwordx4 v164, s[42:43]
	s_waitcnt vmcnt(6)
	s_barrier
	v_mfma_f32_16x16x32_bf16 v[32:35], v[188:191], v[144:147], v[32:35]
	v_mfma_f32_16x16x32_bf16 v[12:15], v[196:199], v[144:147], v[12:15]
	v_mfma_f32_16x16x32_bf16 v[24:27], v[188:191], v[152:155], v[24:27]
	v_mfma_f32_16x16x32_bf16 v[8:11], v[196:199], v[152:155], v[8:11]
	v_mfma_f32_16x16x32_bf16 v[20:23], v[188:191], v[160:163], v[20:23]
	v_mfma_f32_16x16x32_bf16 v[4:7], v[196:199], v[160:163], v[4:7]
	v_mfma_f32_16x16x32_bf16 v[16:19], v[188:191], v[180:183], v[16:19]
	v_mfma_f32_16x16x32_bf16 v[0:3], v[196:199], v[180:183], v[0:3]
	v_mfma_f32_16x16x32_bf16 v[32:35], v[192:195], v[148:151], v[32:35]
	v_mfma_f32_16x16x32_bf16 v[12:15], v[200:203], v[148:151], v[12:15]
	v_mfma_f32_16x16x32_bf16 v[24:27], v[192:195], v[156:159], v[24:27]
	v_mfma_f32_16x16x32_bf16 v[8:11], v[200:203], v[156:159], v[8:11]
	v_mfma_f32_16x16x32_bf16 v[20:23], v[192:195], v[176:179], v[20:23]
	v_mfma_f32_16x16x32_bf16 v[4:7], v[200:203], v[176:179], v[4:7]
	v_mfma_f32_16x16x32_bf16 v[16:19], v[192:195], v[184:187], v[16:19]
	v_mfma_f32_16x16x32_bf16 v[0:3], v[200:203], v[184:187], v[0:3]
	s_add_i32 s42, 0, 0x18000
	v_add_u32_e32 v140, s42, v219
	s_barrier
	ds_read_b128 v[128:131], v140
	ds_read_b128 v[132:135], v140 offset:1024
	ds_read_b128 v[136:139], v140 offset:2048
	ds_read_b128 v[140:143], v140 offset:3072
	s_add_u32 s4, s4, 0x160000
	s_addc_u32 s5, s5, 0
	s_mov_b32 m0, s29
	ds_read_b128 v[144:147], v222 offset:32768
	ds_read_b128 v[148:151], v222 offset:33792
	ds_read_b128 v[152:155], v222 offset:34816
	ds_read_b128 v[156:159], v222 offset:35840
	ds_read_b128 v[160:163], v222 offset:36864
	ds_read_b128 v[176:179], v222 offset:37888
	ds_read_b128 v[180:183], v222 offset:38912
	ds_read_b128 v[184:187], v222 offset:39936
	global_load_lds_dwordx4 v166, s[4:5]
	s_mov_b32 m0, s33
	s_nop 0
	global_load_lds_dwordx4 v164, s[4:5]
	s_waitcnt lgkmcnt(8)
	s_barrier
	s_waitcnt lgkmcnt(0)
	s_waitcnt lgkmcnt(0)
	v_mfma_f32_16x16x32_bf16 v[124:127], v[128:131], v[144:147], v[124:127]
	v_mfma_f32_16x16x32_bf16 v[100:103], v[136:139], v[144:147], v[100:103]
	v_mfma_f32_16x16x32_bf16 v[120:123], v[128:131], v[152:155], v[120:123]
	v_mfma_f32_16x16x32_bf16 v[96:99], v[136:139], v[152:155], v[96:99]
	v_mfma_f32_16x16x32_bf16 v[116:119], v[128:131], v[160:163], v[116:119]
	v_mfma_f32_16x16x32_bf16 v[92:95], v[136:139], v[160:163], v[92:95]
	v_mfma_f32_16x16x32_bf16 v[112:115], v[128:131], v[180:183], v[112:115]
	v_mfma_f32_16x16x32_bf16 v[84:87], v[136:139], v[180:183], v[84:87]
	v_mfma_f32_16x16x32_bf16 v[124:127], v[132:135], v[148:151], v[124:127]
	v_mfma_f32_16x16x32_bf16 v[100:103], v[140:143], v[148:151], v[100:103]
	v_mfma_f32_16x16x32_bf16 v[120:123], v[132:135], v[156:159], v[120:123]
	v_mfma_f32_16x16x32_bf16 v[96:99], v[140:143], v[156:159], v[96:99]
	v_mfma_f32_16x16x32_bf16 v[116:119], v[132:135], v[176:179], v[116:119]
	v_mfma_f32_16x16x32_bf16 v[92:95], v[140:143], v[176:179], v[92:95]
	v_mfma_f32_16x16x32_bf16 v[112:115], v[132:135], v[184:187], v[112:115]
	v_mfma_f32_16x16x32_bf16 v[84:87], v[140:143], v[184:187], v[84:87]
	s_barrier
	s_add_i32 s43, 0, 0x1c000
	s_add_i32 s4, s42, s24
	v_add_u32_e32 v200, s43, v219
	s_mov_b32 m0, s4
	ds_read_b128 v[188:191], v200
	ds_read_b128 v[192:195], v200 offset:1024
	ds_read_b128 v[196:199], v200 offset:2048
	ds_read_b128 v[200:203], v200 offset:3072
	global_load_lds_dwordx4 v166, s[98:99]
	s_add_i32 m0, s4, 0x2000
	s_nop 0
	global_load_lds_dwordx4 v164, s[98:99]
	s_barrier
	s_waitcnt lgkmcnt(0)
	s_waitcnt lgkmcnt(0)
	v_mfma_f32_16x16x32_bf16 v[72:75], v[188:191], v[144:147], v[72:75]
	v_mfma_f32_16x16x32_bf16 v[44:47], v[196:199], v[144:147], v[44:47]
	v_mfma_f32_16x16x32_bf16 v[64:67], v[188:191], v[152:155], v[64:67]
	v_mfma_f32_16x16x32_bf16 v[40:43], v[196:199], v[152:155], v[40:43]
	v_mfma_f32_16x16x32_bf16 v[56:59], v[188:191], v[160:163], v[56:59]
	v_mfma_f32_16x16x32_bf16 v[36:39], v[196:199], v[160:163], v[36:39]
	v_mfma_f32_16x16x32_bf16 v[48:51], v[188:191], v[180:183], v[48:51]
	v_mfma_f32_16x16x32_bf16 v[28:31], v[196:199], v[180:183], v[28:31]
	v_mfma_f32_16x16x32_bf16 v[72:75], v[192:195], v[148:151], v[72:75]
	v_mfma_f32_16x16x32_bf16 v[44:47], v[200:203], v[148:151], v[44:47]
	v_mfma_f32_16x16x32_bf16 v[64:67], v[192:195], v[156:159], v[64:67]
	v_mfma_f32_16x16x32_bf16 v[40:43], v[200:203], v[156:159], v[40:43]
	v_mfma_f32_16x16x32_bf16 v[56:59], v[192:195], v[176:179], v[56:59]
	v_mfma_f32_16x16x32_bf16 v[36:39], v[200:203], v[176:179], v[36:39]
	v_mfma_f32_16x16x32_bf16 v[48:51], v[192:195], v[184:187], v[48:51]
	v_mfma_f32_16x16x32_bf16 v[28:31], v[200:203], v[184:187], v[28:31]
	s_mov_b32 m0, s41
	s_barrier
	ds_read_b128 v[144:147], v222 offset:49152
	ds_read_b128 v[148:151], v222 offset:50176
	ds_read_b128 v[152:155], v222 offset:51200
	ds_read_b128 v[156:159], v222 offset:52224
	ds_read_b128 v[160:163], v222 offset:53248
	ds_read_b128 v[176:179], v222 offset:54272
	ds_read_b128 v[180:183], v222 offset:55296
	ds_read_b128 v[184:187], v222 offset:56320
	global_load_lds_dwordx4 v166, s[100:101]
	s_mov_b32 m0, s50
	s_nop 0
	global_load_lds_dwordx4 v164, s[100:101]
	s_barrier
	s_waitcnt lgkmcnt(0)
	s_waitcnt lgkmcnt(0)
	v_mfma_f32_16x16x32_bf16 v[108:111], v[128:131], v[144:147], v[108:111]
	v_mfma_f32_16x16x32_bf16 v[76:79], v[136:139], v[144:147], v[76:79]
	v_mfma_f32_16x16x32_bf16 v[104:107], v[128:131], v[152:155], v[104:107]
	v_mfma_f32_16x16x32_bf16 v[68:71], v[136:139], v[152:155], v[68:71]
	v_mfma_f32_16x16x32_bf16 v[88:91], v[128:131], v[160:163], v[88:91]
	v_mfma_f32_16x16x32_bf16 v[60:63], v[136:139], v[160:163], v[60:63]
	v_mfma_f32_16x16x32_bf16 v[80:83], v[128:131], v[180:183], v[80:83]
	v_mfma_f32_16x16x32_bf16 v[52:55], v[136:139], v[180:183], v[52:55]
	v_mfma_f32_16x16x32_bf16 v[108:111], v[132:135], v[148:151], v[108:111]
	v_mfma_f32_16x16x32_bf16 v[76:79], v[140:143], v[148:151], v[76:79]
	v_mfma_f32_16x16x32_bf16 v[104:107], v[132:135], v[156:159], v[104:107]
	v_mfma_f32_16x16x32_bf16 v[68:71], v[140:143], v[156:159], v[68:71]
	v_mfma_f32_16x16x32_bf16 v[88:91], v[132:135], v[176:179], v[88:91]
	v_mfma_f32_16x16x32_bf16 v[60:63], v[140:143], v[176:179], v[60:63]
	v_mfma_f32_16x16x32_bf16 v[80:83], v[132:135], v[184:187], v[80:83]
	v_mfma_f32_16x16x32_bf16 v[52:55], v[140:143], v[184:187], v[52:55]
	s_barrier
	s_add_u32 s4, s46, 0x160080
	s_addc_u32 s5, s47, 0
	s_add_i32 s42, s43, s24
	s_mov_b32 m0, s42
	s_nop 0
	global_load_lds_dwordx4 v166, s[4:5]
	s_add_i32 m0, s42, 0x2000
	s_nop 0
	global_load_lds_dwordx4 v164, s[4:5]
	s_waitcnt vmcnt(6)
	s_barrier
	v_mfma_f32_16x16x32_bf16 v[32:35], v[188:191], v[144:147], v[32:35]
	v_mfma_f32_16x16x32_bf16 v[12:15], v[196:199], v[144:147], v[12:15]
	v_mfma_f32_16x16x32_bf16 v[24:27], v[188:191], v[152:155], v[24:27]
	v_mfma_f32_16x16x32_bf16 v[8:11], v[196:199], v[152:155], v[8:11]
	v_mfma_f32_16x16x32_bf16 v[20:23], v[188:191], v[160:163], v[20:23]
	v_mfma_f32_16x16x32_bf16 v[4:7], v[196:199], v[160:163], v[4:7]
	v_mfma_f32_16x16x32_bf16 v[16:19], v[188:191], v[180:183], v[16:19]
	v_mfma_f32_16x16x32_bf16 v[0:3], v[196:199], v[180:183], v[0:3]
	v_mfma_f32_16x16x32_bf16 v[32:35], v[192:195], v[148:151], v[32:35]
	v_mfma_f32_16x16x32_bf16 v[12:15], v[200:203], v[148:151], v[12:15]
	v_mfma_f32_16x16x32_bf16 v[24:27], v[192:195], v[156:159], v[24:27]
	v_mfma_f32_16x16x32_bf16 v[8:11], v[200:203], v[156:159], v[8:11]
	v_mfma_f32_16x16x32_bf16 v[20:23], v[192:195], v[176:179], v[20:23]
	v_mfma_f32_16x16x32_bf16 v[4:7], v[200:203], v[176:179], v[4:7]
	v_mfma_f32_16x16x32_bf16 v[16:19], v[192:195], v[184:187], v[16:19]
	v_mfma_f32_16x16x32_bf16 v[0:3], v[200:203], v[184:187], v[0:3]
	s_add_i32 s61, s61, 2
	s_add_u32 s0, s0, 0x100
	s_addc_u32 s1, s1, 0
	s_cmpk_gt_u32 s61, 0x55
	s_mov_b64 s[42:43], s[44:45]
	s_barrier
	s_cbranch_scc0 .LBB0_1749
	v_lshl_add_u32 v144, s59, 8, v218
	v_lshl_or_b32 v184, s60, 8, v220
	v_ashrrev_i32_e32 v145, 31, v144
	v_ashrrev_i32_e32 v185, 31, v184
	v_lshlrev_b64 v[132:133], 13, v[144:145]
	v_lshlrev_b64 v[146:147], 2, v[184:185]
	v_lshl_add_u64 v[132:133], s[12:13], 0, v[132:133]
	v_lshl_add_u64 v[176:177], v[132:133], 0, v[146:147]
	v_or_b32_e32 v136, 16, v144
	v_add_co_u32_e32 v186, vcc, s53, v176
	v_ashrrev_i32_e32 v137, 31, v136
	v_or_b32_e32 v140, 32, v144
	v_or_b32_e32 v144, 48, v144
	v_addc_co_u32_e32 v187, vcc, 0, v177, vcc
	v_lshlrev_b64 v[136:137], 13, v[136:137]
	v_ashrrev_i32_e32 v141, 31, v140
	v_ashrrev_i32_e32 v145, 31, v144
	v_add_co_u32_e32 v190, vcc, s54, v176
	v_lshl_add_u64 v[128:129], s[16:17], 0, v[146:147]
	v_lshl_add_u64 v[136:137], s[12:13], 0, v[136:137]
	v_lshlrev_b64 v[140:141], 13, v[140:141]
	v_lshlrev_b64 v[144:145], 13, v[144:145]
	v_addc_co_u32_e32 v191, vcc, 0, v177, vcc
	global_load_dwordx4 v[128:131], v[128:129], off
	v_lshl_add_u64 v[178:179], v[136:137], 0, v[146:147]
	global_load_dwordx4 v[132:135], v[176:177], off
	global_load_dwordx4 v[136:139], v[178:179], off
	v_lshl_add_u64 v[140:141], s[12:13], 0, v[140:141]
	v_lshl_add_u64 v[144:145], s[12:13], 0, v[144:145]
	v_add_co_u32_e32 v192, vcc, s55, v176
	v_lshl_add_u64 v[180:181], v[140:141], 0, v[146:147]
	v_lshl_add_u64 v[182:183], v[144:145], 0, v[146:147]
	v_addc_co_u32_e32 v193, vcc, 0, v177, vcc
	global_load_dwordx4 v[140:143], v[180:181], off
	global_load_dwordx4 v[144:147], v[182:183], off
	global_load_dwordx4 v[148:151], v[186:187], off
	global_load_dwordx4 v[160:163], v[190:191], off
	global_load_dwordx4 v[156:159], v[192:193], off
	v_add_co_u32_e32 v188, vcc, s56, v176
	v_pk_add_f32 v[212:213], v[126:127], 0 op_sel_hi:[1,0]
	s_nop 0
	v_addc_co_u32_e32 v189, vcc, 0, v177, vcc
	global_load_dwordx4 v[152:155], v[188:189], off
	v_pk_add_f32 v[214:215], v[124:125], 0 op_sel_hi:[1,0]
	v_pk_add_f32 v[126:127], v[122:123], 0 op_sel_hi:[1,0]
	v_pk_add_f32 v[194:195], v[120:121], 0 op_sel_hi:[1,0]
	v_pk_add_f32 v[196:197], v[118:119], 0 op_sel_hi:[1,0]
	v_pk_add_f32 v[198:199], v[116:117], 0 op_sel_hi:[1,0]
	v_pk_add_f32 v[200:201], v[114:115], 0 op_sel_hi:[1,0]
	v_pk_add_f32 v[202:203], v[112:113], 0 op_sel_hi:[1,0]
	v_pk_add_f32 v[204:205], v[110:111], 0 op_sel_hi:[1,0]
	v_pk_add_f32 v[206:207], v[108:109], 0 op_sel_hi:[1,0]
	v_pk_add_f32 v[208:209], v[106:107], 0 op_sel_hi:[1,0]
	v_pk_add_f32 v[210:211], v[104:105], 0 op_sel_hi:[1,0]
	v_lshl_add_u64 v[120:121], v[176:177], 0, s[20:21]
	v_lshl_add_u64 v[122:123], v[176:177], 0, s[36:37]
	global_load_dwordx4 v[104:107], v[176:177], off offset:64
	global_load_dwordx4 v[108:111], v[178:179], off offset:64
	global_load_dwordx4 v[112:115], v[180:181], off offset:64
	global_load_dwordx4 v[116:119], v[182:183], off offset:64
	global_load_dwordx4 v[224:227], v[120:121], off offset:576
	global_load_dwordx4 v[228:231], v[122:123], off offset:576
	v_lshl_add_u64 v[124:125], v[176:177], 0, s[38:39]
	v_pk_add_f32 v[102:103], v[102:103], 0 op_sel_hi:[1,0]
	v_pk_add_f32 v[100:101], v[100:101], 0 op_sel_hi:[1,0]
	v_pk_add_f32 v[98:99], v[98:99], 0 op_sel_hi:[1,0]
	v_pk_add_f32 v[96:97], v[96:97], 0 op_sel_hi:[1,0]
	v_pk_add_f32 v[74:75], v[74:75], 0 op_sel_hi:[1,0]
	v_pk_add_f32 v[72:73], v[72:73], 0 op_sel_hi:[1,0]
	v_pk_add_f32 v[66:67], v[66:67], 0 op_sel_hi:[1,0]
	v_pk_add_f32 v[64:65], v[64:65], 0 op_sel_hi:[1,0]
	v_pk_add_f32 v[58:59], v[58:59], 0 op_sel_hi:[1,0]
	v_pk_add_f32 v[56:57], v[56:57], 0 op_sel_hi:[1,0]
	v_pk_add_f32 v[46:47], v[46:47], 0 op_sel_hi:[1,0]
	v_pk_add_f32 v[44:45], v[44:45], 0 op_sel_hi:[1,0]
	v_pk_add_f32 v[42:43], v[42:43], 0 op_sel_hi:[1,0]
	v_pk_add_f32 v[40:41], v[40:41], 0 op_sel_hi:[1,0]
	v_pk_add_f32 v[38:39], v[38:39], 0 op_sel_hi:[1,0]
	v_pk_add_f32 v[36:37], v[36:37], 0 op_sel_hi:[1,0]
	v_pk_add_f32 v[30:31], v[30:31], 0 op_sel_hi:[1,0]
	v_pk_add_f32 v[28:29], v[28:29], 0 op_sel_hi:[1,0]
	s_and_b64 vcc, exec, s[6:7]
	s_mov_b32 s60, s57
	s_mov_b32 s59, s58
	s_mov_b64 s[44:45], s[10:11]
	s_mov_b64 s[42:43], s[8:9]
	s_waitcnt vmcnt(0)
	v_pk_fma_f32 v[134:135], v[212:213], v[130:131], v[134:135]
	v_pk_fma_f32 v[132:133], v[214:215], v[128:129], v[132:133]
	global_store_dwordx4 v[176:177], v[132:135], off
	s_nop 1
	v_pk_fma_f32 v[134:135], v[126:127], v[130:131], v[138:139]
	v_pk_fma_f32 v[132:133], v[194:195], v[128:129], v[136:137]
	v_pk_add_f32 v[126:127], v[90:91], 0 op_sel_hi:[1,0]
	v_pk_fma_f32 v[138:139], v[196:197], v[130:131], v[142:143]
	v_pk_fma_f32 v[136:137], v[198:199], v[128:129], v[140:141]
	v_pk_fma_f32 v[142:143], v[200:201], v[130:131], v[146:147]
	v_pk_fma_f32 v[140:141], v[202:203], v[128:129], v[144:145]
	v_pk_fma_f32 v[146:147], v[204:205], v[130:131], v[150:151]
	v_pk_fma_f32 v[144:145], v[206:207], v[128:129], v[148:149]
	v_pk_fma_f32 v[150:151], v[208:209], v[130:131], v[162:163]
	v_pk_fma_f32 v[148:149], v[210:211], v[128:129], v[160:161]
	global_store_dwordx4 v[178:179], v[132:135], off
	global_store_dwordx4 v[180:181], v[136:139], off
	global_store_dwordx4 v[182:183], v[140:143], off
	global_store_dwordx4 v[186:187], v[144:147], off
	global_store_dwordx4 v[190:191], v[148:151], off
	v_pk_add_f32 v[132:133], v[88:89], 0 op_sel_hi:[1,0]
	v_pk_fma_f32 v[134:135], v[126:127], v[130:131], v[158:159]
	v_pk_fma_f32 v[132:133], v[132:133], v[128:129], v[156:157]
	v_pk_add_f32 v[126:127], v[82:83], 0 op_sel_hi:[1,0]
	global_store_dwordx4 v[192:193], v[132:135], off
	v_pk_fma_f32 v[130:131], v[126:127], v[130:131], v[154:155]
	v_or_b32_e32 v126, 16, v184
	v_pk_add_f32 v[132:133], v[80:81], 0 op_sel_hi:[1,0]
	v_ashrrev_i32_e32 v127, 31, v126
	v_pk_fma_f32 v[128:129], v[132:133], v[128:129], v[152:153]
	v_lshl_add_u64 v[146:147], v[176:177], 0, s[14:15]
	global_store_dwordx4 v[188:189], v[128:131], off
	v_lshl_add_u64 v[126:127], v[126:127], 2, s[16:17]
	global_load_dwordx4 v[88:91], v[124:125], off offset:576
	global_load_dwordx4 v[80:83], v[146:147], off offset:576
	s_nop 0
	global_load_dwordx4 v[126:129], v[126:127], off
	s_nop 0
	global_load_dwordx4 v[130:133], v[120:121], off offset:64
	global_load_dwordx4 v[134:137], v[122:123], off offset:64
	global_load_dwordx4 v[138:141], v[124:125], off offset:64
	global_load_dwordx4 v[142:145], v[146:147], off offset:64
	v_pk_add_f32 v[192:193], v[52:53], 0 op_sel_hi:[1,0]
	v_or_b32_e32 v52, 0x80, v184
	v_pk_add_f32 v[148:149], v[94:95], 0 op_sel_hi:[1,0]
	v_pk_add_f32 v[150:151], v[92:93], 0 op_sel_hi:[1,0]
	v_pk_add_f32 v[152:153], v[86:87], 0 op_sel_hi:[1,0]
	v_pk_add_f32 v[154:155], v[84:85], 0 op_sel_hi:[1,0]
	v_pk_add_f32 v[156:157], v[78:79], 0 op_sel_hi:[1,0]
	v_pk_add_f32 v[158:159], v[76:77], 0 op_sel_hi:[1,0]
	v_pk_add_f32 v[160:161], v[70:71], 0 op_sel_hi:[1,0]
	v_pk_add_f32 v[162:163], v[68:69], 0 op_sel_hi:[1,0]
	v_pk_add_f32 v[186:187], v[62:63], 0 op_sel_hi:[1,0]
	v_pk_add_f32 v[188:189], v[60:61], 0 op_sel_hi:[1,0]
	v_pk_add_f32 v[190:191], v[54:55], 0 op_sel_hi:[1,0]
	v_ashrrev_i32_e32 v53, 31, v52
	v_lshl_add_u64 v[194:195], v[52:53], 2, s[16:17]
	global_load_dwordx4 v[52:55], v[176:177], off offset:512
	global_load_dwordx4 v[60:63], v[120:121], off offset:512
	global_load_dwordx4 v[68:71], v[122:123], off offset:512
	global_load_dwordx4 v[76:79], v[124:125], off offset:512
	global_load_dwordx4 v[84:87], v[146:147], off offset:512
	s_waitcnt vmcnt(0)
	v_pk_fma_f32 v[94:95], v[102:103], v[128:129], v[106:107]
	v_pk_fma_f32 v[92:93], v[100:101], v[126:127], v[104:105]
	v_pk_fma_f32 v[98:99], v[98:99], v[128:129], v[110:111]
	v_pk_fma_f32 v[96:97], v[96:97], v[126:127], v[108:109]
	v_pk_fma_f32 v[102:103], v[148:149], v[128:129], v[114:115]
	v_pk_fma_f32 v[100:101], v[150:151], v[126:127], v[112:113]
	v_pk_fma_f32 v[106:107], v[152:153], v[128:129], v[118:119]
	v_pk_fma_f32 v[104:105], v[154:155], v[126:127], v[116:117]
	v_pk_fma_f32 v[110:111], v[156:157], v[128:129], v[132:133]
	v_pk_fma_f32 v[108:109], v[158:159], v[126:127], v[130:131]
	v_pk_fma_f32 v[114:115], v[160:161], v[128:129], v[136:137]
	v_pk_fma_f32 v[112:113], v[162:163], v[126:127], v[134:135]
	v_pk_fma_f32 v[118:119], v[186:187], v[128:129], v[140:141]
	v_pk_fma_f32 v[116:117], v[188:189], v[126:127], v[138:139]
	v_pk_fma_f32 v[128:129], v[190:191], v[128:129], v[144:145]
	v_pk_fma_f32 v[126:127], v[192:193], v[126:127], v[142:143]
	global_store_dwordx4 v[176:177], v[92:95], off offset:64
	global_store_dwordx4 v[178:179], v[96:99], off offset:64
	global_store_dwordx4 v[180:181], v[100:103], off offset:64
	global_store_dwordx4 v[182:183], v[104:107], off offset:64
	global_store_dwordx4 v[120:121], v[108:111], off offset:64
	global_store_dwordx4 v[122:123], v[112:115], off offset:64
	global_store_dwordx4 v[124:125], v[116:119], off offset:64
	global_store_dwordx4 v[146:147], v[126:129], off offset:64
	global_load_dwordx4 v[92:95], v[194:195], off
	global_load_dwordx4 v[96:99], v[178:179], off offset:512
	global_load_dwordx4 v[100:103], v[180:181], off offset:512
	global_load_dwordx4 v[104:107], v[182:183], off offset:512
	v_pk_add_f32 v[132:133], v[16:17], 0 op_sel_hi:[1,0]
	v_or_b32_e32 v16, 0x90, v184
	v_pk_add_f32 v[108:109], v[50:51], 0 op_sel_hi:[1,0]
	v_pk_add_f32 v[110:111], v[48:49], 0 op_sel_hi:[1,0]
	v_pk_add_f32 v[112:113], v[34:35], 0 op_sel_hi:[1,0]
	v_pk_add_f32 v[114:115], v[32:33], 0 op_sel_hi:[1,0]
	v_pk_add_f32 v[116:117], v[26:27], 0 op_sel_hi:[1,0]
	v_pk_add_f32 v[118:119], v[24:25], 0 op_sel_hi:[1,0]
	v_pk_add_f32 v[126:127], v[22:23], 0 op_sel_hi:[1,0]
	v_pk_add_f32 v[128:129], v[20:21], 0 op_sel_hi:[1,0]
	v_pk_add_f32 v[130:131], v[18:19], 0 op_sel_hi:[1,0]
	v_ashrrev_i32_e32 v17, 31, v16
	v_lshl_add_u64 v[134:135], v[16:17], 2, s[16:17]
	global_load_dwordx4 v[16:19], v[176:177], off offset:576
	global_load_dwordx4 v[20:23], v[178:179], off offset:576
	global_load_dwordx4 v[24:27], v[180:181], off offset:576
	global_load_dwordx4 v[32:35], v[182:183], off offset:576
	s_waitcnt vmcnt(0)
	v_pk_fma_f32 v[50:51], v[74:75], v[94:95], v[54:55]
	v_pk_fma_f32 v[48:49], v[72:73], v[92:93], v[52:53]
	v_pk_fma_f32 v[54:55], v[66:67], v[94:95], v[98:99]
	v_pk_fma_f32 v[52:53], v[64:65], v[92:93], v[96:97]
	v_pk_fma_f32 v[58:59], v[58:59], v[94:95], v[102:103]
	v_pk_fma_f32 v[56:57], v[56:57], v[92:93], v[100:101]
	v_pk_fma_f32 v[66:67], v[108:109], v[94:95], v[106:107]
	v_pk_fma_f32 v[64:65], v[110:111], v[92:93], v[104:105]
	v_pk_fma_f32 v[62:63], v[112:113], v[94:95], v[62:63]
	v_pk_fma_f32 v[60:61], v[114:115], v[92:93], v[60:61]
	v_pk_fma_f32 v[70:71], v[116:117], v[94:95], v[70:71]
	v_pk_fma_f32 v[68:69], v[118:119], v[92:93], v[68:69]
	v_pk_fma_f32 v[74:75], v[126:127], v[94:95], v[78:79]
	v_pk_fma_f32 v[72:73], v[128:129], v[92:93], v[76:77]
	v_pk_fma_f32 v[78:79], v[130:131], v[94:95], v[86:87]
	v_pk_fma_f32 v[76:77], v[132:133], v[92:93], v[84:85]
	global_store_dwordx4 v[176:177], v[48:51], off offset:512
	global_store_dwordx4 v[178:179], v[52:55], off offset:512
	global_store_dwordx4 v[180:181], v[56:59], off offset:512
	global_store_dwordx4 v[182:183], v[64:67], off offset:512
	global_store_dwordx4 v[120:121], v[60:63], off offset:512
	global_store_dwordx4 v[122:123], v[68:71], off offset:512
	global_store_dwordx4 v[124:125], v[72:75], off offset:512
	global_store_dwordx4 v[146:147], v[76:79], off offset:512
	global_load_dwordx4 v[48:51], v[134:135], off
	v_pk_add_f32 v[52:53], v[14:15], 0 op_sel_hi:[1,0]
	v_pk_add_f32 v[54:55], v[12:13], 0 op_sel_hi:[1,0]
	v_pk_add_f32 v[56:57], v[10:11], 0 op_sel_hi:[1,0]
	v_pk_add_f32 v[58:59], v[8:9], 0 op_sel_hi:[1,0]
	v_pk_add_f32 v[60:61], v[6:7], 0 op_sel_hi:[1,0]
	v_pk_add_f32 v[62:63], v[4:5], 0 op_sel_hi:[1,0]
	v_pk_add_f32 v[64:65], v[2:3], 0 op_sel_hi:[1,0]
	v_pk_add_f32 v[66:67], v[0:1], 0 op_sel_hi:[1,0]
	s_waitcnt vmcnt(0)
	v_pk_fma_f32 v[2:3], v[46:47], v[50:51], v[18:19]
	v_pk_fma_f32 v[0:1], v[44:45], v[48:49], v[16:17]
	v_pk_fma_f32 v[6:7], v[42:43], v[50:51], v[22:23]
	v_pk_fma_f32 v[4:5], v[40:41], v[48:49], v[20:21]
	v_pk_fma_f32 v[10:11], v[38:39], v[50:51], v[26:27]
	v_pk_fma_f32 v[8:9], v[36:37], v[48:49], v[24:25]
	v_pk_fma_f32 v[14:15], v[30:31], v[50:51], v[34:35]
	v_pk_fma_f32 v[12:13], v[28:29], v[48:49], v[32:33]
	v_pk_fma_f32 v[18:19], v[52:53], v[50:51], v[226:227]
	v_pk_fma_f32 v[16:17], v[54:55], v[48:49], v[224:225]
	v_pk_fma_f32 v[22:23], v[56:57], v[50:51], v[230:231]
	v_pk_fma_f32 v[20:21], v[58:59], v[48:49], v[228:229]
	v_pk_fma_f32 v[26:27], v[60:61], v[50:51], v[90:91]
	v_pk_fma_f32 v[24:25], v[62:63], v[48:49], v[88:89]
	v_pk_fma_f32 v[30:31], v[64:65], v[50:51], v[82:83]
	v_pk_fma_f32 v[28:29], v[66:67], v[48:49], v[80:81]
	global_store_dwordx4 v[176:177], v[0:3], off offset:576
	global_store_dwordx4 v[178:179], v[4:7], off offset:576
	global_store_dwordx4 v[180:181], v[8:11], off offset:576
	global_store_dwordx4 v[182:183], v[12:15], off offset:576
	global_store_dwordx4 v[120:121], v[16:19], off offset:576
	global_store_dwordx4 v[122:123], v[20:23], off offset:576
	global_store_dwordx4 v[124:125], v[24:27], off offset:576
	global_store_dwordx4 v[146:147], v[28:31], off offset:576
	s_cbranch_vccz .LBB0_1738
	s_waitcnt vmcnt(0)
	s_cmpk_gt_u32 s23, 0xff
	s_cbranch_scc1 .LBB0_1753
	s_barrier

	.amdhsa_kernel _Z4mega4Args
		.amdhsa_group_segment_fixed_size 0
		.amdhsa_private_segment_fixed_size 0
		.amdhsa_kernarg_size 632
		.amdhsa_user_sgpr_count 2
		.amdhsa_user_sgpr_dispatch_ptr 0
		.amdhsa_user_sgpr_queue_ptr 0
		.amdhsa_user_sgpr_kernarg_segment_ptr 1
		.amdhsa_user_sgpr_dispatch_id 0
		.amdhsa_user_sgpr_kernarg_preload_length 0
		.amdhsa_user_sgpr_kernarg_preload_offset 0
		.amdhsa_user_sgpr_private_segment_size 0
		.amdhsa_uses_dynamic_stack 0
		.amdhsa_enable_private_segment 0
		.amdhsa_system_sgpr_workgroup_id_x 1
		.amdhsa_system_sgpr_workgroup_id_y 0
		.amdhsa_system_sgpr_workgroup_id_z 0
		.amdhsa_system_sgpr_workgroup_info 0
		.amdhsa_system_vgpr_workitem_id 2
		.amdhsa_next_free_vgpr 256
		.amdhsa_next_free_sgpr 102
		.amdhsa_accum_offset 256
		.amdhsa_reserve_vcc 1
		.amdhsa_float_round_mode_32 0
		.amdhsa_float_round_mode_16_64 0
		.amdhsa_float_denorm_mode_32 3
		.amdhsa_float_denorm_mode_16_64 3
		.amdhsa_dx10_clamp 1
		.amdhsa_ieee_mode 1
		.amdhsa_fp16_overflow 0
		.amdhsa_tg_split 0
		.amdhsa_exception_fp_ieee_invalid_op 0
		.amdhsa_exception_fp_denorm_src 0
		.amdhsa_exception_fp_ieee_div_zero 0
		.amdhsa_exception_fp_ieee_overflow 0
		.amdhsa_exception_fp_ieee_underflow 0
		.amdhsa_exception_fp_ieee_inexact 0
		.amdhsa_exception_int_div_zero 0
	.end_amdhsa_kernel

amdhsa.kernels:
  - .agpr_count:     0
    .args:
      - .offset:         0
        .size:           376
        .value_kind:     by_value
      - .offset:         376
        .size:           4
        .value_kind:     hidden_block_count_x
      - .offset:         380
        .size:           4
        .value_kind:     hidden_block_count_y
      - .offset:         384
        .size:           4
        .value_kind:     hidden_block_count_z
      - .offset:         388
        .size:           2
        .value_kind:     hidden_group_size_x
      - .offset:         390
        .size:           2
        .value_kind:     hidden_group_size_y
      - .offset:         392
        .size:           2
        .value_kind:     hidden_group_size_z
      - .offset:         394
        .size:           2
        .value_kind:     hidden_remainder_x
      - .offset:         396
        .size:           2
        .value_kind:     hidden_remainder_y
      - .offset:         398
        .size:           2
        .value_kind:     hidden_remainder_z
      - .offset:         416
        .size:           8
        .value_kind:     hidden_global_offset_x
      - .offset:         424
        .size:           8
        .value_kind:     hidden_global_offset_y
      - .offset:         432
        .size:           8
        .value_kind:     hidden_global_offset_z
      - .offset:         440
        .size:           2
        .value_kind:     hidden_grid_dims
      - .offset:         464
        .size:           8
        .value_kind:     hidden_multigrid_sync_arg
      - .offset:         496
        .size:           4
        .value_kind:     hidden_dynamic_lds_size
    .group_segment_fixed_size: 0
    .kernarg_segment_align: 8
    .kernarg_segment_size: 632
    .language:       OpenCL C
    .language_version:
      - 2
      - 0
    .max_flat_workgroup_size: 512
    .name:           _Z4mega4Args
    .private_segment_fixed_size: 0
    .sgpr_count:     108
    .sgpr_spill_count: 31
    .symbol:         _Z4mega4Args.kd
    .uniform_work_group_size: 1
    .uses_dynamic_stack: false
    .vgpr_count:     256
    .vgpr_spill_count: 0
    .wavefront_size: 64
